# GEMM K-loops: 5-slot LDS ring (static LDS 16 KiB) keeps LDS-DMA in flight across barriers; attention: mask-free sub-tile code below the diagonal; expert phase per-row prefetch
# speedup vs baseline: 1.1446x; 1.0330x over previous
.LBB0_71:
	s_ashr_i32 s36, s31, 2
	s_and_b32 s36, s36, -8
	s_or_b32 s36, s36, s3
	s_ashr_i32 s37, s36, 31
	s_lshr_b32 s37, s37, 29
	s_add_i32 s37, s36, s37
	s_ashr_i32 s43, s37, 3
	s_and_b32 s37, s37, 0x1ffff8
	s_bfe_u32 s5, s31, 0x20003
	s_sub_i32 s42, s36, s37
	s_lshl_b32 s37, s43, 2
	s_lshl_b32 s33, s5, 8
	s_or_b32 s37, s37, s5
	s_lshl_b32 s5, s42, 11
	s_lshl_b32 s42, s31, 8
	s_and_b32 s42, s42, 0x700
	s_or_b32 s42, s5, s42
	v_add_u32_e32 v0, s42, v187
	v_ashrrev_i32_e32 v1, 31, v0
	v_lshl_add_u32 v2, s37, 8, v187
	v_lshlrev_b64 v[0:1], 12, v[0:1]
	v_ashrrev_i32_e32 v3, 31, v2
	v_readfirstlane_b32 s5, v188
	v_lshl_add_u64 v[0:1], v[146:147], 0, v[0:1]
	v_lshlrev_b64 v[2:3], 12, v[2:3]
	s_add_i32 m0, s5, -16
	v_readfirstlane_b32 s5, v200
	v_lshl_add_u64 v[2:3], v[148:149], 0, v[2:3]
	global_load_lds_dwordx4 v[0:1], off
	s_add_i32 m0, s5, -16
	v_readfirstlane_b32 s5, v201
	global_load_lds_dwordx4 v[2:3], off
	v_lshl_add_u64 v[4:5], v[0:1], 0, s[6:7]
	s_add_i32 m0, s5, -16
	v_readfirstlane_b32 s5, v202
	global_load_lds_dwordx4 v[4:5], off
	v_lshl_add_u64 v[4:5], v[2:3], 0, s[6:7]
	s_add_i32 m0, s5, -16
	v_readfirstlane_b32 s5, v203
	global_load_lds_dwordx4 v[4:5], off
	v_lshl_add_u64 v[4:5], v[0:1], 0, s[14:15]
	s_add_i32 m0, s5, -16
	v_readfirstlane_b32 s5, v204
	global_load_lds_dwordx4 v[4:5], off
	v_lshl_add_u64 v[4:5], v[2:3], 0, s[14:15]
	s_add_i32 m0, s5, -16
	v_readfirstlane_b32 s5, v205
	global_load_lds_dwordx4 v[4:5], off
	v_lshl_add_u64 v[0:1], v[0:1], 0, s[20:21]
	s_add_i32 m0, s5, -16
	v_readfirstlane_b32 s5, v206
	global_load_lds_dwordx4 v[0:1], off
	v_lshl_add_u64 v[0:1], v[2:3], 0, s[20:21]
	s_add_i32 m0, s5, -16
	s_and_b32 s4, s35, 0x700
	global_load_lds_dwordx4 v[0:1], off
	s_lshl_b32 s5, s36, 11
	s_or_b32 s4, s4, s5
	v_add_u32_e32 v0, s4, v187
	s_lshl_b32 s4, s43, 14
	v_subrev_u32_e32 v0, s4, v0
	v_ashrrev_i32_e32 v1, 31, v0
	s_lshl_b32 s4, s43, 10
	v_lshlrev_b64 v[0:1], 12, v[0:1]
	s_or_b32 s4, s33, s4
	v_lshl_add_u64 v[128:129], v[158:159], 0, v[0:1]
	v_add_u32_e32 v0, s4, v187
	v_ashrrev_i32_e32 v1, 31, v0
	v_lshlrev_b64 v[0:1], 12, v[0:1]
	v_lshl_add_u64 v[130:131], v[160:161], 0, v[0:1]
	s_mov_b64 s[4:5], 0
	s_mov_b32 s43, 0
	v_mov_b32_e32 v0, 0
	v_mov_b32_e32 v1, v145
	v_mov_b32_e32 v2, v145
	v_mov_b32_e32 v3, v145
	v_mov_b32_e32 v4, v145
	v_mov_b32_e32 v5, v145
	v_mov_b32_e32 v6, v145
	v_mov_b32_e32 v7, v145
	s_waitcnt vmcnt(0)
	v_mov_b32_e32 v8, v145
	v_mov_b32_e32 v9, v145
	v_mov_b32_e32 v10, v145
	v_mov_b32_e32 v11, v145
	v_mov_b32_e32 v12, v145
	v_mov_b32_e32 v13, v145
	v_mov_b32_e32 v14, v145
	v_mov_b32_e32 v15, v145
	v_mov_b32_e32 v16, 0
	v_mov_b32_e32 v17, v145
	v_mov_b32_e32 v18, v145
	v_mov_b32_e32 v19, v145
	v_mov_b32_e32 v20, v145
	v_mov_b32_e32 v21, v145
	v_mov_b32_e32 v22, v145
	v_mov_b32_e32 v23, v145
	v_mov_b32_e32 v24, v145
	v_mov_b32_e32 v25, v145
	v_mov_b32_e32 v26, v145
	v_mov_b32_e32 v27, v145
	v_mov_b32_e32 v28, v145
	v_mov_b32_e32 v29, v145
	v_mov_b32_e32 v30, v145
	v_mov_b32_e32 v31, v145
	v_mov_b32_e32 v32, 0
	v_mov_b32_e32 v33, v145
	v_mov_b32_e32 v34, v145
	v_mov_b32_e32 v35, v145
	v_mov_b32_e32 v36, v145
	v_mov_b32_e32 v37, v145
	v_mov_b32_e32 v38, v145
	v_mov_b32_e32 v39, v145
	v_mov_b32_e32 v40, v145
	v_mov_b32_e32 v41, v145
	v_mov_b32_e32 v42, v145
	v_mov_b32_e32 v43, v145
	v_mov_b32_e32 v44, v145
	v_mov_b32_e32 v45, v145
	v_mov_b32_e32 v46, v145
	v_mov_b32_e32 v47, v145
	v_mov_b32_e32 v48, 0
	v_mov_b32_e32 v49, v145
	v_mov_b32_e32 v50, v145
	v_mov_b32_e32 v51, v145
	v_mov_b32_e32 v52, v145
	v_mov_b32_e32 v53, v145
	v_mov_b32_e32 v54, v145
	v_mov_b32_e32 v55, v145
	v_mov_b32_e32 v56, v145
	v_mov_b32_e32 v57, v145
	v_mov_b32_e32 v58, v145
	v_mov_b32_e32 v59, v145
	v_mov_b32_e32 v60, v145
	v_mov_b32_e32 v61, v145
	v_mov_b32_e32 v62, v145
	v_mov_b32_e32 v63, v145
	v_mov_b32_e32 v64, 0
	v_mov_b32_e32 v65, v145
	v_mov_b32_e32 v66, v145
	v_mov_b32_e32 v67, v145
	v_mov_b32_e32 v68, v145
	v_mov_b32_e32 v69, v145
	v_mov_b32_e32 v70, v145
	v_mov_b32_e32 v71, v145
	v_mov_b32_e32 v72, v145
	v_mov_b32_e32 v73, v145
	v_mov_b32_e32 v74, v145
	v_mov_b32_e32 v75, v145
	v_mov_b32_e32 v76, v145
	v_mov_b32_e32 v77, v145
	v_mov_b32_e32 v78, v145
	v_mov_b32_e32 v79, v145
	v_mov_b32_e32 v80, 0
	v_mov_b32_e32 v81, v145
	v_mov_b32_e32 v82, v145
	v_mov_b32_e32 v83, v145
	v_mov_b32_e32 v84, v145
	v_mov_b32_e32 v85, v145
	v_mov_b32_e32 v86, v145
	v_mov_b32_e32 v87, v145
	v_mov_b32_e32 v88, v145
	v_mov_b32_e32 v89, v145
	v_mov_b32_e32 v90, v145
	v_mov_b32_e32 v91, v145
	v_mov_b32_e32 v92, v145
	v_mov_b32_e32 v93, v145
	v_mov_b32_e32 v94, v145
	v_mov_b32_e32 v95, v145
	v_mov_b32_e32 v96, 0
	v_mov_b32_e32 v97, v145
	v_mov_b32_e32 v98, v145
	v_mov_b32_e32 v99, v145
	v_mov_b32_e32 v100, v145
	v_mov_b32_e32 v101, v145
	v_mov_b32_e32 v102, v145
	v_mov_b32_e32 v103, v145
	v_mov_b32_e32 v104, v145
	v_mov_b32_e32 v105, v145
	v_mov_b32_e32 v106, v145
	v_mov_b32_e32 v107, v145
	v_mov_b32_e32 v108, v145
	v_mov_b32_e32 v109, v145
	v_mov_b32_e32 v110, v145
	v_mov_b32_e32 v111, v145
	v_mov_b32_e32 v112, 0
	v_mov_b32_e32 v113, v145
	v_mov_b32_e32 v114, v145
	v_mov_b32_e32 v115, v145
	v_mov_b32_e32 v116, v145
	v_mov_b32_e32 v117, v145
	v_mov_b32_e32 v118, v145
	v_mov_b32_e32 v119, v145
	v_mov_b32_e32 v120, v145
	v_mov_b32_e32 v121, v145
	v_mov_b32_e32 v122, v145
	v_mov_b32_e32 v123, v145
	v_mov_b32_e32 v124, v145
	v_mov_b32_e32 v125, v145
	v_mov_b32_e32 v126, v145
	v_mov_b32_e32 v127, v145
	s_waitcnt lgkmcnt(0)
	s_barrier
	v_readfirstlane_b32 s48, v188
	s_sub_u32 s48, s48, 16
	s_mov_b32 s49, 0
	s_mov_b32 s50, 0x8000
	s_mov_b32 s52, 0x10000
	v_add_u32_e32 v132, v194, v195
	v_add_u32_e32 v135, v196, v195
	s_add_u32 m0, s52, s48
	v_lshl_add_u64 v[140:141], v[128:129], 0, s[22:23]
	global_load_lds_dwordx4 v[140:141], off
	s_add_u32 s53, s52, s48
	s_add_u32 m0, s53, 0x2000
	v_lshl_add_u64 v[140:141], v[128:129], 0, s[24:25]
	global_load_lds_dwordx4 v[140:141], off
	s_add_u32 s53, s52, s48
	s_add_u32 m0, s53, 0x4000
	v_lshl_add_u64 v[140:141], v[128:129], 0, s[26:27]
	global_load_lds_dwordx4 v[140:141], off
	s_add_u32 s53, s52, s48
	s_add_u32 m0, s53, 0x6000
	v_lshl_add_u64 v[140:141], v[128:129], 0, s[28:29]
	global_load_lds_dwordx4 v[140:141], off
	v_add3_u32 v133, v193, v132, s49
	v_add3_u32 v134, v193, v135, s50
	ds_read_b128 v[164:167], v134
	ds_read_b128 v[172:175], v133
	ds_read_b128 v[168:171], v134 offset:4096
	ds_read_b128 v[176:179], v133 offset:4096
	ds_read_b128 v[180:183], v133 offset:8192
	ds_read_b128 v[212:215], v133 offset:12288
.Lgr1_loop:
	s_add_u32 s51, s50, 0x10000
	s_sub_u32 s53, s51, 0x28000
	s_cmp_ge_u32 s51, 0x28000
	s_cselect_b32 s51, s53, s51
	s_add_u32 s52, s49, 0x20000
	s_sub_u32 s53, s52, 0x28000
	s_cmp_ge_u32 s52, 0x28000
	s_cselect_b32 s52, s53, s52
	v_add3_u32 v133, v197, v132, s49
	v_add3_u32 v134, v197, v135, s50
	ds_read_b128 v[216:219], v134
	ds_read_b128 v[224:227], v133
	ds_read_b128 v[220:223], v134 offset:4096
	ds_read_b128 v[228:231], v133 offset:4096
	ds_read_b128 v[232:235], v133 offset:8192
	ds_read_b128 v[236:239], v133 offset:12288
	s_add_u32 s54, s4, 0x80
	s_addc_u32 s55, s5, 0
	v_lshl_add_u64 v[136:137], v[128:129], 0, s[54:55]
	v_lshl_add_u64 v[138:139], v[130:131], 0, s[4:5]
	s_waitcnt lgkmcnt(6)
	v_mfma_f32_32x32x16_bf16 v[112:127], v[164:167], v[172:175], v[112:127]
	s_add_u32 m0, s51, s48
	v_lshl_add_u64 v[140:141], v[138:139], 0, s[22:23]
	global_load_lds_dwordx4 v[140:141], off
	v_mfma_f32_32x32x16_bf16 v[96:111], v[168:171], v[172:175], v[96:111]
	s_add_u32 s53, s51, s48
	s_add_u32 m0, s53, 0x2000
	v_lshl_add_u64 v[140:141], v[138:139], 0, s[24:25]
	global_load_lds_dwordx4 v[140:141], off
	v_mfma_f32_32x32x16_bf16 v[80:95], v[164:167], v[176:179], v[80:95]
	s_add_u32 s53, s51, s48
	s_add_u32 m0, s53, 0x4000
	v_lshl_add_u64 v[140:141], v[138:139], 0, s[26:27]
	global_load_lds_dwordx4 v[140:141], off
	v_mfma_f32_32x32x16_bf16 v[64:79], v[168:171], v[176:179], v[64:79]
	s_add_u32 s53, s51, s48
	s_add_u32 m0, s53, 0x6000
	v_lshl_add_u64 v[140:141], v[138:139], 0, s[28:29]
	global_load_lds_dwordx4 v[140:141], off
	v_mfma_f32_32x32x16_bf16 v[48:63], v[164:167], v[180:183], v[48:63]
	s_add_u32 m0, s52, s48
	v_lshl_add_u64 v[140:141], v[136:137], 0, s[22:23]
	global_load_lds_dwordx4 v[140:141], off
	v_mfma_f32_32x32x16_bf16 v[32:47], v[168:171], v[180:183], v[32:47]
	s_add_u32 s53, s52, s48
	s_add_u32 m0, s53, 0x2000
	v_lshl_add_u64 v[140:141], v[136:137], 0, s[24:25]
	global_load_lds_dwordx4 v[140:141], off
	v_mfma_f32_32x32x16_bf16 v[16:31], v[164:167], v[212:215], v[16:31]
	s_add_u32 s53, s52, s48
	s_add_u32 m0, s53, 0x4000
	v_lshl_add_u64 v[140:141], v[136:137], 0, s[26:27]
	global_load_lds_dwordx4 v[140:141], off
	v_mfma_f32_32x32x16_bf16 v[0:15], v[168:171], v[212:215], v[0:15]
	s_add_u32 s53, s52, s48
	s_add_u32 m0, s53, 0x6000
	v_lshl_add_u64 v[140:141], v[136:137], 0, s[28:29]
	global_load_lds_dwordx4 v[140:141], off
	v_add3_u32 v133, v198, v132, s49
	v_add3_u32 v134, v198, v135, s50
	ds_read_b128 v[164:167], v134
	ds_read_b128 v[172:175], v133
	ds_read_b128 v[168:171], v134 offset:4096
	ds_read_b128 v[176:179], v133 offset:4096
	ds_read_b128 v[180:183], v133 offset:8192
	ds_read_b128 v[212:215], v133 offset:12288
	s_waitcnt lgkmcnt(6)
	v_mfma_f32_32x32x16_bf16 v[112:127], v[216:219], v[224:227], v[112:127]
	v_mfma_f32_32x32x16_bf16 v[96:111], v[220:223], v[224:227], v[96:111]
	v_mfma_f32_32x32x16_bf16 v[80:95], v[216:219], v[228:231], v[80:95]
	v_mfma_f32_32x32x16_bf16 v[64:79], v[220:223], v[228:231], v[64:79]
	v_mfma_f32_32x32x16_bf16 v[48:63], v[216:219], v[232:235], v[48:63]
	v_mfma_f32_32x32x16_bf16 v[32:47], v[220:223], v[232:235], v[32:47]
	v_mfma_f32_32x32x16_bf16 v[16:31], v[216:219], v[236:239], v[16:31]
	v_mfma_f32_32x32x16_bf16 v[0:15], v[220:223], v[236:239], v[0:15]
	v_add3_u32 v133, v199, v132, s49
	v_add3_u32 v134, v199, v135, s50
	ds_read_b128 v[216:219], v134
	ds_read_b128 v[224:227], v133
	ds_read_b128 v[220:223], v134 offset:4096
	ds_read_b128 v[228:231], v133 offset:4096
	ds_read_b128 v[232:235], v133 offset:8192
	ds_read_b128 v[236:239], v133 offset:12288
	s_waitcnt lgkmcnt(6)
	v_mfma_f32_32x32x16_bf16 v[112:127], v[164:167], v[172:175], v[112:127]
	v_mfma_f32_32x32x16_bf16 v[96:111], v[168:171], v[172:175], v[96:111]
	v_mfma_f32_32x32x16_bf16 v[80:95], v[164:167], v[176:179], v[80:95]
	v_mfma_f32_32x32x16_bf16 v[64:79], v[168:171], v[176:179], v[64:79]
	v_mfma_f32_32x32x16_bf16 v[48:63], v[164:167], v[180:183], v[48:63]
	v_mfma_f32_32x32x16_bf16 v[32:47], v[168:171], v[180:183], v[32:47]
	v_mfma_f32_32x32x16_bf16 v[16:31], v[164:167], v[212:215], v[16:31]
	v_mfma_f32_32x32x16_bf16 v[0:15], v[168:171], v[212:215], v[0:15]
	s_waitcnt lgkmcnt(0)
	v_mfma_f32_32x32x16_bf16 v[112:127], v[216:219], v[224:227], v[112:127]
	v_mfma_f32_32x32x16_bf16 v[96:111], v[220:223], v[224:227], v[96:111]
	v_mfma_f32_32x32x16_bf16 v[80:95], v[216:219], v[228:231], v[80:95]
	v_mfma_f32_32x32x16_bf16 v[64:79], v[220:223], v[228:231], v[64:79]
	s_add_u32 s4, s4, 0x80
	s_addc_u32 s5, s5, 0
	s_add_u32 s49, s49, 0x10000
	s_sub_u32 s53, s49, 0x28000
	s_cmp_ge_u32 s49, 0x28000
	s_cselect_b32 s49, s53, s49
	s_mov_b32 s50, s51
	s_waitcnt vmcnt(4)
	s_barrier
	v_add3_u32 v133, v193, v132, s49
	v_add3_u32 v134, v193, v135, s50
	ds_read_b128 v[164:167], v134
	ds_read_b128 v[172:175], v133
	ds_read_b128 v[168:171], v134 offset:4096
	ds_read_b128 v[176:179], v133 offset:4096
	ds_read_b128 v[180:183], v133 offset:8192
	ds_read_b128 v[212:215], v133 offset:12288
	v_mfma_f32_32x32x16_bf16 v[48:63], v[216:219], v[232:235], v[48:63]
	v_mfma_f32_32x32x16_bf16 v[32:47], v[220:223], v[232:235], v[32:47]
	v_mfma_f32_32x32x16_bf16 v[16:31], v[216:219], v[236:239], v[16:31]
	v_mfma_f32_32x32x16_bf16 v[0:15], v[220:223], v[236:239], v[0:15]
	s_cmpk_lg_i32 s4, 0xf00
	s_cbranch_scc1 .Lgr1_loop
	s_add_u32 s51, s50, 0x10000
	s_sub_u32 s53, s51, 0x28000
	s_cmp_ge_u32 s51, 0x28000
	s_cselect_b32 s51, s53, s51
	v_add3_u32 v133, v197, v132, s49
	v_add3_u32 v134, v197, v135, s50
	ds_read_b128 v[216:219], v134
	ds_read_b128 v[224:227], v133
	ds_read_b128 v[220:223], v134 offset:4096
	ds_read_b128 v[228:231], v133 offset:4096
	ds_read_b128 v[232:235], v133 offset:8192
	ds_read_b128 v[236:239], v133 offset:12288
	s_add_u32 s54, s4, 0x80
	s_addc_u32 s55, s5, 0
	v_lshl_add_u64 v[136:137], v[128:129], 0, s[54:55]
	v_lshl_add_u64 v[138:139], v[130:131], 0, s[4:5]
	s_waitcnt lgkmcnt(6)
	v_mfma_f32_32x32x16_bf16 v[112:127], v[164:167], v[172:175], v[112:127]
	s_add_u32 m0, s51, s48
	v_lshl_add_u64 v[140:141], v[138:139], 0, s[22:23]
	global_load_lds_dwordx4 v[140:141], off
	v_mfma_f32_32x32x16_bf16 v[96:111], v[168:171], v[172:175], v[96:111]
	s_add_u32 s53, s51, s48
	s_add_u32 m0, s53, 0x2000
	v_lshl_add_u64 v[140:141], v[138:139], 0, s[24:25]
	global_load_lds_dwordx4 v[140:141], off
	v_mfma_f32_32x32x16_bf16 v[80:95], v[164:167], v[176:179], v[80:95]
	s_add_u32 s53, s51, s48
	s_add_u32 m0, s53, 0x4000
	v_lshl_add_u64 v[140:141], v[138:139], 0, s[26:27]
	global_load_lds_dwordx4 v[140:141], off
	v_mfma_f32_32x32x16_bf16 v[64:79], v[168:171], v[176:179], v[64:79]
	s_add_u32 s53, s51, s48
	s_add_u32 m0, s53, 0x6000
	v_lshl_add_u64 v[140:141], v[138:139], 0, s[28:29]
	global_load_lds_dwordx4 v[140:141], off
	v_mfma_f32_32x32x16_bf16 v[48:63], v[164:167], v[180:183], v[48:63]
	v_mfma_f32_32x32x16_bf16 v[32:47], v[168:171], v[180:183], v[32:47]
	v_mfma_f32_32x32x16_bf16 v[16:31], v[164:167], v[212:215], v[16:31]
	v_mfma_f32_32x32x16_bf16 v[0:15], v[168:171], v[212:215], v[0:15]
	v_add3_u32 v133, v198, v132, s49
	v_add3_u32 v134, v198, v135, s50
	ds_read_b128 v[164:167], v134
	ds_read_b128 v[172:175], v133
	ds_read_b128 v[168:171], v134 offset:4096
	ds_read_b128 v[176:179], v133 offset:4096
	ds_read_b128 v[180:183], v133 offset:8192
	ds_read_b128 v[212:215], v133 offset:12288
	s_waitcnt lgkmcnt(6)
	v_mfma_f32_32x32x16_bf16 v[112:127], v[216:219], v[224:227], v[112:127]
	v_mfma_f32_32x32x16_bf16 v[96:111], v[220:223], v[224:227], v[96:111]
	v_mfma_f32_32x32x16_bf16 v[80:95], v[216:219], v[228:231], v[80:95]
	v_mfma_f32_32x32x16_bf16 v[64:79], v[220:223], v[228:231], v[64:79]
	v_mfma_f32_32x32x16_bf16 v[48:63], v[216:219], v[232:235], v[48:63]
	v_mfma_f32_32x32x16_bf16 v[32:47], v[220:223], v[232:235], v[32:47]
	v_mfma_f32_32x32x16_bf16 v[16:31], v[216:219], v[236:239], v[16:31]
	v_mfma_f32_32x32x16_bf16 v[0:15], v[220:223], v[236:239], v[0:15]
	v_add3_u32 v133, v199, v132, s49
	v_add3_u32 v134, v199, v135, s50
	ds_read_b128 v[216:219], v134
	ds_read_b128 v[224:227], v133
	ds_read_b128 v[220:223], v134 offset:4096
	ds_read_b128 v[228:231], v133 offset:4096
	ds_read_b128 v[232:235], v133 offset:8192
	ds_read_b128 v[236:239], v133 offset:12288
	s_waitcnt lgkmcnt(6)
	v_mfma_f32_32x32x16_bf16 v[112:127], v[164:167], v[172:175], v[112:127]
	v_mfma_f32_32x32x16_bf16 v[96:111], v[168:171], v[172:175], v[96:111]
	v_mfma_f32_32x32x16_bf16 v[80:95], v[164:167], v[176:179], v[80:95]
	v_mfma_f32_32x32x16_bf16 v[64:79], v[168:171], v[176:179], v[64:79]
	v_mfma_f32_32x32x16_bf16 v[48:63], v[164:167], v[180:183], v[48:63]
	v_mfma_f32_32x32x16_bf16 v[32:47], v[168:171], v[180:183], v[32:47]
	v_mfma_f32_32x32x16_bf16 v[16:31], v[164:167], v[212:215], v[16:31]
	v_mfma_f32_32x32x16_bf16 v[0:15], v[168:171], v[212:215], v[0:15]
	s_waitcnt lgkmcnt(0)
	v_mfma_f32_32x32x16_bf16 v[112:127], v[216:219], v[224:227], v[112:127]
	v_mfma_f32_32x32x16_bf16 v[96:111], v[220:223], v[224:227], v[96:111]
	v_mfma_f32_32x32x16_bf16 v[80:95], v[216:219], v[228:231], v[80:95]
	v_mfma_f32_32x32x16_bf16 v[64:79], v[220:223], v[228:231], v[64:79]
	s_add_u32 s4, s4, 0x80
	s_addc_u32 s5, s5, 0
	s_add_u32 s49, s49, 0x10000
	s_sub_u32 s53, s49, 0x28000
	s_cmp_ge_u32 s49, 0x28000
	s_cselect_b32 s49, s53, s49
	s_mov_b32 s50, s51
	s_waitcnt vmcnt(0)
	s_barrier
	v_add3_u32 v133, v193, v132, s49
	v_add3_u32 v134, v193, v135, s50
	ds_read_b128 v[164:167], v134
	ds_read_b128 v[172:175], v133
	ds_read_b128 v[168:171], v134 offset:4096
	ds_read_b128 v[176:179], v133 offset:4096
	ds_read_b128 v[180:183], v133 offset:8192
	ds_read_b128 v[212:215], v133 offset:12288
	v_mfma_f32_32x32x16_bf16 v[48:63], v[216:219], v[232:235], v[48:63]
	v_mfma_f32_32x32x16_bf16 v[32:47], v[220:223], v[232:235], v[32:47]
	v_mfma_f32_32x32x16_bf16 v[16:31], v[216:219], v[236:239], v[16:31]
	v_mfma_f32_32x32x16_bf16 v[0:15], v[220:223], v[236:239], v[0:15]
	v_add3_u32 v133, v197, v132, s49
	v_add3_u32 v134, v197, v135, s50
	ds_read_b128 v[216:219], v134
	ds_read_b128 v[224:227], v133
	ds_read_b128 v[220:223], v134 offset:4096
	ds_read_b128 v[228:231], v133 offset:4096
	ds_read_b128 v[232:235], v133 offset:8192
	ds_read_b128 v[236:239], v133 offset:12288
	s_waitcnt lgkmcnt(6)
	v_mfma_f32_32x32x16_bf16 v[112:127], v[164:167], v[172:175], v[112:127]
	v_mfma_f32_32x32x16_bf16 v[96:111], v[168:171], v[172:175], v[96:111]
	v_mfma_f32_32x32x16_bf16 v[80:95], v[164:167], v[176:179], v[80:95]
	v_mfma_f32_32x32x16_bf16 v[64:79], v[168:171], v[176:179], v[64:79]
	v_mfma_f32_32x32x16_bf16 v[48:63], v[164:167], v[180:183], v[48:63]
	v_mfma_f32_32x32x16_bf16 v[32:47], v[168:171], v[180:183], v[32:47]
	v_mfma_f32_32x32x16_bf16 v[16:31], v[164:167], v[212:215], v[16:31]
	v_mfma_f32_32x32x16_bf16 v[0:15], v[168:171], v[212:215], v[0:15]
	v_add3_u32 v133, v198, v132, s49
	v_add3_u32 v134, v198, v135, s50
	ds_read_b128 v[164:167], v134
	ds_read_b128 v[172:175], v133
	ds_read_b128 v[168:171], v134 offset:4096
	ds_read_b128 v[176:179], v133 offset:4096
	ds_read_b128 v[180:183], v133 offset:8192
	ds_read_b128 v[212:215], v133 offset:12288
	s_waitcnt lgkmcnt(6)
	v_mfma_f32_32x32x16_bf16 v[112:127], v[216:219], v[224:227], v[112:127]
	v_mfma_f32_32x32x16_bf16 v[96:111], v[220:223], v[224:227], v[96:111]
	v_mfma_f32_32x32x16_bf16 v[80:95], v[216:219], v[228:231], v[80:95]
	v_mfma_f32_32x32x16_bf16 v[64:79], v[220:223], v[228:231], v[64:79]
	v_mfma_f32_32x32x16_bf16 v[48:63], v[216:219], v[232:235], v[48:63]
	v_mfma_f32_32x32x16_bf16 v[32:47], v[220:223], v[232:235], v[32:47]
	v_mfma_f32_32x32x16_bf16 v[16:31], v[216:219], v[236:239], v[16:31]
	v_mfma_f32_32x32x16_bf16 v[0:15], v[220:223], v[236:239], v[0:15]
	v_add3_u32 v133, v199, v132, s49
	v_add3_u32 v134, v199, v135, s50
	ds_read_b128 v[216:219], v134
	ds_read_b128 v[224:227], v133
	ds_read_b128 v[220:223], v134 offset:4096
	ds_read_b128 v[228:231], v133 offset:4096
	ds_read_b128 v[232:235], v133 offset:8192
	ds_read_b128 v[236:239], v133 offset:12288
	s_waitcnt lgkmcnt(6)
	v_mfma_f32_32x32x16_bf16 v[112:127], v[164:167], v[172:175], v[112:127]
	v_mfma_f32_32x32x16_bf16 v[96:111], v[168:171], v[172:175], v[96:111]
	v_mfma_f32_32x32x16_bf16 v[80:95], v[164:167], v[176:179], v[80:95]
	v_mfma_f32_32x32x16_bf16 v[64:79], v[168:171], v[176:179], v[64:79]
	v_mfma_f32_32x32x16_bf16 v[48:63], v[164:167], v[180:183], v[48:63]
	v_mfma_f32_32x32x16_bf16 v[32:47], v[168:171], v[180:183], v[32:47]
	v_mfma_f32_32x32x16_bf16 v[16:31], v[164:167], v[212:215], v[16:31]
	v_mfma_f32_32x32x16_bf16 v[0:15], v[168:171], v[212:215], v[0:15]
	s_waitcnt vmcnt(0) lgkmcnt(0)
	s_barrier
	v_mfma_f32_32x32x16_bf16 v[112:127], v[216:219], v[224:227], v[112:127]
	v_mfma_f32_32x32x16_bf16 v[96:111], v[220:223], v[224:227], v[96:111]
	v_mfma_f32_32x32x16_bf16 v[80:95], v[216:219], v[228:231], v[80:95]
	v_mfma_f32_32x32x16_bf16 v[64:79], v[220:223], v[228:231], v[64:79]
	v_mfma_f32_32x32x16_bf16 v[48:63], v[216:219], v[232:235], v[48:63]
	v_mfma_f32_32x32x16_bf16 v[32:47], v[220:223], v[232:235], v[32:47]
	v_mfma_f32_32x32x16_bf16 v[16:31], v[216:219], v[236:239], v[16:31]
	v_mfma_f32_32x32x16_bf16 v[0:15], v[220:223], v[236:239], v[0:15]
	s_nop 15

.LBB0_107:
	s_cmp_lt_u32 s42, s98
	s_cbranch_scc1 .Lnd_107
	s_and_b32 s33, s42, 1
	s_mul_i32 s6, s33, 0x9000
	s_cmp_lt_u32 s42, s98
	s_cselect_b64 vcc, -1, 0
	v_cmp_le_i32_e64 s[4:5], s97, v195
	v_add_u32_e32 v199, s6, v187
	v_add_u32_e32 v198, s6, v188
	v_add_u32_e32 v200, s97, v178
	s_and_saveexec_b64 s[54:55], s[4:5]
	s_cbranch_execz .LBB0_109
	ds_read_b128 v[202:205], v199
	ds_read_b128 v[206:209], v199 offset:32
	ds_read_b128 v[210:213], v193
	ds_read_b128 v[214:217], v193 offset:32
	ds_read_b128 v[218:221], v199 offset:64
	ds_read_b128 v[222:225], v199 offset:96
	ds_read_b128 v[226:229], v193 offset:64
	ds_read_b128 v[230:233], v193 offset:96
	s_waitcnt lgkmcnt(5)
	v_mfma_f32_32x32x16_bf16 v[144:159], v[202:205], v[210:213], v[0:15]
	s_waitcnt lgkmcnt(4)
	v_mfma_f32_32x32x16_bf16 v[144:159], v[206:209], v[214:217], v[144:159]
	s_waitcnt lgkmcnt(1)
	v_mfma_f32_32x32x16_bf16 v[144:159], v[218:221], v[226:229], v[144:159]
	s_waitcnt lgkmcnt(0)
	v_mfma_f32_32x32x16_bf16 v[144:159], v[222:225], v[230:233], v[144:159]
	s_nop 11
	v_exp_f32_e32 v146, v146
	v_cmp_lt_i32_e64 s[6:7], v200, v194
	v_add_u32_e32 v202, 2, v200
	s_or_b64 s[10:11], vcc, s[6:7]
	v_cmp_gt_i32_e64 s[6:7], v202, v194
	v_exp_f32_e32 v147, v147
	v_exp_f32_e32 v148, v148
	v_cndmask_b32_e64 v202, v146, 0, s[6:7]
	v_cndmask_b32_e32 v146, v202, v146, vcc
	v_add_u32_e32 v202, 3, v200
	v_cmp_gt_i32_e64 s[16:17], v202, v194
	v_exp_f32_e32 v149, v149
	v_exp_f32_e32 v150, v150
	v_cndmask_b32_e64 v202, v147, 0, s[16:17]
	v_cndmask_b32_e32 v147, v202, v147, vcc
	v_add_u32_e32 v202, 8, v200
	v_cmp_gt_i32_e64 s[8:9], v202, v194
	v_exp_f32_e32 v151, v151
	v_exp_f32_e32 v152, v152
	v_cndmask_b32_e64 v202, v148, 0, s[8:9]
	v_cndmask_b32_e32 v148, v202, v148, vcc
	v_add_u32_e32 v202, 9, v200
	v_cmp_gt_i32_e64 s[20:21], v202, v194
	v_exp_f32_e32 v153, v153
	v_exp_f32_e32 v144, v144
	v_cndmask_b32_e64 v202, v149, 0, s[20:21]
	v_cndmask_b32_e32 v149, v202, v149, vcc
	v_add_u32_e32 v202, 10, v200
	v_cmp_gt_i32_e64 s[12:13], v202, v194
	v_exp_f32_e32 v154, v154
	v_exp_f32_e32 v145, v145
	v_cndmask_b32_e64 v202, v150, 0, s[12:13]
	v_cndmask_b32_e32 v150, v202, v150, vcc
	v_add_u32_e32 v202, 11, v200
	v_cmp_gt_i32_e64 s[24:25], v202, v194
	v_cmp_gt_i32_e64 s[4:5], v200, v194
	v_exp_f32_e32 v155, v155
	v_cndmask_b32_e64 v202, v151, 0, s[24:25]
	v_cndmask_b32_e32 v151, v202, v151, vcc
	v_add_u32_e32 v202, 16, v200
	v_cmp_gt_i32_e64 s[14:15], v202, v194
	v_cndmask_b32_e64 v201, v144, 0, s[4:5]
	v_cndmask_b32_e32 v144, v201, v144, vcc
	v_cndmask_b32_e64 v202, v152, 0, s[14:15]
	v_cndmask_b32_e32 v152, v202, v152, vcc
	v_add_u32_e32 v202, 17, v200
	v_cmp_gt_i32_e64 s[28:29], v202, v194
	v_add_f32_e32 v201, 0, v144
	v_cndmask_b32_e64 v145, 0, v145, s[10:11]
	v_cndmask_b32_e64 v202, v153, 0, s[28:29]
	v_cndmask_b32_e32 v153, v202, v153, vcc
	v_add_u32_e32 v202, 18, v200
	v_cmp_gt_i32_e64 s[18:19], v202, v194
	v_exp_f32_e32 v156, v156
	v_add_f32_e32 v201, v145, v201
	v_cndmask_b32_e64 v202, v154, 0, s[18:19]
	v_cndmask_b32_e32 v154, v202, v154, vcc
	v_add_u32_e32 v202, 19, v200
	v_cmp_gt_i32_e64 s[30:31], v202, v194
	v_add_f32_e32 v201, v146, v201
	v_add_f32_e32 v201, v147, v201
	v_cndmask_b32_e64 v202, v155, 0, s[30:31]
	v_cndmask_b32_e32 v155, v202, v155, vcc
	v_add_u32_e32 v202, 24, v200
	v_cmp_gt_i32_e64 s[22:23], v202, v194
	v_exp_f32_e32 v157, v157
	v_add_f32_e32 v201, v148, v201
	v_cndmask_b32_e64 v202, v156, 0, s[22:23]
	v_add_f32_e32 v201, v149, v201
	v_cndmask_b32_e32 v156, v202, v156, vcc
	v_add_u32_e32 v202, 25, v200
	v_add_f32_e32 v201, v150, v201
	v_cmp_gt_i32_e64 s[34:35], v202, v194
	v_exp_f32_e32 v158, v158
	v_add_f32_e32 v201, v151, v201
	v_cndmask_b32_e64 v202, v157, 0, s[34:35]
	v_add_f32_e32 v201, v152, v201
	v_cndmask_b32_e32 v157, v202, v157, vcc
	v_add_u32_e32 v202, 26, v200
	v_add_f32_e32 v201, v153, v201
	v_cmp_gt_i32_e64 s[26:27], v202, v194
	v_exp_f32_e32 v159, v159
	v_add_f32_e32 v201, v154, v201
	v_cndmask_b32_e64 v202, v158, 0, s[26:27]
	v_add_f32_e32 v201, v155, v201
	v_cndmask_b32_e32 v158, v202, v158, vcc
	v_add_u32_e32 v202, 27, v200
	v_add_f32_e32 v201, v156, v201
	v_cmp_gt_i32_e64 s[36:37], v202, v194
	v_add_f32_e32 v201, v157, v201
	v_add_f32_e32 v201, v158, v201
	v_cndmask_b32_e64 v202, v159, 0, s[36:37]
	v_cndmask_b32_e32 v159, v202, v159, vcc
	v_cvt_pk_bf16_f32 v202, v144, v145
	v_add_f32_e32 v144, v159, v201
	v_add_f32_e32 v196, v196, v144
	v_cvt_pk_bf16_f32 v203, v146, v147
	v_cvt_pk_bf16_f32 v204, v148, v149
	v_cvt_pk_bf16_f32 v205, v150, v151
	v_cvt_pk_bf16_f32 v206, v152, v153
	v_cvt_pk_bf16_f32 v207, v154, v155
	v_cvt_pk_bf16_f32 v208, v156, v157
	v_cvt_pk_bf16_f32 v209, v158, v159
	ds_read_b128 v[210:213], v199 offset:9216
	ds_read_b128 v[214:217], v199 offset:9248
	ds_read_b128 v[218:221], v193 offset:36864
	ds_read_b128 v[222:225], v193 offset:36896
	ds_read_b128 v[226:229], v199 offset:9280
	ds_read_b128 v[230:233], v199 offset:9312
	ds_read_b128 v[234:237], v193 offset:36928
	ds_read_b128 v[238:241], v193 offset:36960
	s_waitcnt lgkmcnt(5)
	v_mfma_f32_32x32x16_bf16 v[144:159], v[210:213], v[218:221], v[0:15]
	s_waitcnt lgkmcnt(4)
	v_mfma_f32_32x32x16_bf16 v[144:159], v[214:217], v[222:225], v[144:159]
	ds_read_b128 v[210:213], v198
	ds_read_b128 v[214:217], v198 offset:32
	ds_read_b128 v[218:221], v198 offset:4608
	ds_read_b128 v[222:225], v198 offset:4640
	s_waitcnt lgkmcnt(5)
	v_mfma_f32_32x32x16_bf16 v[144:159], v[226:229], v[234:237], v[144:159]
	s_waitcnt lgkmcnt(4)
	v_mfma_f32_32x32x16_bf16 v[144:159], v[230:233], v[238:241], v[144:159]
	s_nop 11
	v_exp_f32_e32 v144, v144
	v_exp_f32_e32 v145, v145
	v_exp_f32_e32 v146, v146
	v_exp_f32_e32 v147, v147
	v_cndmask_b32_e64 v201, v144, 0, s[4:5]
	v_exp_f32_e32 v148, v148
	v_cndmask_b32_e32 v144, v201, v144, vcc
	v_exp_f32_e32 v149, v149
	v_cndmask_b32_e64 v145, 0, v145, s[10:11]
	v_add_f32_e32 v201, 0, v144
	v_cndmask_b32_e64 v226, v146, 0, s[6:7]
	v_exp_f32_e32 v150, v150
	v_add_f32_e32 v201, v145, v201
	v_cndmask_b32_e32 v146, v226, v146, vcc
	v_cndmask_b32_e64 v226, v147, 0, s[16:17]
	v_exp_f32_e32 v151, v151
	v_add_f32_e32 v201, v146, v201
	v_cndmask_b32_e32 v147, v226, v147, vcc
	v_cndmask_b32_e64 v226, v148, 0, s[8:9]
	v_exp_f32_e32 v152, v152
	v_add_f32_e32 v201, v147, v201
	v_cndmask_b32_e32 v148, v226, v148, vcc
	v_cndmask_b32_e64 v226, v149, 0, s[20:21]
	v_exp_f32_e32 v153, v153
	v_add_f32_e32 v201, v148, v201
	v_cndmask_b32_e32 v149, v226, v149, vcc
	v_cndmask_b32_e64 v226, v150, 0, s[12:13]
	v_exp_f32_e32 v154, v154
	v_add_f32_e32 v201, v149, v201
	v_cndmask_b32_e32 v150, v226, v150, vcc
	v_cndmask_b32_e64 v226, v151, 0, s[24:25]
	v_exp_f32_e32 v155, v155
	v_add_f32_e32 v201, v150, v201
	v_cndmask_b32_e32 v151, v226, v151, vcc
	v_cndmask_b32_e64 v226, v152, 0, s[14:15]
	v_exp_f32_e32 v156, v156
	v_add_f32_e32 v201, v151, v201
	v_cndmask_b32_e32 v152, v226, v152, vcc
	v_cndmask_b32_e64 v226, v153, 0, s[28:29]
	v_exp_f32_e32 v157, v157
	v_add_f32_e32 v201, v152, v201
	v_cndmask_b32_e32 v153, v226, v153, vcc
	v_cndmask_b32_e64 v226, v154, 0, s[18:19]
	v_exp_f32_e32 v158, v158
	v_add_f32_e32 v201, v153, v201
	v_cndmask_b32_e32 v154, v226, v154, vcc
	v_cndmask_b32_e64 v226, v155, 0, s[30:31]
	v_exp_f32_e32 v159, v159
	v_add_f32_e32 v201, v154, v201
	v_cndmask_b32_e32 v155, v226, v155, vcc
	v_cndmask_b32_e64 v226, v156, 0, s[22:23]
	v_add_f32_e32 v201, v155, v201
	v_cndmask_b32_e32 v156, v226, v156, vcc
	v_cndmask_b32_e64 v226, v157, 0, s[34:35]
	v_add_f32_e32 v201, v156, v201
	v_cndmask_b32_e32 v157, v226, v157, vcc
	v_cndmask_b32_e64 v226, v158, 0, s[26:27]
	v_add_f32_e32 v201, v157, v201
	v_cndmask_b32_e32 v158, v226, v158, vcc
	v_cndmask_b32_e64 v226, v159, 0, s[36:37]
	v_add_f32_e32 v201, v158, v201
	v_cndmask_b32_e32 v159, v226, v159, vcc
	v_cvt_pk_bf16_f32 v144, v144, v145
	v_cvt_pk_bf16_f32 v145, v146, v147
	v_cvt_pk_bf16_f32 v146, v148, v149
	v_cvt_pk_bf16_f32 v147, v150, v151
	v_cvt_pk_bf16_f32 v148, v152, v153
	v_cvt_pk_bf16_f32 v149, v154, v155
	v_cvt_pk_bf16_f32 v150, v156, v157
	v_cvt_pk_bf16_f32 v151, v158, v159
	v_add_f32_e32 v201, v159, v201
	ds_read_b128 v[152:155], v198 offset:9216
	ds_read_b128 v[156:159], v198 offset:9248
	ds_read_b128 v[226:229], v198 offset:13824
	ds_read_b128 v[230:233], v198 offset:13856
	s_waitcnt lgkmcnt(7)
	v_mfma_f32_32x32x16_bf16 v[112:127], v[210:213], v[202:205], v[112:127]
	v_mfma_f32_32x32x16_bf16 v[128:143], v[210:213], v[144:147], v[128:143]
	s_waitcnt lgkmcnt(5)
	v_mfma_f32_32x32x16_bf16 v[80:95], v[218:221], v[202:205], v[80:95]
	v_mfma_f32_32x32x16_bf16 v[96:111], v[218:221], v[144:147], v[96:111]
	v_mfma_f32_32x32x16_bf16 v[112:127], v[214:217], v[206:209], v[112:127]
	v_mfma_f32_32x32x16_bf16 v[128:143], v[214:217], v[148:151], v[128:143]
	s_waitcnt lgkmcnt(4)
	v_mfma_f32_32x32x16_bf16 v[80:95], v[222:225], v[206:209], v[80:95]
	v_mfma_f32_32x32x16_bf16 v[96:111], v[222:225], v[148:151], v[96:111]
	s_waitcnt lgkmcnt(3)
	v_mfma_f32_32x32x16_bf16 v[48:63], v[152:155], v[202:205], v[48:63]
	v_add_f32_e32 v197, v197, v201
	v_mfma_f32_32x32x16_bf16 v[64:79], v[152:155], v[144:147], v[64:79]
	s_waitcnt lgkmcnt(1)
	v_mfma_f32_32x32x16_bf16 v[16:31], v[226:229], v[202:205], v[16:31]
	v_mfma_f32_32x32x16_bf16 v[32:47], v[226:229], v[144:147], v[32:47]
	v_mfma_f32_32x32x16_bf16 v[48:63], v[156:159], v[206:209], v[48:63]
	v_mfma_f32_32x32x16_bf16 v[64:79], v[156:159], v[148:151], v[64:79]
	s_waitcnt lgkmcnt(0)
	v_mfma_f32_32x32x16_bf16 v[16:31], v[230:233], v[206:209], v[16:31]
	v_mfma_f32_32x32x16_bf16 v[32:47], v[230:233], v[148:151], v[32:47]

.Lnd_107:
	s_and_b32 s33, s42, 1
	s_mul_i32 s6, s33, 0x9000
	s_cmp_lt_u32 s42, s98
	s_cselect_b64 vcc, -1, 0
	v_cmp_le_i32_e64 s[4:5], s97, v195
	v_add_u32_e32 v199, s6, v187
	v_add_u32_e32 v198, s6, v188
	v_add_u32_e32 v200, s97, v178
	s_and_saveexec_b64 s[54:55], s[4:5]
	s_cbranch_execz .Lnd_109
	ds_read_b128 v[202:205], v199
	ds_read_b128 v[206:209], v199 offset:32
	ds_read_b128 v[210:213], v193
	ds_read_b128 v[214:217], v193 offset:32
	ds_read_b128 v[218:221], v199 offset:64
	ds_read_b128 v[222:225], v199 offset:96
	ds_read_b128 v[226:229], v193 offset:64
	ds_read_b128 v[230:233], v193 offset:96
	s_waitcnt lgkmcnt(5)
	v_mfma_f32_32x32x16_bf16 v[144:159], v[202:205], v[210:213], v[0:15]
	s_waitcnt lgkmcnt(4)
	v_mfma_f32_32x32x16_bf16 v[144:159], v[206:209], v[214:217], v[144:159]
	s_waitcnt lgkmcnt(1)
	v_mfma_f32_32x32x16_bf16 v[144:159], v[218:221], v[226:229], v[144:159]
	s_waitcnt lgkmcnt(0)
	v_mfma_f32_32x32x16_bf16 v[144:159], v[222:225], v[230:233], v[144:159]
	s_nop 11
	v_exp_f32_e32 v146, v146
	v_exp_f32_e32 v147, v147
	v_exp_f32_e32 v148, v148
	v_exp_f32_e32 v149, v149
	v_exp_f32_e32 v150, v150
	v_exp_f32_e32 v151, v151
	v_exp_f32_e32 v152, v152
	v_exp_f32_e32 v153, v153
	v_exp_f32_e32 v144, v144
	v_exp_f32_e32 v154, v154
	v_exp_f32_e32 v145, v145
	v_exp_f32_e32 v155, v155
	v_add_f32_e32 v201, 0, v144
	v_exp_f32_e32 v156, v156
	v_add_f32_e32 v201, v145, v201
	v_add_f32_e32 v201, v146, v201
	v_add_f32_e32 v201, v147, v201
	v_exp_f32_e32 v157, v157
	v_add_f32_e32 v201, v148, v201
	v_add_f32_e32 v201, v149, v201
	v_add_f32_e32 v201, v150, v201
	v_exp_f32_e32 v158, v158
	v_add_f32_e32 v201, v151, v201
	v_add_f32_e32 v201, v152, v201
	v_add_f32_e32 v201, v153, v201
	v_exp_f32_e32 v159, v159
	v_add_f32_e32 v201, v154, v201
	v_add_f32_e32 v201, v155, v201
	v_add_f32_e32 v201, v156, v201
	v_add_f32_e32 v201, v157, v201
	v_add_f32_e32 v201, v158, v201
	v_cvt_pk_bf16_f32 v202, v144, v145
	v_add_f32_e32 v144, v159, v201
	v_add_f32_e32 v196, v196, v144
	v_cvt_pk_bf16_f32 v203, v146, v147
	v_cvt_pk_bf16_f32 v204, v148, v149
	v_cvt_pk_bf16_f32 v205, v150, v151
	v_cvt_pk_bf16_f32 v206, v152, v153
	v_cvt_pk_bf16_f32 v207, v154, v155
	v_cvt_pk_bf16_f32 v208, v156, v157
	v_cvt_pk_bf16_f32 v209, v158, v159
	ds_read_b128 v[210:213], v199 offset:9216
	ds_read_b128 v[214:217], v199 offset:9248
	ds_read_b128 v[218:221], v193 offset:36864
	ds_read_b128 v[222:225], v193 offset:36896
	ds_read_b128 v[226:229], v199 offset:9280
	ds_read_b128 v[230:233], v199 offset:9312
	ds_read_b128 v[234:237], v193 offset:36928
	ds_read_b128 v[238:241], v193 offset:36960
	s_waitcnt lgkmcnt(5)
	v_mfma_f32_32x32x16_bf16 v[144:159], v[210:213], v[218:221], v[0:15]
	s_waitcnt lgkmcnt(4)
	v_mfma_f32_32x32x16_bf16 v[144:159], v[214:217], v[222:225], v[144:159]
	ds_read_b128 v[210:213], v198
	ds_read_b128 v[214:217], v198 offset:32
	ds_read_b128 v[218:221], v198 offset:4608
	ds_read_b128 v[222:225], v198 offset:4640
	s_waitcnt lgkmcnt(5)
	v_mfma_f32_32x32x16_bf16 v[144:159], v[226:229], v[234:237], v[144:159]
	s_waitcnt lgkmcnt(4)
	v_mfma_f32_32x32x16_bf16 v[144:159], v[230:233], v[238:241], v[144:159]
	s_nop 11
	v_exp_f32_e32 v144, v144
	v_exp_f32_e32 v145, v145
	v_exp_f32_e32 v146, v146
	v_exp_f32_e32 v147, v147
	v_exp_f32_e32 v148, v148
	v_exp_f32_e32 v149, v149
	v_add_f32_e32 v201, 0, v144
	v_exp_f32_e32 v150, v150
	v_add_f32_e32 v201, v145, v201
	v_exp_f32_e32 v151, v151
	v_add_f32_e32 v201, v146, v201
	v_exp_f32_e32 v152, v152
	v_add_f32_e32 v201, v147, v201
	v_exp_f32_e32 v153, v153
	v_add_f32_e32 v201, v148, v201
	v_exp_f32_e32 v154, v154
	v_add_f32_e32 v201, v149, v201
	v_exp_f32_e32 v155, v155
	v_add_f32_e32 v201, v150, v201
	v_exp_f32_e32 v156, v156
	v_add_f32_e32 v201, v151, v201
	v_exp_f32_e32 v157, v157
	v_add_f32_e32 v201, v152, v201
	v_exp_f32_e32 v158, v158
	v_add_f32_e32 v201, v153, v201
	v_exp_f32_e32 v159, v159
	v_add_f32_e32 v201, v154, v201
	v_add_f32_e32 v201, v155, v201
	v_add_f32_e32 v201, v156, v201
	v_add_f32_e32 v201, v157, v201
	v_add_f32_e32 v201, v158, v201
	v_cvt_pk_bf16_f32 v144, v144, v145
	v_cvt_pk_bf16_f32 v145, v146, v147
	v_cvt_pk_bf16_f32 v146, v148, v149
	v_cvt_pk_bf16_f32 v147, v150, v151
	v_cvt_pk_bf16_f32 v148, v152, v153
	v_cvt_pk_bf16_f32 v149, v154, v155
	v_cvt_pk_bf16_f32 v150, v156, v157
	v_cvt_pk_bf16_f32 v151, v158, v159
	v_add_f32_e32 v201, v159, v201
	ds_read_b128 v[152:155], v198 offset:9216
	ds_read_b128 v[156:159], v198 offset:9248
	ds_read_b128 v[226:229], v198 offset:13824
	ds_read_b128 v[230:233], v198 offset:13856
	s_waitcnt lgkmcnt(7)
	v_mfma_f32_32x32x16_bf16 v[112:127], v[210:213], v[202:205], v[112:127]
	v_mfma_f32_32x32x16_bf16 v[128:143], v[210:213], v[144:147], v[128:143]
	s_waitcnt lgkmcnt(5)
	v_mfma_f32_32x32x16_bf16 v[80:95], v[218:221], v[202:205], v[80:95]
	v_mfma_f32_32x32x16_bf16 v[96:111], v[218:221], v[144:147], v[96:111]
	v_mfma_f32_32x32x16_bf16 v[112:127], v[214:217], v[206:209], v[112:127]
	v_mfma_f32_32x32x16_bf16 v[128:143], v[214:217], v[148:151], v[128:143]
	s_waitcnt lgkmcnt(4)
	v_mfma_f32_32x32x16_bf16 v[80:95], v[222:225], v[206:209], v[80:95]
	v_mfma_f32_32x32x16_bf16 v[96:111], v[222:225], v[148:151], v[96:111]
	s_waitcnt lgkmcnt(3)
	v_mfma_f32_32x32x16_bf16 v[48:63], v[152:155], v[202:205], v[48:63]
	v_add_f32_e32 v197, v197, v201
	v_mfma_f32_32x32x16_bf16 v[64:79], v[152:155], v[144:147], v[64:79]
	s_waitcnt lgkmcnt(1)
	v_mfma_f32_32x32x16_bf16 v[16:31], v[226:229], v[202:205], v[16:31]
	v_mfma_f32_32x32x16_bf16 v[32:47], v[226:229], v[144:147], v[32:47]
	v_mfma_f32_32x32x16_bf16 v[48:63], v[156:159], v[206:209], v[48:63]
	v_mfma_f32_32x32x16_bf16 v[64:79], v[156:159], v[148:151], v[64:79]
	s_waitcnt lgkmcnt(0)
	v_mfma_f32_32x32x16_bf16 v[16:31], v[230:233], v[206:209], v[16:31]
	v_mfma_f32_32x32x16_bf16 v[32:47], v[230:233], v[148:151], v[32:47]
.Lnd_109:
	s_or_b64 exec, exec, s[54:55]
	s_add_i32 s4, s97, 32
	v_cmp_le_i32_e64 s[4:5], s4, v195
	s_and_saveexec_b64 s[54:55], s[4:5]
	s_cbranch_execz .LBB0_111
	ds_read_b128 v[202:205], v199 offset:4608
	ds_read_b128 v[206:209], v199 offset:4640
	ds_read_b128 v[210:213], v193
	ds_read_b128 v[214:217], v193 offset:32
	ds_read_b128 v[218:221], v199 offset:4672
	ds_read_b128 v[222:225], v199 offset:4704
	ds_read_b128 v[226:229], v193 offset:64
	ds_read_b128 v[230:233], v193 offset:96
	s_waitcnt lgkmcnt(5)
	v_mfma_f32_32x32x16_bf16 v[144:159], v[202:205], v[210:213], v[0:15]
	s_waitcnt lgkmcnt(4)
	v_mfma_f32_32x32x16_bf16 v[144:159], v[206:209], v[214:217], v[144:159]
	s_waitcnt lgkmcnt(1)
	v_mfma_f32_32x32x16_bf16 v[144:159], v[218:221], v[226:229], v[144:159]
	s_waitcnt lgkmcnt(0)
	v_mfma_f32_32x32x16_bf16 v[144:159], v[222:225], v[230:233], v[144:159]
	s_nop 11
	v_exp_f32_e32 v146, v146
	v_exp_f32_e32 v147, v147
	v_exp_f32_e32 v148, v148
	v_exp_f32_e32 v149, v149
	v_exp_f32_e32 v150, v150
	v_exp_f32_e32 v151, v151
	v_exp_f32_e32 v152, v152
	v_exp_f32_e32 v153, v153
	v_exp_f32_e32 v144, v144
	v_exp_f32_e32 v145, v145
	v_exp_f32_e32 v154, v154
	v_exp_f32_e32 v155, v155
	v_add_f32_e32 v201, 0, v144
	v_add_f32_e32 v201, v145, v201
	v_add_f32_e32 v201, v146, v201
	v_exp_f32_e32 v156, v156
	v_add_f32_e32 v201, v147, v201
	v_add_f32_e32 v201, v148, v201
	v_add_f32_e32 v201, v149, v201
	v_exp_f32_e32 v157, v157
	v_add_f32_e32 v201, v150, v201
	v_add_f32_e32 v201, v151, v201
	v_add_f32_e32 v201, v152, v201
	v_exp_f32_e32 v158, v158
	v_add_f32_e32 v201, v153, v201
	v_exp_f32_e32 v159, v159
	v_add_f32_e32 v201, v154, v201
	v_add_f32_e32 v201, v155, v201
	v_add_f32_e32 v201, v156, v201
	v_add_f32_e32 v201, v157, v201
	v_add_f32_e32 v208, v158, v201
	v_cvt_pk_bf16_f32 v200, v144, v145
	v_add_f32_e32 v144, v159, v208
	v_add_f32_e32 v196, v196, v144
	v_cvt_pk_bf16_f32 v201, v146, v147
	v_cvt_pk_bf16_f32 v202, v148, v149
	v_cvt_pk_bf16_f32 v203, v150, v151
	v_cvt_pk_bf16_f32 v204, v152, v153
	v_cvt_pk_bf16_f32 v205, v154, v155
	v_cvt_pk_bf16_f32 v206, v156, v157
	v_cvt_pk_bf16_f32 v207, v158, v159
	ds_read_b128 v[208:211], v199 offset:13824
	ds_read_b128 v[212:215], v199 offset:13856
	ds_read_b128 v[216:219], v193 offset:36864
	ds_read_b128 v[220:223], v193 offset:36896
	ds_read_b128 v[224:227], v199 offset:13888
	ds_read_b128 v[228:231], v199 offset:13920
	ds_read_b128 v[232:235], v193 offset:36928
	ds_read_b128 v[236:239], v193 offset:36960
	s_waitcnt lgkmcnt(5)
	v_mfma_f32_32x32x16_bf16 v[144:159], v[208:211], v[216:219], v[0:15]
	s_waitcnt lgkmcnt(4)
	v_mfma_f32_32x32x16_bf16 v[144:159], v[212:215], v[220:223], v[144:159]
	ds_read_b128 v[208:211], v198 offset:64
	ds_read_b128 v[212:215], v198 offset:96
	ds_read_b128 v[216:219], v198 offset:4672
	ds_read_b128 v[220:223], v198 offset:4704
	s_waitcnt lgkmcnt(5)
	v_mfma_f32_32x32x16_bf16 v[144:159], v[224:227], v[232:235], v[144:159]
	s_waitcnt lgkmcnt(4)
	v_mfma_f32_32x32x16_bf16 v[144:159], v[228:231], v[236:239], v[144:159]
	s_nop 11
	v_exp_f32_e32 v144, v144
	v_exp_f32_e32 v145, v145
	v_exp_f32_e32 v146, v146
	v_exp_f32_e32 v147, v147
	v_exp_f32_e32 v148, v148
	v_exp_f32_e32 v149, v149
	v_add_f32_e32 v199, 0, v144
	v_exp_f32_e32 v150, v150
	v_add_f32_e32 v199, v145, v199
	v_exp_f32_e32 v151, v151
	v_add_f32_e32 v199, v146, v199
	v_exp_f32_e32 v152, v152
	v_add_f32_e32 v199, v147, v199
	v_exp_f32_e32 v153, v153
	v_add_f32_e32 v199, v148, v199
	v_exp_f32_e32 v154, v154
	v_add_f32_e32 v199, v149, v199
	v_exp_f32_e32 v155, v155
	v_add_f32_e32 v199, v150, v199
	v_exp_f32_e32 v156, v156
	v_add_f32_e32 v199, v151, v199
	v_exp_f32_e32 v157, v157
	v_add_f32_e32 v199, v152, v199
	v_exp_f32_e32 v158, v158
	v_add_f32_e32 v199, v153, v199
	v_exp_f32_e32 v159, v159
	v_add_f32_e32 v199, v154, v199
	v_add_f32_e32 v199, v155, v199
	v_add_f32_e32 v199, v156, v199
	v_add_f32_e32 v199, v157, v199
	v_add_f32_e32 v199, v158, v199
	v_cvt_pk_bf16_f32 v144, v144, v145
	v_cvt_pk_bf16_f32 v145, v146, v147
	v_cvt_pk_bf16_f32 v146, v148, v149
	v_cvt_pk_bf16_f32 v147, v150, v151
	v_cvt_pk_bf16_f32 v148, v152, v153
	v_cvt_pk_bf16_f32 v149, v154, v155
	v_cvt_pk_bf16_f32 v150, v156, v157
	v_cvt_pk_bf16_f32 v151, v158, v159
	v_add_f32_e32 v199, v159, v199
	ds_read_b128 v[152:155], v198 offset:9280
	ds_read_b128 v[156:159], v198 offset:9312
	ds_read_b128 v[224:227], v198 offset:13888
	ds_read_b128 v[228:231], v198 offset:13920
	s_waitcnt lgkmcnt(7)
	v_mfma_f32_32x32x16_bf16 v[112:127], v[208:211], v[200:203], v[112:127]
	v_mfma_f32_32x32x16_bf16 v[128:143], v[208:211], v[144:147], v[128:143]
	s_waitcnt lgkmcnt(5)
	v_mfma_f32_32x32x16_bf16 v[80:95], v[216:219], v[200:203], v[80:95]
	v_mfma_f32_32x32x16_bf16 v[96:111], v[216:219], v[144:147], v[96:111]
	v_mfma_f32_32x32x16_bf16 v[112:127], v[212:215], v[204:207], v[112:127]
	v_mfma_f32_32x32x16_bf16 v[128:143], v[212:215], v[148:151], v[128:143]
	s_waitcnt lgkmcnt(4)
	v_mfma_f32_32x32x16_bf16 v[80:95], v[220:223], v[204:207], v[80:95]
	v_mfma_f32_32x32x16_bf16 v[96:111], v[220:223], v[148:151], v[96:111]
	s_waitcnt lgkmcnt(3)
	v_mfma_f32_32x32x16_bf16 v[48:63], v[152:155], v[200:203], v[48:63]
	v_add_f32_e32 v197, v197, v199
	v_mfma_f32_32x32x16_bf16 v[64:79], v[152:155], v[144:147], v[64:79]
	s_waitcnt lgkmcnt(1)
	v_mfma_f32_32x32x16_bf16 v[16:31], v[224:227], v[200:203], v[16:31]
	v_mfma_f32_32x32x16_bf16 v[32:47], v[224:227], v[144:147], v[32:47]
	v_mfma_f32_32x32x16_bf16 v[48:63], v[156:159], v[204:207], v[48:63]
	v_mfma_f32_32x32x16_bf16 v[64:79], v[156:159], v[148:151], v[64:79]
	s_waitcnt lgkmcnt(0)
	v_mfma_f32_32x32x16_bf16 v[16:31], v[228:231], v[204:207], v[16:31]
	v_mfma_f32_32x32x16_bf16 v[32:47], v[228:231], v[148:151], v[32:47]
	s_branch .LBB0_111

.LBB0_164:
	s_ashr_i32 s33, s30, 2
	s_and_b32 s33, s33, -8
	s_or_b32 s33, s33, s3
	s_ashr_i32 s37, s33, 31
	s_lshr_b32 s37, s37, 29
	s_add_i32 s37, s33, s37
	s_ashr_i32 s39, s37, 3
	s_and_b32 s37, s37, 0x1ffff8
	s_sub_i32 s37, s33, s37
	s_lshl_b32 s38, s30, 8
	s_lshl_b32 s37, s37, 11
	s_and_b32 s38, s38, 0x700
	s_or_b32 s37, s37, s38
	s_lshl_b32 s38, s30, 5
	s_lshl_b32 s40, s39, 10
	s_and_b32 s38, s38, 0x300
	v_add_u32_e32 v0, s37, v149
	s_or_b32 s38, s40, s38
	v_ashrrev_i32_e32 v1, 31, v0
	v_add_u32_e32 v2, s38, v149
	v_lshlrev_b64 v[0:1], 12, v[0:1]
	v_ashrrev_i32_e32 v3, 31, v2
	v_readfirstlane_b32 s41, v150
	v_lshl_add_u64 v[0:1], v[130:131], 0, v[0:1]
	v_lshlrev_b64 v[2:3], 12, v[2:3]
	s_add_i32 m0, s41, -16
	v_readfirstlane_b32 s41, v128
	v_lshl_add_u64 v[2:3], v[132:133], 0, v[2:3]
	global_load_lds_dwordx4 v[0:1], off
	s_add_i32 m0, s41, -16
	v_readfirstlane_b32 s41, v160
	global_load_lds_dwordx4 v[2:3], off
	v_lshl_add_u64 v[4:5], v[0:1], 0, s[12:13]
	s_add_i32 m0, s41, -16
	v_readfirstlane_b32 s41, v161
	global_load_lds_dwordx4 v[4:5], off
	v_lshl_add_u64 v[4:5], v[2:3], 0, s[12:13]
	s_add_i32 m0, s41, -16
	v_readfirstlane_b32 s41, v162
	global_load_lds_dwordx4 v[4:5], off
	v_lshl_add_u64 v[4:5], v[0:1], 0, s[14:15]
	s_add_i32 m0, s41, -16
	v_readfirstlane_b32 s41, v163
	global_load_lds_dwordx4 v[4:5], off
	v_lshl_add_u64 v[4:5], v[2:3], 0, s[14:15]
	s_add_i32 m0, s41, -16
	v_readfirstlane_b32 s41, v164
	global_load_lds_dwordx4 v[4:5], off
	v_lshl_add_u64 v[0:1], v[0:1], 0, s[16:17]
	s_add_i32 m0, s41, -16
	v_readfirstlane_b32 s41, v165
	global_load_lds_dwordx4 v[0:1], off
	v_lshl_add_u64 v[0:1], v[2:3], 0, s[16:17]
	s_add_i32 m0, s41, -16
	s_and_b32 s28, s31, 0x700
	global_load_lds_dwordx4 v[0:1], off
	s_lshl_b32 s33, s33, 11
	s_or_b32 s28, s28, s33
	v_add_u32_e32 v0, s28, v149
	s_lshl_b32 s28, s39, 14
	v_subrev_u32_e32 v0, s28, v0
	s_and_b32 s29, s35, 0x300
	v_ashrrev_i32_e32 v1, 31, v0
	v_lshlrev_b64 v[0:1], 12, v[0:1]
	s_or_b32 s28, s29, s40
	v_lshl_add_u64 v[138:139], v[134:135], 0, v[0:1]
	v_add_u32_e32 v0, s28, v149
	v_ashrrev_i32_e32 v1, 31, v0
	v_lshlrev_b64 v[0:1], 12, v[0:1]
	v_lshl_add_u64 v[140:141], v[136:137], 0, v[0:1]
	s_mov_b32 s39, 0
	s_mov_b64 s[28:29], 0
	v_mov_b32_e32 v0, 0
	v_mov_b32_e32 v1, v129
	v_mov_b32_e32 v2, v129
	v_mov_b32_e32 v3, v129
	v_mov_b32_e32 v4, v129
	v_mov_b32_e32 v5, v129
	v_mov_b32_e32 v6, v129
	v_mov_b32_e32 v7, v129
	v_mov_b32_e32 v8, v129
	v_mov_b32_e32 v9, v129
	v_mov_b32_e32 v10, v129
	v_mov_b32_e32 v11, v129
	v_mov_b32_e32 v12, v129
	v_mov_b32_e32 v13, v129
	v_mov_b32_e32 v14, v129
	v_mov_b32_e32 v15, v129
	v_mov_b32_e32 v16, 0
	v_mov_b32_e32 v17, v129
	v_mov_b32_e32 v18, v129
	v_mov_b32_e32 v19, v129
	v_mov_b32_e32 v20, v129
	v_mov_b32_e32 v21, v129
	v_mov_b32_e32 v22, v129
	v_mov_b32_e32 v23, v129
	v_mov_b32_e32 v24, v129
	v_mov_b32_e32 v25, v129
	v_mov_b32_e32 v26, v129
	v_mov_b32_e32 v27, v129
	v_mov_b32_e32 v28, v129
	v_mov_b32_e32 v29, v129
	v_mov_b32_e32 v30, v129
	v_mov_b32_e32 v31, v129
	v_mov_b32_e32 v32, 0
	v_mov_b32_e32 v33, v129
	v_mov_b32_e32 v34, v129
	v_mov_b32_e32 v35, v129
	v_mov_b32_e32 v36, v129
	v_mov_b32_e32 v37, v129
	v_mov_b32_e32 v38, v129
	v_mov_b32_e32 v39, v129
	v_mov_b32_e32 v40, v129
	v_mov_b32_e32 v41, v129
	v_mov_b32_e32 v42, v129
	v_mov_b32_e32 v43, v129
	v_mov_b32_e32 v44, v129
	v_mov_b32_e32 v45, v129
	v_mov_b32_e32 v46, v129
	v_mov_b32_e32 v47, v129
	v_mov_b32_e32 v48, 0
	v_mov_b32_e32 v49, v129
	v_mov_b32_e32 v50, v129
	v_mov_b32_e32 v51, v129
	v_mov_b32_e32 v52, v129
	v_mov_b32_e32 v53, v129
	v_mov_b32_e32 v54, v129
	v_mov_b32_e32 v55, v129
	v_mov_b32_e32 v56, v129
	v_mov_b32_e32 v57, v129
	v_mov_b32_e32 v58, v129
	v_mov_b32_e32 v59, v129
	v_mov_b32_e32 v60, v129
	v_mov_b32_e32 v61, v129
	v_mov_b32_e32 v62, v129
	v_mov_b32_e32 v63, v129
	v_mov_b32_e32 v64, 0
	v_mov_b32_e32 v65, v129
	v_mov_b32_e32 v66, v129
	v_mov_b32_e32 v67, v129
	v_mov_b32_e32 v68, v129
	v_mov_b32_e32 v69, v129
	v_mov_b32_e32 v70, v129
	v_mov_b32_e32 v71, v129
	v_mov_b32_e32 v72, v129
	v_mov_b32_e32 v73, v129
	v_mov_b32_e32 v74, v129
	v_mov_b32_e32 v75, v129
	v_mov_b32_e32 v76, v129
	v_mov_b32_e32 v77, v129
	v_mov_b32_e32 v78, v129
	v_mov_b32_e32 v79, v129
	v_mov_b32_e32 v80, 0
	v_mov_b32_e32 v81, v129
	v_mov_b32_e32 v82, v129
	v_mov_b32_e32 v83, v129
	v_mov_b32_e32 v84, v129
	v_mov_b32_e32 v85, v129
	v_mov_b32_e32 v86, v129
	v_mov_b32_e32 v87, v129
	v_mov_b32_e32 v88, v129
	v_mov_b32_e32 v89, v129
	v_mov_b32_e32 v90, v129
	v_mov_b32_e32 v91, v129
	v_mov_b32_e32 v92, v129
	v_mov_b32_e32 v93, v129
	v_mov_b32_e32 v94, v129
	v_mov_b32_e32 v95, v129
	v_mov_b32_e32 v96, 0
	v_mov_b32_e32 v97, v129
	v_mov_b32_e32 v98, v129
	v_mov_b32_e32 v99, v129
	v_mov_b32_e32 v100, v129
	v_mov_b32_e32 v101, v129
	v_mov_b32_e32 v102, v129
	v_mov_b32_e32 v103, v129
	v_mov_b32_e32 v104, v129
	v_mov_b32_e32 v105, v129
	v_mov_b32_e32 v106, v129
	v_mov_b32_e32 v107, v129
	v_mov_b32_e32 v108, v129
	v_mov_b32_e32 v109, v129
	v_mov_b32_e32 v110, v129
	v_mov_b32_e32 v111, v129
	v_mov_b32_e32 v112, 0
	v_mov_b32_e32 v113, v129
	v_mov_b32_e32 v114, v129
	v_mov_b32_e32 v115, v129
	v_mov_b32_e32 v116, v129
	v_mov_b32_e32 v117, v129
	v_mov_b32_e32 v118, v129
	v_mov_b32_e32 v119, v129
	v_mov_b32_e32 v120, v129
	v_mov_b32_e32 v121, v129
	v_mov_b32_e32 v122, v129
	v_mov_b32_e32 v123, v129
	v_mov_b32_e32 v124, v129
	v_mov_b32_e32 v125, v129
	v_mov_b32_e32 v126, v129
	v_mov_b32_e32 v127, v129
	s_waitcnt vmcnt(0) lgkmcnt(0)
	s_barrier
	v_readfirstlane_b32 s48, v150
	s_sub_u32 s48, s48, 16
	s_mov_b32 s49, 0
	s_mov_b32 s50, 0x8000
	s_mov_b32 s52, 0x10000
	v_add_u32_e32 v142, v154, v155
	v_add_u32_e32 v145, v156, v155
	s_add_u32 m0, s52, s48
	v_lshl_add_u64 v[170:171], v[138:139], 0, s[18:19]
	global_load_lds_dwordx4 v[170:171], off
	s_add_u32 s53, s52, s48
	s_add_u32 m0, s53, 0x2000
	v_lshl_add_u64 v[170:171], v[138:139], 0, s[20:21]
	global_load_lds_dwordx4 v[170:171], off
	s_add_u32 s53, s52, s48
	s_add_u32 m0, s53, 0x4000
	v_lshl_add_u64 v[170:171], v[138:139], 0, s[22:23]
	global_load_lds_dwordx4 v[170:171], off
	s_add_u32 s53, s52, s48
	s_add_u32 m0, s53, 0x6000
	v_lshl_add_u64 v[170:171], v[138:139], 0, s[24:25]
	global_load_lds_dwordx4 v[170:171], off
	v_add3_u32 v143, v153, v142, s49
	v_add3_u32 v144, v153, v145, s50
	ds_read_b128 v[188:191], v144
	ds_read_b128 v[196:199], v143
	ds_read_b128 v[192:195], v144 offset:4096
	ds_read_b128 v[200:203], v143 offset:4096
	ds_read_b128 v[204:207], v143 offset:8192
	ds_read_b128 v[208:211], v143 offset:12288
.Lgr2_loop:
	s_add_u32 s51, s50, 0x10000
	s_sub_u32 s53, s51, 0x28000
	s_cmp_ge_u32 s51, 0x28000
	s_cselect_b32 s51, s53, s51
	s_add_u32 s52, s49, 0x20000
	s_sub_u32 s53, s52, 0x28000
	s_cmp_ge_u32 s52, 0x28000
	s_cselect_b32 s52, s53, s52
	v_add3_u32 v143, v157, v142, s49
	v_add3_u32 v144, v157, v145, s50
	ds_read_b128 v[212:215], v144
	ds_read_b128 v[220:223], v143
	ds_read_b128 v[216:219], v144 offset:4096
	ds_read_b128 v[224:227], v143 offset:4096
	ds_read_b128 v[228:231], v143 offset:8192
	ds_read_b128 v[232:235], v143 offset:12288
	s_add_u32 s54, s28, 0x80
	s_addc_u32 s55, s29, 0
	v_lshl_add_u64 v[166:167], v[138:139], 0, s[54:55]
	v_lshl_add_u64 v[168:169], v[140:141], 0, s[28:29]
	s_waitcnt lgkmcnt(6)
	v_mfma_f32_32x32x16_bf16 v[112:127], v[188:191], v[196:199], v[112:127]
	s_add_u32 m0, s51, s48
	v_lshl_add_u64 v[170:171], v[168:169], 0, s[18:19]
	global_load_lds_dwordx4 v[170:171], off
	v_mfma_f32_32x32x16_bf16 v[96:111], v[192:195], v[196:199], v[96:111]
	s_add_u32 s53, s51, s48
	s_add_u32 m0, s53, 0x2000
	v_lshl_add_u64 v[170:171], v[168:169], 0, s[20:21]
	global_load_lds_dwordx4 v[170:171], off
	v_mfma_f32_32x32x16_bf16 v[80:95], v[188:191], v[200:203], v[80:95]
	s_add_u32 s53, s51, s48
	s_add_u32 m0, s53, 0x4000
	v_lshl_add_u64 v[170:171], v[168:169], 0, s[22:23]
	global_load_lds_dwordx4 v[170:171], off
	v_mfma_f32_32x32x16_bf16 v[64:79], v[192:195], v[200:203], v[64:79]
	s_add_u32 s53, s51, s48
	s_add_u32 m0, s53, 0x6000
	v_lshl_add_u64 v[170:171], v[168:169], 0, s[24:25]
	global_load_lds_dwordx4 v[170:171], off
	v_mfma_f32_32x32x16_bf16 v[48:63], v[188:191], v[204:207], v[48:63]
	s_add_u32 m0, s52, s48
	v_lshl_add_u64 v[170:171], v[166:167], 0, s[18:19]
	global_load_lds_dwordx4 v[170:171], off
	v_mfma_f32_32x32x16_bf16 v[32:47], v[192:195], v[204:207], v[32:47]
	s_add_u32 s53, s52, s48
	s_add_u32 m0, s53, 0x2000
	v_lshl_add_u64 v[170:171], v[166:167], 0, s[20:21]
	global_load_lds_dwordx4 v[170:171], off
	v_mfma_f32_32x32x16_bf16 v[16:31], v[188:191], v[208:211], v[16:31]
	s_add_u32 s53, s52, s48
	s_add_u32 m0, s53, 0x4000
	v_lshl_add_u64 v[170:171], v[166:167], 0, s[22:23]
	global_load_lds_dwordx4 v[170:171], off
	v_mfma_f32_32x32x16_bf16 v[0:15], v[192:195], v[208:211], v[0:15]
	s_add_u32 s53, s52, s48
	s_add_u32 m0, s53, 0x6000
	v_lshl_add_u64 v[170:171], v[166:167], 0, s[24:25]
	global_load_lds_dwordx4 v[170:171], off
	v_add3_u32 v143, v158, v142, s49
	v_add3_u32 v144, v158, v145, s50
	ds_read_b128 v[188:191], v144
	ds_read_b128 v[196:199], v143
	ds_read_b128 v[192:195], v144 offset:4096
	ds_read_b128 v[200:203], v143 offset:4096
	ds_read_b128 v[204:207], v143 offset:8192
	ds_read_b128 v[208:211], v143 offset:12288
	s_waitcnt lgkmcnt(6)
	v_mfma_f32_32x32x16_bf16 v[112:127], v[212:215], v[220:223], v[112:127]
	v_mfma_f32_32x32x16_bf16 v[96:111], v[216:219], v[220:223], v[96:111]
	v_mfma_f32_32x32x16_bf16 v[80:95], v[212:215], v[224:227], v[80:95]
	v_mfma_f32_32x32x16_bf16 v[64:79], v[216:219], v[224:227], v[64:79]
	v_mfma_f32_32x32x16_bf16 v[48:63], v[212:215], v[228:231], v[48:63]
	v_mfma_f32_32x32x16_bf16 v[32:47], v[216:219], v[228:231], v[32:47]
	v_mfma_f32_32x32x16_bf16 v[16:31], v[212:215], v[232:235], v[16:31]
	v_mfma_f32_32x32x16_bf16 v[0:15], v[216:219], v[232:235], v[0:15]
	v_add3_u32 v143, v159, v142, s49
	v_add3_u32 v144, v159, v145, s50
	ds_read_b128 v[212:215], v144
	ds_read_b128 v[220:223], v143
	ds_read_b128 v[216:219], v144 offset:4096
	ds_read_b128 v[224:227], v143 offset:4096
	ds_read_b128 v[228:231], v143 offset:8192
	ds_read_b128 v[232:235], v143 offset:12288
	s_waitcnt lgkmcnt(6)
	v_mfma_f32_32x32x16_bf16 v[112:127], v[188:191], v[196:199], v[112:127]
	v_mfma_f32_32x32x16_bf16 v[96:111], v[192:195], v[196:199], v[96:111]
	v_mfma_f32_32x32x16_bf16 v[80:95], v[188:191], v[200:203], v[80:95]
	v_mfma_f32_32x32x16_bf16 v[64:79], v[192:195], v[200:203], v[64:79]
	v_mfma_f32_32x32x16_bf16 v[48:63], v[188:191], v[204:207], v[48:63]
	v_mfma_f32_32x32x16_bf16 v[32:47], v[192:195], v[204:207], v[32:47]
	v_mfma_f32_32x32x16_bf16 v[16:31], v[188:191], v[208:211], v[16:31]
	v_mfma_f32_32x32x16_bf16 v[0:15], v[192:195], v[208:211], v[0:15]
	s_waitcnt lgkmcnt(0)
	v_mfma_f32_32x32x16_bf16 v[112:127], v[212:215], v[220:223], v[112:127]
	v_mfma_f32_32x32x16_bf16 v[96:111], v[216:219], v[220:223], v[96:111]
	v_mfma_f32_32x32x16_bf16 v[80:95], v[212:215], v[224:227], v[80:95]
	v_mfma_f32_32x32x16_bf16 v[64:79], v[216:219], v[224:227], v[64:79]
	s_add_u32 s28, s28, 0x80
	s_addc_u32 s29, s29, 0
	s_add_u32 s49, s49, 0x10000
	s_sub_u32 s53, s49, 0x28000
	s_cmp_ge_u32 s49, 0x28000
	s_cselect_b32 s49, s53, s49
	s_mov_b32 s50, s51
	s_waitcnt vmcnt(4)
	s_barrier
	v_add3_u32 v143, v153, v142, s49
	v_add3_u32 v144, v153, v145, s50
	ds_read_b128 v[188:191], v144
	ds_read_b128 v[196:199], v143
	ds_read_b128 v[192:195], v144 offset:4096
	ds_read_b128 v[200:203], v143 offset:4096
	ds_read_b128 v[204:207], v143 offset:8192
	ds_read_b128 v[208:211], v143 offset:12288
	v_mfma_f32_32x32x16_bf16 v[48:63], v[212:215], v[228:231], v[48:63]
	v_mfma_f32_32x32x16_bf16 v[32:47], v[216:219], v[228:231], v[32:47]
	v_mfma_f32_32x32x16_bf16 v[16:31], v[212:215], v[232:235], v[16:31]
	v_mfma_f32_32x32x16_bf16 v[0:15], v[216:219], v[232:235], v[0:15]
	s_cmpk_lg_i32 s28, 0xf00
	s_cbranch_scc1 .Lgr2_loop
	s_add_u32 s51, s50, 0x10000
	s_sub_u32 s53, s51, 0x28000
	s_cmp_ge_u32 s51, 0x28000
	s_cselect_b32 s51, s53, s51
	v_add3_u32 v143, v157, v142, s49
	v_add3_u32 v144, v157, v145, s50
	ds_read_b128 v[212:215], v144
	ds_read_b128 v[220:223], v143
	ds_read_b128 v[216:219], v144 offset:4096
	ds_read_b128 v[224:227], v143 offset:4096
	ds_read_b128 v[228:231], v143 offset:8192
	ds_read_b128 v[232:235], v143 offset:12288
	s_add_u32 s54, s28, 0x80
	s_addc_u32 s55, s29, 0
	v_lshl_add_u64 v[166:167], v[138:139], 0, s[54:55]
	v_lshl_add_u64 v[168:169], v[140:141], 0, s[28:29]
	s_waitcnt lgkmcnt(6)
	v_mfma_f32_32x32x16_bf16 v[112:127], v[188:191], v[196:199], v[112:127]
	s_add_u32 m0, s51, s48
	v_lshl_add_u64 v[170:171], v[168:169], 0, s[18:19]
	global_load_lds_dwordx4 v[170:171], off
	v_mfma_f32_32x32x16_bf16 v[96:111], v[192:195], v[196:199], v[96:111]
	s_add_u32 s53, s51, s48
	s_add_u32 m0, s53, 0x2000
	v_lshl_add_u64 v[170:171], v[168:169], 0, s[20:21]
	global_load_lds_dwordx4 v[170:171], off
	v_mfma_f32_32x32x16_bf16 v[80:95], v[188:191], v[200:203], v[80:95]
	s_add_u32 s53, s51, s48
	s_add_u32 m0, s53, 0x4000
	v_lshl_add_u64 v[170:171], v[168:169], 0, s[22:23]
	global_load_lds_dwordx4 v[170:171], off
	v_mfma_f32_32x32x16_bf16 v[64:79], v[192:195], v[200:203], v[64:79]
	s_add_u32 s53, s51, s48
	s_add_u32 m0, s53, 0x6000
	v_lshl_add_u64 v[170:171], v[168:169], 0, s[24:25]
	global_load_lds_dwordx4 v[170:171], off
	v_mfma_f32_32x32x16_bf16 v[48:63], v[188:191], v[204:207], v[48:63]
	v_mfma_f32_32x32x16_bf16 v[32:47], v[192:195], v[204:207], v[32:47]
	v_mfma_f32_32x32x16_bf16 v[16:31], v[188:191], v[208:211], v[16:31]
	v_mfma_f32_32x32x16_bf16 v[0:15], v[192:195], v[208:211], v[0:15]
	v_add3_u32 v143, v158, v142, s49
	v_add3_u32 v144, v158, v145, s50
	ds_read_b128 v[188:191], v144
	ds_read_b128 v[196:199], v143
	ds_read_b128 v[192:195], v144 offset:4096
	ds_read_b128 v[200:203], v143 offset:4096
	ds_read_b128 v[204:207], v143 offset:8192
	ds_read_b128 v[208:211], v143 offset:12288
	s_waitcnt lgkmcnt(6)
	v_mfma_f32_32x32x16_bf16 v[112:127], v[212:215], v[220:223], v[112:127]
	v_mfma_f32_32x32x16_bf16 v[96:111], v[216:219], v[220:223], v[96:111]
	v_mfma_f32_32x32x16_bf16 v[80:95], v[212:215], v[224:227], v[80:95]
	v_mfma_f32_32x32x16_bf16 v[64:79], v[216:219], v[224:227], v[64:79]
	v_mfma_f32_32x32x16_bf16 v[48:63], v[212:215], v[228:231], v[48:63]
	v_mfma_f32_32x32x16_bf16 v[32:47], v[216:219], v[228:231], v[32:47]
	v_mfma_f32_32x32x16_bf16 v[16:31], v[212:215], v[232:235], v[16:31]
	v_mfma_f32_32x32x16_bf16 v[0:15], v[216:219], v[232:235], v[0:15]
	v_add3_u32 v143, v159, v142, s49
	v_add3_u32 v144, v159, v145, s50
	ds_read_b128 v[212:215], v144
	ds_read_b128 v[220:223], v143
	ds_read_b128 v[216:219], v144 offset:4096
	ds_read_b128 v[224:227], v143 offset:4096
	ds_read_b128 v[228:231], v143 offset:8192
	ds_read_b128 v[232:235], v143 offset:12288
	s_waitcnt lgkmcnt(6)
	v_mfma_f32_32x32x16_bf16 v[112:127], v[188:191], v[196:199], v[112:127]
	v_mfma_f32_32x32x16_bf16 v[96:111], v[192:195], v[196:199], v[96:111]
	v_mfma_f32_32x32x16_bf16 v[80:95], v[188:191], v[200:203], v[80:95]
	v_mfma_f32_32x32x16_bf16 v[64:79], v[192:195], v[200:203], v[64:79]
	v_mfma_f32_32x32x16_bf16 v[48:63], v[188:191], v[204:207], v[48:63]
	v_mfma_f32_32x32x16_bf16 v[32:47], v[192:195], v[204:207], v[32:47]
	v_mfma_f32_32x32x16_bf16 v[16:31], v[188:191], v[208:211], v[16:31]
	v_mfma_f32_32x32x16_bf16 v[0:15], v[192:195], v[208:211], v[0:15]
	s_waitcnt lgkmcnt(0)
	v_mfma_f32_32x32x16_bf16 v[112:127], v[212:215], v[220:223], v[112:127]
	v_mfma_f32_32x32x16_bf16 v[96:111], v[216:219], v[220:223], v[96:111]
	v_mfma_f32_32x32x16_bf16 v[80:95], v[212:215], v[224:227], v[80:95]
	v_mfma_f32_32x32x16_bf16 v[64:79], v[216:219], v[224:227], v[64:79]
	s_add_u32 s28, s28, 0x80
	s_addc_u32 s29, s29, 0
	s_add_u32 s49, s49, 0x10000
	s_sub_u32 s53, s49, 0x28000
	s_cmp_ge_u32 s49, 0x28000
	s_cselect_b32 s49, s53, s49
	s_mov_b32 s50, s51
	s_waitcnt vmcnt(0)
	s_barrier
	v_add3_u32 v143, v153, v142, s49
	v_add3_u32 v144, v153, v145, s50
	ds_read_b128 v[188:191], v144
	ds_read_b128 v[196:199], v143
	ds_read_b128 v[192:195], v144 offset:4096
	ds_read_b128 v[200:203], v143 offset:4096
	ds_read_b128 v[204:207], v143 offset:8192
	ds_read_b128 v[208:211], v143 offset:12288
	v_mfma_f32_32x32x16_bf16 v[48:63], v[212:215], v[228:231], v[48:63]
	v_mfma_f32_32x32x16_bf16 v[32:47], v[216:219], v[228:231], v[32:47]
	v_mfma_f32_32x32x16_bf16 v[16:31], v[212:215], v[232:235], v[16:31]
	v_mfma_f32_32x32x16_bf16 v[0:15], v[216:219], v[232:235], v[0:15]
	v_add3_u32 v143, v157, v142, s49
	v_add3_u32 v144, v157, v145, s50
	ds_read_b128 v[212:215], v144
	ds_read_b128 v[220:223], v143
	ds_read_b128 v[216:219], v144 offset:4096
	ds_read_b128 v[224:227], v143 offset:4096
	ds_read_b128 v[228:231], v143 offset:8192
	ds_read_b128 v[232:235], v143 offset:12288
	s_waitcnt lgkmcnt(6)
	v_mfma_f32_32x32x16_bf16 v[112:127], v[188:191], v[196:199], v[112:127]
	v_mfma_f32_32x32x16_bf16 v[96:111], v[192:195], v[196:199], v[96:111]
	v_mfma_f32_32x32x16_bf16 v[80:95], v[188:191], v[200:203], v[80:95]
	v_mfma_f32_32x32x16_bf16 v[64:79], v[192:195], v[200:203], v[64:79]
	v_mfma_f32_32x32x16_bf16 v[48:63], v[188:191], v[204:207], v[48:63]
	v_mfma_f32_32x32x16_bf16 v[32:47], v[192:195], v[204:207], v[32:47]
	v_mfma_f32_32x32x16_bf16 v[16:31], v[188:191], v[208:211], v[16:31]
	v_mfma_f32_32x32x16_bf16 v[0:15], v[192:195], v[208:211], v[0:15]
	v_add3_u32 v143, v158, v142, s49
	v_add3_u32 v144, v158, v145, s50
	ds_read_b128 v[188:191], v144
	ds_read_b128 v[196:199], v143
	ds_read_b128 v[192:195], v144 offset:4096
	ds_read_b128 v[200:203], v143 offset:4096
	ds_read_b128 v[204:207], v143 offset:8192
	ds_read_b128 v[208:211], v143 offset:12288
	s_waitcnt lgkmcnt(6)
	v_mfma_f32_32x32x16_bf16 v[112:127], v[212:215], v[220:223], v[112:127]
	v_mfma_f32_32x32x16_bf16 v[96:111], v[216:219], v[220:223], v[96:111]
	v_mfma_f32_32x32x16_bf16 v[80:95], v[212:215], v[224:227], v[80:95]
	v_mfma_f32_32x32x16_bf16 v[64:79], v[216:219], v[224:227], v[64:79]
	v_mfma_f32_32x32x16_bf16 v[48:63], v[212:215], v[228:231], v[48:63]
	v_mfma_f32_32x32x16_bf16 v[32:47], v[216:219], v[228:231], v[32:47]
	v_mfma_f32_32x32x16_bf16 v[16:31], v[212:215], v[232:235], v[16:31]
	v_mfma_f32_32x32x16_bf16 v[0:15], v[216:219], v[232:235], v[0:15]
	v_add3_u32 v143, v159, v142, s49
	v_add3_u32 v144, v159, v145, s50
	ds_read_b128 v[212:215], v144
	ds_read_b128 v[220:223], v143
	ds_read_b128 v[216:219], v144 offset:4096
	ds_read_b128 v[224:227], v143 offset:4096
	ds_read_b128 v[228:231], v143 offset:8192
	ds_read_b128 v[232:235], v143 offset:12288
	s_waitcnt lgkmcnt(6)
	v_mfma_f32_32x32x16_bf16 v[112:127], v[188:191], v[196:199], v[112:127]
	v_mfma_f32_32x32x16_bf16 v[96:111], v[192:195], v[196:199], v[96:111]
	v_mfma_f32_32x32x16_bf16 v[80:95], v[188:191], v[200:203], v[80:95]
	v_mfma_f32_32x32x16_bf16 v[64:79], v[192:195], v[200:203], v[64:79]
	v_mfma_f32_32x32x16_bf16 v[48:63], v[188:191], v[204:207], v[48:63]
	v_mfma_f32_32x32x16_bf16 v[32:47], v[192:195], v[204:207], v[32:47]
	v_mfma_f32_32x32x16_bf16 v[16:31], v[188:191], v[208:211], v[16:31]
	v_mfma_f32_32x32x16_bf16 v[0:15], v[192:195], v[208:211], v[0:15]
	s_waitcnt vmcnt(0) lgkmcnt(0)
	s_barrier
	v_mfma_f32_32x32x16_bf16 v[112:127], v[212:215], v[220:223], v[112:127]
	v_mfma_f32_32x32x16_bf16 v[96:111], v[216:219], v[220:223], v[96:111]
	v_mfma_f32_32x32x16_bf16 v[80:95], v[212:215], v[224:227], v[80:95]
	v_mfma_f32_32x32x16_bf16 v[64:79], v[216:219], v[224:227], v[64:79]
	v_mfma_f32_32x32x16_bf16 v[48:63], v[212:215], v[228:231], v[48:63]
	v_mfma_f32_32x32x16_bf16 v[32:47], v[216:219], v[228:231], v[32:47]
	v_mfma_f32_32x32x16_bf16 v[16:31], v[212:215], v[232:235], v[16:31]
	v_mfma_f32_32x32x16_bf16 v[0:15], v[216:219], v[232:235], v[0:15]
	s_nop 15
	s_branch .LBB0_163

.LBB0_198:
	s_ashr_i32 s27, s30, 2
	s_and_b32 s27, s27, -8
	s_or_b32 s33, s27, s3
	s_ashr_i32 s27, s33, 31
	s_lshr_b32 s27, s27, 29
	s_add_i32 s27, s33, s27
	s_ashr_i32 s46, s27, 3
	s_bfe_u32 s26, s30, 0x20003
	s_and_b32 s27, s27, 0x1ffff8
	s_lshl_b32 s47, s46, 2
	s_lshl_b32 s29, s26, 8
	s_sub_i32 s27, s33, s27
	s_or_b32 s26, s47, s26
	s_lshl_b32 s47, s30, 8
	s_lshl_b32 s27, s27, 11
	s_and_b32 s47, s47, 0x700
	s_or_b32 s27, s27, s47
	v_add_u32_e32 v0, s27, v142
	v_ashrrev_i32_e32 v1, 31, v0
	v_lshl_add_u32 v2, s26, 8, v142
	v_lshlrev_b64 v[0:1], 12, v[0:1]
	v_ashrrev_i32_e32 v3, 31, v2
	v_readfirstlane_b32 s47, v143
	v_add_u32_e32 v4, 0x8000, v143
	v_lshl_add_u64 v[0:1], v[130:131], 0, v[0:1]
	v_lshlrev_b64 v[2:3], 12, v[2:3]
	s_add_i32 m0, s47, -16
	v_readfirstlane_b32 s47, v4
	v_add_u32_e32 v6, 0x2000, v143
	v_lshl_add_u64 v[2:3], v[132:133], 0, v[2:3]
	global_load_lds_dwordx4 v[0:1], off
	s_add_i32 m0, s47, -16
	v_readfirstlane_b32 s47, v6
	v_add_u32_e32 v6, 0xa000, v143
	global_load_lds_dwordx4 v[2:3], off
	v_lshl_add_u64 v[4:5], v[0:1], 0, s[12:13]
	s_add_i32 m0, s47, -16
	v_readfirstlane_b32 s47, v6
	v_add_u32_e32 v6, 0x4000, v143
	global_load_lds_dwordx4 v[4:5], off
	v_lshl_add_u64 v[4:5], v[2:3], 0, s[12:13]
	s_add_i32 m0, s47, -16
	v_readfirstlane_b32 s47, v6
	v_add_u32_e32 v6, 0xc000, v143
	global_load_lds_dwordx4 v[4:5], off
	v_lshl_add_u64 v[4:5], v[0:1], 0, s[14:15]
	s_add_i32 m0, s47, -16
	v_readfirstlane_b32 s47, v6
	global_load_lds_dwordx4 v[4:5], off
	v_lshl_add_u64 v[4:5], v[2:3], 0, s[14:15]
	s_add_i32 m0, s47, -16
	v_lshl_add_u64 v[0:1], v[0:1], 0, s[16:17]
	global_load_lds_dwordx4 v[4:5], off
	v_add_u32_e32 v4, 0x6000, v143
	s_and_b32 s28, s34, 0x700
	v_readfirstlane_b32 s47, v4
	s_add_i32 m0, s47, -16
	s_lshl_b32 s33, s33, 11
	global_load_lds_dwordx4 v[0:1], off
	v_lshl_add_u64 v[0:1], v[2:3], 0, s[16:17]
	v_add_u32_e32 v2, 0xe000, v143
	s_or_b32 s28, s28, s33
	v_readfirstlane_b32 s47, v2
	s_add_i32 m0, s47, -16
	v_mov_b32_e32 v2, v129
	global_load_lds_dwordx4 v[0:1], off
	v_add_u32_e32 v0, s28, v142
	s_lshl_b32 s28, s46, 14
	v_subrev_u32_e32 v0, s28, v0
	v_ashrrev_i32_e32 v1, 31, v0
	s_lshl_b32 s28, s46, 10
	v_lshlrev_b64 v[0:1], 12, v[0:1]
	s_or_b32 s28, s29, s28
	v_lshl_add_u64 v[138:139], v[134:135], 0, v[0:1]
	v_add_u32_e32 v0, s28, v142
	v_ashrrev_i32_e32 v1, 31, v0
	v_lshlrev_b64 v[0:1], 12, v[0:1]
	v_lshl_add_u64 v[140:141], v[136:137], 0, v[0:1]
	s_mov_b64 s[28:29], 0
	s_mov_b32 s46, 0
	v_mov_b32_e32 v0, 0
	v_mov_b32_e32 v1, v129
	v_mov_b32_e32 v3, v129
	v_mov_b32_e32 v4, v129
	v_mov_b32_e32 v5, v129
	v_mov_b32_e32 v6, v129
	v_mov_b32_e32 v7, v129
	v_mov_b32_e32 v8, v129
	v_mov_b32_e32 v9, v129
	v_mov_b32_e32 v10, v129
	v_mov_b32_e32 v11, v129
	v_mov_b32_e32 v12, v129
	v_mov_b32_e32 v13, v129
	v_mov_b32_e32 v14, v129
	v_mov_b32_e32 v15, v129
	v_mov_b32_e32 v16, 0
	v_mov_b32_e32 v17, v129
	v_mov_b32_e32 v18, v129
	v_mov_b32_e32 v19, v129
	v_mov_b32_e32 v20, v129
	v_mov_b32_e32 v21, v129
	v_mov_b32_e32 v22, v129
	v_mov_b32_e32 v23, v129
	v_mov_b32_e32 v24, v129
	v_mov_b32_e32 v25, v129
	v_mov_b32_e32 v26, v129
	v_mov_b32_e32 v27, v129
	v_mov_b32_e32 v28, v129
	v_mov_b32_e32 v29, v129
	v_mov_b32_e32 v30, v129
	v_mov_b32_e32 v31, v129
	v_mov_b32_e32 v32, 0
	v_mov_b32_e32 v33, v129
	v_mov_b32_e32 v34, v129
	v_mov_b32_e32 v35, v129
	v_mov_b32_e32 v36, v129
	v_mov_b32_e32 v37, v129
	v_mov_b32_e32 v38, v129
	v_mov_b32_e32 v39, v129
	v_mov_b32_e32 v40, v129
	v_mov_b32_e32 v41, v129
	v_mov_b32_e32 v42, v129
	v_mov_b32_e32 v43, v129
	v_mov_b32_e32 v44, v129
	v_mov_b32_e32 v45, v129
	v_mov_b32_e32 v46, v129
	v_mov_b32_e32 v47, v129
	v_mov_b32_e32 v48, 0
	v_mov_b32_e32 v49, v129
	v_mov_b32_e32 v50, v129
	v_mov_b32_e32 v51, v129
	v_mov_b32_e32 v52, v129
	v_mov_b32_e32 v53, v129
	v_mov_b32_e32 v54, v129
	v_mov_b32_e32 v55, v129
	v_mov_b32_e32 v56, v129
	v_mov_b32_e32 v57, v129
	v_mov_b32_e32 v58, v129
	v_mov_b32_e32 v59, v129
	v_mov_b32_e32 v60, v129
	v_mov_b32_e32 v61, v129
	v_mov_b32_e32 v62, v129
	v_mov_b32_e32 v63, v129
	v_mov_b32_e32 v64, 0
	v_mov_b32_e32 v65, v129
	v_mov_b32_e32 v66, v129
	v_mov_b32_e32 v67, v129
	v_mov_b32_e32 v68, v129
	v_mov_b32_e32 v69, v129
	v_mov_b32_e32 v70, v129
	v_mov_b32_e32 v71, v129
	v_mov_b32_e32 v72, v129
	v_mov_b32_e32 v73, v129
	v_mov_b32_e32 v74, v129
	v_mov_b32_e32 v75, v129
	v_mov_b32_e32 v76, v129
	v_mov_b32_e32 v77, v129
	v_mov_b32_e32 v78, v129
	v_mov_b32_e32 v79, v129
	v_mov_b32_e32 v80, 0
	v_mov_b32_e32 v81, v129
	v_mov_b32_e32 v82, v129
	v_mov_b32_e32 v83, v129
	v_mov_b32_e32 v84, v129
	v_mov_b32_e32 v85, v129
	v_mov_b32_e32 v86, v129
	v_mov_b32_e32 v87, v129
	v_mov_b32_e32 v88, v129
	v_mov_b32_e32 v89, v129
	v_mov_b32_e32 v90, v129
	v_mov_b32_e32 v91, v129
	v_mov_b32_e32 v92, v129
	v_mov_b32_e32 v93, v129
	v_mov_b32_e32 v94, v129
	v_mov_b32_e32 v95, v129
	v_mov_b32_e32 v96, 0
	v_mov_b32_e32 v97, v129
	v_mov_b32_e32 v98, v129
	v_mov_b32_e32 v99, v129
	v_mov_b32_e32 v100, v129
	v_mov_b32_e32 v101, v129
	v_mov_b32_e32 v102, v129
	v_mov_b32_e32 v103, v129
	v_mov_b32_e32 v104, v129
	v_mov_b32_e32 v105, v129
	v_mov_b32_e32 v106, v129
	v_mov_b32_e32 v107, v129
	v_mov_b32_e32 v108, v129
	v_mov_b32_e32 v109, v129
	v_mov_b32_e32 v110, v129
	v_mov_b32_e32 v111, v129
	v_mov_b32_e32 v112, 0
	v_mov_b32_e32 v113, v129
	v_mov_b32_e32 v114, v129
	v_mov_b32_e32 v115, v129
	v_mov_b32_e32 v116, v129
	v_mov_b32_e32 v117, v129
	v_mov_b32_e32 v118, v129
	v_mov_b32_e32 v119, v129
	v_mov_b32_e32 v120, v129
	v_mov_b32_e32 v121, v129
	v_mov_b32_e32 v122, v129
	v_mov_b32_e32 v123, v129
	v_mov_b32_e32 v124, v129
	v_mov_b32_e32 v125, v129
	v_mov_b32_e32 v126, v129
	v_mov_b32_e32 v127, v129
	s_waitcnt vmcnt(0) lgkmcnt(0)
	s_barrier
	v_readfirstlane_b32 s48, v143
	s_sub_u32 s48, s48, 16
	s_mov_b32 s49, 0
	s_mov_b32 s50, 0x8000
	s_mov_b32 s52, 0x10000
	v_add_u32_e32 v240, v148, v149
	v_mov_b32_e32 v244, v150
	s_add_u32 m0, s52, s48
	v_lshl_add_u64 v[250:251], v[138:139], 0, s[18:19]
	global_load_lds_dwordx4 v[250:251], off
	s_add_u32 s53, s52, s48
	s_add_u32 m0, s53, 0x2000
	v_lshl_add_u64 v[250:251], v[138:139], 0, s[20:21]
	global_load_lds_dwordx4 v[250:251], off
	s_add_u32 s53, s52, s48
	s_add_u32 m0, s53, 0x4000
	v_lshl_add_u64 v[250:251], v[138:139], 0, s[22:23]
	global_load_lds_dwordx4 v[250:251], off
	s_add_u32 s53, s52, s48
	s_add_u32 m0, s53, 0x6000
	v_lshl_add_u64 v[250:251], v[138:139], 0, s[24:25]
	global_load_lds_dwordx4 v[250:251], off
	v_add3_u32 v241, v147, v240, s49
	v_add3_u32 v243, v147, v244, s50
	ds_read_b128 v[192:195], v243
	ds_read_b128 v[200:203], v241
	ds_read_b128 v[196:199], v243 offset:4096
	ds_read_b128 v[204:207], v241 offset:4096
	ds_read_b128 v[208:211], v241 offset:8192
	ds_read_b128 v[212:215], v241 offset:12288
.Lgr3_loop:
	s_add_u32 s51, s50, 0x10000
	s_sub_u32 s53, s51, 0x28000
	s_cmp_ge_u32 s51, 0x28000
	s_cselect_b32 s51, s53, s51
	s_add_u32 s52, s49, 0x20000
	s_sub_u32 s53, s52, 0x28000
	s_cmp_ge_u32 s52, 0x28000
	s_cselect_b32 s52, s53, s52
	v_add3_u32 v241, v151, v240, s49
	v_add3_u32 v243, v151, v244, s50
	ds_read_b128 v[216:219], v243
	ds_read_b128 v[224:227], v241
	ds_read_b128 v[220:223], v243 offset:4096
	ds_read_b128 v[228:231], v241 offset:4096
	ds_read_b128 v[232:235], v241 offset:8192
	ds_read_b128 v[236:239], v241 offset:12288
	s_add_u32 s54, s28, 0x80
	s_addc_u32 s55, s29, 0
	v_lshl_add_u64 v[246:247], v[138:139], 0, s[54:55]
	v_lshl_add_u64 v[248:249], v[140:141], 0, s[28:29]
	s_waitcnt lgkmcnt(6)
	v_mfma_f32_32x32x16_bf16 v[112:127], v[192:195], v[200:203], v[112:127]
	s_add_u32 m0, s51, s48
	v_lshl_add_u64 v[250:251], v[248:249], 0, s[18:19]
	global_load_lds_dwordx4 v[250:251], off
	v_mfma_f32_32x32x16_bf16 v[96:111], v[196:199], v[200:203], v[96:111]
	s_add_u32 s53, s51, s48
	s_add_u32 m0, s53, 0x2000
	v_lshl_add_u64 v[250:251], v[248:249], 0, s[20:21]
	global_load_lds_dwordx4 v[250:251], off
	v_mfma_f32_32x32x16_bf16 v[80:95], v[192:195], v[204:207], v[80:95]
	s_add_u32 s53, s51, s48
	s_add_u32 m0, s53, 0x4000
	v_lshl_add_u64 v[250:251], v[248:249], 0, s[22:23]
	global_load_lds_dwordx4 v[250:251], off
	v_mfma_f32_32x32x16_bf16 v[64:79], v[196:199], v[204:207], v[64:79]
	s_add_u32 s53, s51, s48
	s_add_u32 m0, s53, 0x6000
	v_lshl_add_u64 v[250:251], v[248:249], 0, s[24:25]
	global_load_lds_dwordx4 v[250:251], off
	v_mfma_f32_32x32x16_bf16 v[48:63], v[192:195], v[208:211], v[48:63]
	s_add_u32 m0, s52, s48
	v_lshl_add_u64 v[250:251], v[246:247], 0, s[18:19]
	global_load_lds_dwordx4 v[250:251], off
	v_mfma_f32_32x32x16_bf16 v[32:47], v[196:199], v[208:211], v[32:47]
	s_add_u32 s53, s52, s48
	s_add_u32 m0, s53, 0x2000
	v_lshl_add_u64 v[250:251], v[246:247], 0, s[20:21]
	global_load_lds_dwordx4 v[250:251], off
	v_mfma_f32_32x32x16_bf16 v[16:31], v[192:195], v[212:215], v[16:31]
	s_add_u32 s53, s52, s48
	s_add_u32 m0, s53, 0x4000
	v_lshl_add_u64 v[250:251], v[246:247], 0, s[22:23]
	global_load_lds_dwordx4 v[250:251], off
	v_mfma_f32_32x32x16_bf16 v[0:15], v[196:199], v[212:215], v[0:15]
	s_add_u32 s53, s52, s48
	s_add_u32 m0, s53, 0x6000
	v_lshl_add_u64 v[250:251], v[246:247], 0, s[24:25]
	global_load_lds_dwordx4 v[250:251], off
	v_add3_u32 v241, v152, v240, s49
	v_add3_u32 v243, v152, v244, s50
	ds_read_b128 v[192:195], v243
	ds_read_b128 v[200:203], v241
	ds_read_b128 v[196:199], v243 offset:4096
	ds_read_b128 v[204:207], v241 offset:4096
	ds_read_b128 v[208:211], v241 offset:8192
	ds_read_b128 v[212:215], v241 offset:12288
	s_waitcnt lgkmcnt(6)
	v_mfma_f32_32x32x16_bf16 v[112:127], v[216:219], v[224:227], v[112:127]
	v_mfma_f32_32x32x16_bf16 v[96:111], v[220:223], v[224:227], v[96:111]
	v_mfma_f32_32x32x16_bf16 v[80:95], v[216:219], v[228:231], v[80:95]
	v_mfma_f32_32x32x16_bf16 v[64:79], v[220:223], v[228:231], v[64:79]
	v_mfma_f32_32x32x16_bf16 v[48:63], v[216:219], v[232:235], v[48:63]
	v_mfma_f32_32x32x16_bf16 v[32:47], v[220:223], v[232:235], v[32:47]
	v_mfma_f32_32x32x16_bf16 v[16:31], v[216:219], v[236:239], v[16:31]
	v_mfma_f32_32x32x16_bf16 v[0:15], v[220:223], v[236:239], v[0:15]
	v_add3_u32 v241, v153, v240, s49
	v_add3_u32 v243, v153, v244, s50
	ds_read_b128 v[216:219], v243
	ds_read_b128 v[224:227], v241
	ds_read_b128 v[220:223], v243 offset:4096
	ds_read_b128 v[228:231], v241 offset:4096
	ds_read_b128 v[232:235], v241 offset:8192
	ds_read_b128 v[236:239], v241 offset:12288
	s_waitcnt lgkmcnt(6)
	v_mfma_f32_32x32x16_bf16 v[112:127], v[192:195], v[200:203], v[112:127]
	v_mfma_f32_32x32x16_bf16 v[96:111], v[196:199], v[200:203], v[96:111]
	v_mfma_f32_32x32x16_bf16 v[80:95], v[192:195], v[204:207], v[80:95]
	v_mfma_f32_32x32x16_bf16 v[64:79], v[196:199], v[204:207], v[64:79]
	v_mfma_f32_32x32x16_bf16 v[48:63], v[192:195], v[208:211], v[48:63]
	v_mfma_f32_32x32x16_bf16 v[32:47], v[196:199], v[208:211], v[32:47]
	v_mfma_f32_32x32x16_bf16 v[16:31], v[192:195], v[212:215], v[16:31]
	v_mfma_f32_32x32x16_bf16 v[0:15], v[196:199], v[212:215], v[0:15]
	s_waitcnt lgkmcnt(0)
	v_mfma_f32_32x32x16_bf16 v[112:127], v[216:219], v[224:227], v[112:127]
	v_mfma_f32_32x32x16_bf16 v[96:111], v[220:223], v[224:227], v[96:111]
	v_mfma_f32_32x32x16_bf16 v[80:95], v[216:219], v[228:231], v[80:95]
	v_mfma_f32_32x32x16_bf16 v[64:79], v[220:223], v[228:231], v[64:79]
	s_add_u32 s28, s28, 0x80
	s_addc_u32 s29, s29, 0
	s_add_u32 s49, s49, 0x10000
	s_sub_u32 s53, s49, 0x28000
	s_cmp_ge_u32 s49, 0x28000
	s_cselect_b32 s49, s53, s49
	s_mov_b32 s50, s51
	s_waitcnt vmcnt(4)
	s_barrier
	v_add3_u32 v241, v147, v240, s49
	v_add3_u32 v243, v147, v244, s50
	ds_read_b128 v[192:195], v243
	ds_read_b128 v[200:203], v241
	ds_read_b128 v[196:199], v243 offset:4096
	ds_read_b128 v[204:207], v241 offset:4096
	ds_read_b128 v[208:211], v241 offset:8192
	ds_read_b128 v[212:215], v241 offset:12288
	v_mfma_f32_32x32x16_bf16 v[48:63], v[216:219], v[232:235], v[48:63]
	v_mfma_f32_32x32x16_bf16 v[32:47], v[220:223], v[232:235], v[32:47]
	v_mfma_f32_32x32x16_bf16 v[16:31], v[216:219], v[236:239], v[16:31]
	v_mfma_f32_32x32x16_bf16 v[0:15], v[220:223], v[236:239], v[0:15]
	s_cmpk_lg_i32 s28, 0xf00
	s_cbranch_scc1 .Lgr3_loop
	s_add_u32 s51, s50, 0x10000
	s_sub_u32 s53, s51, 0x28000
	s_cmp_ge_u32 s51, 0x28000
	s_cselect_b32 s51, s53, s51
	v_add3_u32 v241, v151, v240, s49
	v_add3_u32 v243, v151, v244, s50
	ds_read_b128 v[216:219], v243
	ds_read_b128 v[224:227], v241
	ds_read_b128 v[220:223], v243 offset:4096
	ds_read_b128 v[228:231], v241 offset:4096
	ds_read_b128 v[232:235], v241 offset:8192
	ds_read_b128 v[236:239], v241 offset:12288
	s_add_u32 s54, s28, 0x80
	s_addc_u32 s55, s29, 0
	v_lshl_add_u64 v[246:247], v[138:139], 0, s[54:55]
	v_lshl_add_u64 v[248:249], v[140:141], 0, s[28:29]
	s_waitcnt lgkmcnt(6)
	v_mfma_f32_32x32x16_bf16 v[112:127], v[192:195], v[200:203], v[112:127]
	s_add_u32 m0, s51, s48
	v_lshl_add_u64 v[250:251], v[248:249], 0, s[18:19]
	global_load_lds_dwordx4 v[250:251], off
	v_mfma_f32_32x32x16_bf16 v[96:111], v[196:199], v[200:203], v[96:111]
	s_add_u32 s53, s51, s48
	s_add_u32 m0, s53, 0x2000
	v_lshl_add_u64 v[250:251], v[248:249], 0, s[20:21]
	global_load_lds_dwordx4 v[250:251], off
	v_mfma_f32_32x32x16_bf16 v[80:95], v[192:195], v[204:207], v[80:95]
	s_add_u32 s53, s51, s48
	s_add_u32 m0, s53, 0x4000
	v_lshl_add_u64 v[250:251], v[248:249], 0, s[22:23]
	global_load_lds_dwordx4 v[250:251], off
	v_mfma_f32_32x32x16_bf16 v[64:79], v[196:199], v[204:207], v[64:79]
	s_add_u32 s53, s51, s48
	s_add_u32 m0, s53, 0x6000
	v_lshl_add_u64 v[250:251], v[248:249], 0, s[24:25]
	global_load_lds_dwordx4 v[250:251], off
	v_mfma_f32_32x32x16_bf16 v[48:63], v[192:195], v[208:211], v[48:63]
	v_mfma_f32_32x32x16_bf16 v[32:47], v[196:199], v[208:211], v[32:47]
	v_mfma_f32_32x32x16_bf16 v[16:31], v[192:195], v[212:215], v[16:31]
	v_mfma_f32_32x32x16_bf16 v[0:15], v[196:199], v[212:215], v[0:15]
	v_add3_u32 v241, v152, v240, s49
	v_add3_u32 v243, v152, v244, s50
	ds_read_b128 v[192:195], v243
	ds_read_b128 v[200:203], v241
	ds_read_b128 v[196:199], v243 offset:4096
	ds_read_b128 v[204:207], v241 offset:4096
	ds_read_b128 v[208:211], v241 offset:8192
	ds_read_b128 v[212:215], v241 offset:12288
	s_waitcnt lgkmcnt(6)
	v_mfma_f32_32x32x16_bf16 v[112:127], v[216:219], v[224:227], v[112:127]
	v_mfma_f32_32x32x16_bf16 v[96:111], v[220:223], v[224:227], v[96:111]
	v_mfma_f32_32x32x16_bf16 v[80:95], v[216:219], v[228:231], v[80:95]
	v_mfma_f32_32x32x16_bf16 v[64:79], v[220:223], v[228:231], v[64:79]
	v_mfma_f32_32x32x16_bf16 v[48:63], v[216:219], v[232:235], v[48:63]
	v_mfma_f32_32x32x16_bf16 v[32:47], v[220:223], v[232:235], v[32:47]
	v_mfma_f32_32x32x16_bf16 v[16:31], v[216:219], v[236:239], v[16:31]
	v_mfma_f32_32x32x16_bf16 v[0:15], v[220:223], v[236:239], v[0:15]
	v_add3_u32 v241, v153, v240, s49
	v_add3_u32 v243, v153, v244, s50
	ds_read_b128 v[216:219], v243
	ds_read_b128 v[224:227], v241
	ds_read_b128 v[220:223], v243 offset:4096
	ds_read_b128 v[228:231], v241 offset:4096
	ds_read_b128 v[232:235], v241 offset:8192
	ds_read_b128 v[236:239], v241 offset:12288
	s_waitcnt lgkmcnt(6)
	v_mfma_f32_32x32x16_bf16 v[112:127], v[192:195], v[200:203], v[112:127]
	v_mfma_f32_32x32x16_bf16 v[96:111], v[196:199], v[200:203], v[96:111]
	v_mfma_f32_32x32x16_bf16 v[80:95], v[192:195], v[204:207], v[80:95]
	v_mfma_f32_32x32x16_bf16 v[64:79], v[196:199], v[204:207], v[64:79]
	v_mfma_f32_32x32x16_bf16 v[48:63], v[192:195], v[208:211], v[48:63]
	v_mfma_f32_32x32x16_bf16 v[32:47], v[196:199], v[208:211], v[32:47]
	v_mfma_f32_32x32x16_bf16 v[16:31], v[192:195], v[212:215], v[16:31]
	v_mfma_f32_32x32x16_bf16 v[0:15], v[196:199], v[212:215], v[0:15]
	s_waitcnt lgkmcnt(0)
	v_mfma_f32_32x32x16_bf16 v[112:127], v[216:219], v[224:227], v[112:127]
	v_mfma_f32_32x32x16_bf16 v[96:111], v[220:223], v[224:227], v[96:111]
	v_mfma_f32_32x32x16_bf16 v[80:95], v[216:219], v[228:231], v[80:95]
	v_mfma_f32_32x32x16_bf16 v[64:79], v[220:223], v[228:231], v[64:79]
	s_add_u32 s28, s28, 0x80
	s_addc_u32 s29, s29, 0
	s_add_u32 s49, s49, 0x10000
	s_sub_u32 s53, s49, 0x28000
	s_cmp_ge_u32 s49, 0x28000
	s_cselect_b32 s49, s53, s49
	s_mov_b32 s50, s51
	s_waitcnt vmcnt(0)
	s_barrier
	v_add3_u32 v241, v147, v240, s49
	v_add3_u32 v243, v147, v244, s50
	ds_read_b128 v[192:195], v243
	ds_read_b128 v[200:203], v241
	ds_read_b128 v[196:199], v243 offset:4096
	ds_read_b128 v[204:207], v241 offset:4096
	ds_read_b128 v[208:211], v241 offset:8192
	ds_read_b128 v[212:215], v241 offset:12288
	v_mfma_f32_32x32x16_bf16 v[48:63], v[216:219], v[232:235], v[48:63]
	v_mfma_f32_32x32x16_bf16 v[32:47], v[220:223], v[232:235], v[32:47]
	v_mfma_f32_32x32x16_bf16 v[16:31], v[216:219], v[236:239], v[16:31]
	v_mfma_f32_32x32x16_bf16 v[0:15], v[220:223], v[236:239], v[0:15]
	v_add3_u32 v241, v151, v240, s49
	v_add3_u32 v243, v151, v244, s50
	ds_read_b128 v[216:219], v243
	ds_read_b128 v[224:227], v241
	ds_read_b128 v[220:223], v243 offset:4096
	ds_read_b128 v[228:231], v241 offset:4096
	ds_read_b128 v[232:235], v241 offset:8192
	ds_read_b128 v[236:239], v241 offset:12288
	s_waitcnt lgkmcnt(6)
	v_mfma_f32_32x32x16_bf16 v[112:127], v[192:195], v[200:203], v[112:127]
	v_mfma_f32_32x32x16_bf16 v[96:111], v[196:199], v[200:203], v[96:111]
	v_mfma_f32_32x32x16_bf16 v[80:95], v[192:195], v[204:207], v[80:95]
	v_mfma_f32_32x32x16_bf16 v[64:79], v[196:199], v[204:207], v[64:79]
	v_mfma_f32_32x32x16_bf16 v[48:63], v[192:195], v[208:211], v[48:63]
	v_mfma_f32_32x32x16_bf16 v[32:47], v[196:199], v[208:211], v[32:47]
	v_mfma_f32_32x32x16_bf16 v[16:31], v[192:195], v[212:215], v[16:31]
	v_mfma_f32_32x32x16_bf16 v[0:15], v[196:199], v[212:215], v[0:15]
	v_add3_u32 v241, v152, v240, s49
	v_add3_u32 v243, v152, v244, s50
	ds_read_b128 v[192:195], v243
	ds_read_b128 v[200:203], v241
	ds_read_b128 v[196:199], v243 offset:4096
	ds_read_b128 v[204:207], v241 offset:4096
	ds_read_b128 v[208:211], v241 offset:8192
	ds_read_b128 v[212:215], v241 offset:12288
	s_waitcnt lgkmcnt(6)
	v_mfma_f32_32x32x16_bf16 v[112:127], v[216:219], v[224:227], v[112:127]
	v_mfma_f32_32x32x16_bf16 v[96:111], v[220:223], v[224:227], v[96:111]
	v_mfma_f32_32x32x16_bf16 v[80:95], v[216:219], v[228:231], v[80:95]
	v_mfma_f32_32x32x16_bf16 v[64:79], v[220:223], v[228:231], v[64:79]
	v_mfma_f32_32x32x16_bf16 v[48:63], v[216:219], v[232:235], v[48:63]
	v_mfma_f32_32x32x16_bf16 v[32:47], v[220:223], v[232:235], v[32:47]
	v_mfma_f32_32x32x16_bf16 v[16:31], v[216:219], v[236:239], v[16:31]
	v_mfma_f32_32x32x16_bf16 v[0:15], v[220:223], v[236:239], v[0:15]
	v_add3_u32 v241, v153, v240, s49
	v_add3_u32 v243, v153, v244, s50
	ds_read_b128 v[216:219], v243
	ds_read_b128 v[224:227], v241
	ds_read_b128 v[220:223], v243 offset:4096
	ds_read_b128 v[228:231], v241 offset:4096
	ds_read_b128 v[232:235], v241 offset:8192
	ds_read_b128 v[236:239], v241 offset:12288
	s_waitcnt lgkmcnt(6)
	v_mfma_f32_32x32x16_bf16 v[112:127], v[192:195], v[200:203], v[112:127]
	v_mfma_f32_32x32x16_bf16 v[96:111], v[196:199], v[200:203], v[96:111]
	v_mfma_f32_32x32x16_bf16 v[80:95], v[192:195], v[204:207], v[80:95]
	v_mfma_f32_32x32x16_bf16 v[64:79], v[196:199], v[204:207], v[64:79]
	v_mfma_f32_32x32x16_bf16 v[48:63], v[192:195], v[208:211], v[48:63]
	v_mfma_f32_32x32x16_bf16 v[32:47], v[196:199], v[208:211], v[32:47]
	v_mfma_f32_32x32x16_bf16 v[16:31], v[192:195], v[212:215], v[16:31]
	v_mfma_f32_32x32x16_bf16 v[0:15], v[196:199], v[212:215], v[0:15]
	s_waitcnt vmcnt(0) lgkmcnt(0)
	s_barrier
	v_mfma_f32_32x32x16_bf16 v[112:127], v[216:219], v[224:227], v[112:127]
	v_mfma_f32_32x32x16_bf16 v[96:111], v[220:223], v[224:227], v[96:111]
	v_mfma_f32_32x32x16_bf16 v[80:95], v[216:219], v[228:231], v[80:95]
	v_mfma_f32_32x32x16_bf16 v[64:79], v[220:223], v[228:231], v[64:79]
	v_mfma_f32_32x32x16_bf16 v[48:63], v[216:219], v[232:235], v[48:63]
	v_mfma_f32_32x32x16_bf16 v[32:47], v[220:223], v[232:235], v[32:47]
	v_mfma_f32_32x32x16_bf16 v[16:31], v[216:219], v[236:239], v[16:31]
	v_mfma_f32_32x32x16_bf16 v[0:15], v[220:223], v[236:239], v[0:15]
	s_nop 15

.Lex_chunk:
	s_movk_i32 s36, 0
	s_mul_i32 s37, s36, s5
	s_add_i32 s37, s37, s6
	s_min_u32 s37, s37, 0x3fff
	s_lshl_b32 s37, s37, 9
	s_add_u32 s82, s12, s37
	s_addc_u32 s83, s13, 0
	v_lshlrev_b32_e32 v219, 2, v228
	global_load_dword v96, v219, s[82:83]
	global_load_dword v97, v219, s[82:83] offset:256
	s_movk_i32 s36, 1
	s_mul_i32 s37, s36, s5
	s_add_i32 s37, s37, s6
	s_min_u32 s37, s37, 0x3fff
	s_lshl_b32 s37, s37, 9
	s_add_u32 s82, s12, s37
	s_addc_u32 s83, s13, 0
	v_lshlrev_b32_e32 v219, 2, v228
	global_load_dword v98, v219, s[82:83]
	global_load_dword v99, v219, s[82:83] offset:256
	s_movk_i32 s36, 2
	s_mul_i32 s37, s36, s5
	s_add_i32 s37, s37, s6
	s_min_u32 s37, s37, 0x3fff
	s_lshl_b32 s37, s37, 9
	s_add_u32 s82, s12, s37
	s_addc_u32 s83, s13, 0
	v_lshlrev_b32_e32 v219, 2, v228
	global_load_dword v100, v219, s[82:83]
	global_load_dword v101, v219, s[82:83] offset:256
	s_movk_i32 s36, 3
	s_mul_i32 s37, s36, s5
	s_add_i32 s37, s37, s6
	s_min_u32 s37, s37, 0x3fff
	s_lshl_b32 s37, s37, 9
	s_add_u32 s82, s12, s37
	s_addc_u32 s83, s13, 0
	v_lshlrev_b32_e32 v219, 2, v228
	global_load_dword v102, v219, s[82:83]
	global_load_dword v103, v219, s[82:83] offset:256
	s_movk_i32 s36, 4
	s_mul_i32 s37, s36, s5
	s_add_i32 s37, s37, s6
	s_min_u32 s37, s37, 0x3fff
	s_lshl_b32 s37, s37, 9
	s_add_u32 s82, s12, s37
	s_addc_u32 s83, s13, 0
	v_lshlrev_b32_e32 v219, 2, v228
	global_load_dword v104, v219, s[82:83]
	global_load_dword v105, v219, s[82:83] offset:256
	s_movk_i32 s36, 5
	s_mul_i32 s37, s36, s5
	s_add_i32 s37, s37, s6
	s_min_u32 s37, s37, 0x3fff
	s_lshl_b32 s37, s37, 9
	s_add_u32 s82, s12, s37
	s_addc_u32 s83, s13, 0
	v_lshlrev_b32_e32 v219, 2, v228
	global_load_dword v106, v219, s[82:83]
	global_load_dword v107, v219, s[82:83] offset:256
	s_movk_i32 s36, 6
	s_mul_i32 s37, s36, s5
	s_add_i32 s37, s37, s6
	s_min_u32 s37, s37, 0x3fff
	s_lshl_b32 s37, s37, 9
	s_add_u32 s82, s12, s37
	s_addc_u32 s83, s13, 0
	v_lshlrev_b32_e32 v219, 2, v228
	global_load_dword v108, v219, s[82:83]
	global_load_dword v109, v219, s[82:83] offset:256
	s_movk_i32 s36, 7
	s_mul_i32 s37, s36, s5
	s_add_i32 s37, s37, s6
	s_min_u32 s37, s37, 0x3fff
	s_lshl_b32 s37, s37, 9
	s_add_u32 s82, s12, s37
	s_addc_u32 s83, s13, 0
	v_lshlrev_b32_e32 v219, 2, v228
	global_load_dword v110, v219, s[82:83]
	global_load_dword v111, v219, s[82:83] offset:256
	s_waitcnt vmcnt(0)
	ds_write_b32 v230, v96 offset:0
	ds_write_b32 v230, v97 offset:256
	ds_write_b32 v230, v98 offset:512
	ds_write_b32 v230, v99 offset:768
	ds_write_b32 v230, v100 offset:1024
	ds_write_b32 v230, v101 offset:1280
	ds_write_b32 v230, v102 offset:1536
	ds_write_b32 v230, v103 offset:1792
	ds_write_b32 v230, v104 offset:2048
	ds_write_b32 v230, v105 offset:2304
	ds_write_b32 v230, v106 offset:2560
	ds_write_b32 v230, v107 offset:2816
	ds_write_b32 v230, v108 offset:3072
	ds_write_b32 v230, v109 offset:3328
	ds_write_b32 v230, v110 offset:3584
	ds_write_b32 v230, v111 offset:3840
	s_waitcnt lgkmcnt(0)
	s_mov_b32 s8, 0
	s_mov_b32 s7, 0
	s_mov_b32 s54, 0
	s_mov_b32 s53, 0
	s_mul_i32 s55, s53, s5
	s_add_i32 s55, s55, s6
	s_min_u32 s55, s55, 0x3fff
	s_and_b32 s34, s54, 7
	s_mul_i32 s34, s34, 0x300000
	s_cmp_lt_u32 s54, 8
	s_cselect_b32 s30, s16, s18
	s_cselect_b32 s31, s17, s19
	s_add_u32 s30, s30, s34
	s_addc_u32 s31, s31, 0
	s_and_b32 s34, s54, 7
	s_lshl_b32 s34, s34, 6
	s_lshl_b32 s35, s55, 12
	s_add_u32 s34, s34, s35
	s_add_u32 s32, s10, s34
	s_addc_u32 s33, s11, 0
	s_lshl_b32 s34, s53, 9
	v_add_u32_e32 v216, s34, v223
	ds_read_b128 v[80:83], v216 offset:0
	ds_read_b128 v[84:87], v216 offset:16
	ds_read_b128 v[88:91], v216 offset:32
	ds_read_b128 v[92:95], v216 offset:48
	s_waitcnt lgkmcnt(0)
	global_load_dwordx2 v[64:65], v224, s[32:33] offset:0
	global_load_dwordx2 v[66:67], v224, s[32:33] offset:512
	global_load_dwordx2 v[68:69], v224, s[32:33] offset:1024
	global_load_dwordx2 v[70:71], v224, s[32:33] offset:1536
	global_load_dwordx2 v[72:73], v224, s[32:33] offset:2048
	global_load_dwordx2 v[74:75], v224, s[32:33] offset:2560
	global_load_dwordx2 v[76:77], v224, s[32:33] offset:3072
	global_load_dwordx2 v[78:79], v224, s[32:33] offset:3584
	v_mad_u32_u24 v217, v80, s52, v220
	v_add_u32_e32 v218, v217, v221
	global_load_dwordx4 v[96:99], v217, s[30:31]
	global_load_dwordx2 v[100:101], v218, s[30:31]
	v_mad_u32_u24 v217, v81, s52, v220
	v_add_u32_e32 v218, v217, v221
	global_load_dwordx4 v[102:105], v217, s[30:31]
	global_load_dwordx2 v[106:107], v218, s[30:31]
	v_mad_u32_u24 v217, v82, s52, v220
	v_add_u32_e32 v218, v217, v221
	global_load_dwordx4 v[108:111], v217, s[30:31]
	global_load_dwordx2 v[112:113], v218, s[30:31]
	v_mad_u32_u24 v217, v83, s52, v220
	v_add_u32_e32 v218, v217, v221
	global_load_dwordx4 v[114:117], v217, s[30:31]
	global_load_dwordx2 v[118:119], v218, s[30:31]
	v_mad_u32_u24 v217, v84, s52, v220
	v_add_u32_e32 v218, v217, v221
	global_load_dwordx4 v[120:123], v217, s[30:31]
	global_load_dwordx2 v[124:125], v218, s[30:31]
	v_mad_u32_u24 v217, v85, s52, v220
	v_add_u32_e32 v218, v217, v221
	global_load_dwordx4 v[126:129], v217, s[30:31]
	global_load_dwordx2 v[130:131], v218, s[30:31]
	v_mad_u32_u24 v217, v86, s52, v220
	v_add_u32_e32 v218, v217, v221
	global_load_dwordx4 v[132:135], v217, s[30:31]
	global_load_dwordx2 v[136:137], v218, s[30:31]
	v_mad_u32_u24 v217, v87, s52, v220
	v_add_u32_e32 v218, v217, v221
	global_load_dwordx4 v[138:141], v217, s[30:31]
	global_load_dwordx2 v[142:143], v218, s[30:31]
	v_mad_u32_u24 v217, v88, s52, v220
	v_add_u32_e32 v218, v217, v221
	global_load_dwordx4 v[144:147], v217, s[30:31]
	global_load_dwordx2 v[148:149], v218, s[30:31]
	v_mad_u32_u24 v217, v89, s52, v220
	v_add_u32_e32 v218, v217, v221
	global_load_dwordx4 v[150:153], v217, s[30:31]
	global_load_dwordx2 v[154:155], v218, s[30:31]
	v_mad_u32_u24 v217, v90, s52, v220
	v_add_u32_e32 v218, v217, v221
	global_load_dwordx4 v[156:159], v217, s[30:31]
	global_load_dwordx2 v[160:161], v218, s[30:31]
	v_mad_u32_u24 v217, v91, s52, v220
	v_add_u32_e32 v218, v217, v221
	global_load_dwordx4 v[162:165], v217, s[30:31]
	global_load_dwordx2 v[166:167], v218, s[30:31]
	v_mad_u32_u24 v217, v92, s52, v220
	v_add_u32_e32 v218, v217, v221
	global_load_dwordx4 v[168:171], v217, s[30:31]
	global_load_dwordx2 v[172:173], v218, s[30:31]
	v_mad_u32_u24 v217, v93, s52, v220
	v_add_u32_e32 v218, v217, v221
	global_load_dwordx4 v[174:177], v217, s[30:31]
	global_load_dwordx2 v[178:179], v218, s[30:31]
	v_mad_u32_u24 v217, v94, s52, v220
	v_add_u32_e32 v218, v217, v221
	global_load_dwordx4 v[180:183], v217, s[30:31]
	global_load_dwordx2 v[184:185], v218, s[30:31]
	v_mad_u32_u24 v217, v95, s52, v220
	v_add_u32_e32 v218, v217, v221
	global_load_dwordx4 v[186:189], v217, s[30:31]
	global_load_dwordx2 v[190:191], v218, s[30:31]
	s_add_i32 s53, s7, 1
	s_mov_b32 s54, s8
	s_cmp_eq_u32 s53, 8
	s_cselect_b32 s53, 0, s53
	s_cselect_b32 s34, 1, 0
	s_add_i32 s54, s54, s34
	s_mul_i32 s55, s53, s5
	s_add_i32 s55, s55, s6
	s_min_u32 s55, s55, 0x3fff
	s_and_b32 s34, s54, 7
	s_mul_i32 s34, s34, 0x300000
	s_cmp_lt_u32 s54, 8
	s_cselect_b32 s30, s16, s18
	s_cselect_b32 s31, s17, s19
	s_add_u32 s30, s30, s34
	s_addc_u32 s31, s31, 0
	s_and_b32 s34, s54, 7
	s_lshl_b32 s34, s34, 6
	s_lshl_b32 s35, s55, 12
	s_add_u32 s34, s34, s35
	s_add_u32 s32, s10, s34
	s_addc_u32 s33, s11, 0
	s_lshl_b32 s34, s53, 9
	v_add_u32_e32 v216, s34, v223
	ds_read_b128 v[80:83], v216 offset:0
	ds_read_b128 v[84:87], v216 offset:16
	ds_read_b128 v[88:91], v216 offset:32
	ds_read_b128 v[92:95], v216 offset:48
.Lex_uloop:
	s_waitcnt vmcnt(32)
	v_lshlrev_b32_e32 v32, 16, v64
	v_and_b32_e32 v33, 0xffff0000, v64
	v_lshlrev_b32_e32 v34, 16, v65
	v_and_b32_e32 v35, 0xffff0000, v65
	v_lshlrev_b32_e32 v36, 16, v66
	v_and_b32_e32 v37, 0xffff0000, v66
	v_lshlrev_b32_e32 v38, 16, v67
	v_and_b32_e32 v39, 0xffff0000, v67
	v_lshlrev_b32_e32 v40, 16, v68
	v_and_b32_e32 v41, 0xffff0000, v68
	v_lshlrev_b32_e32 v42, 16, v69
	v_and_b32_e32 v43, 0xffff0000, v69
	v_lshlrev_b32_e32 v44, 16, v70
	v_and_b32_e32 v45, 0xffff0000, v70
	v_lshlrev_b32_e32 v46, 16, v71
	v_and_b32_e32 v47, 0xffff0000, v71
	v_lshlrev_b32_e32 v48, 16, v72
	v_and_b32_e32 v49, 0xffff0000, v72
	v_lshlrev_b32_e32 v50, 16, v73
	v_and_b32_e32 v51, 0xffff0000, v73
	v_lshlrev_b32_e32 v52, 16, v74
	v_and_b32_e32 v53, 0xffff0000, v74
	v_lshlrev_b32_e32 v54, 16, v75
	v_and_b32_e32 v55, 0xffff0000, v75
	v_lshlrev_b32_e32 v56, 16, v76
	v_and_b32_e32 v57, 0xffff0000, v76
	v_lshlrev_b32_e32 v58, 16, v77
	v_and_b32_e32 v59, 0xffff0000, v77
	v_lshlrev_b32_e32 v60, 16, v78
	v_and_b32_e32 v61, 0xffff0000, v78
	v_lshlrev_b32_e32 v62, 16, v79
	v_and_b32_e32 v63, 0xffff0000, v79
	s_waitcnt lgkmcnt(0)
	s_waitcnt vmcnt(30)
	v_cvt_scalef32_pk32_f32_fp6 v[0:31], v[96:101], 1.0
	v_pk_mul_f32 v[208:209], v[0:1], v[32:33]
	v_pk_mul_f32 v[210:211], v[2:3], v[34:35]
	v_pk_fma_f32 v[208:209], v[4:5], v[36:37], v[208:209]
	v_pk_fma_f32 v[210:211], v[6:7], v[38:39], v[210:211]
	v_pk_fma_f32 v[208:209], v[8:9], v[40:41], v[208:209]
	v_pk_fma_f32 v[210:211], v[10:11], v[42:43], v[210:211]
	v_pk_fma_f32 v[208:209], v[12:13], v[44:45], v[208:209]
	v_pk_fma_f32 v[210:211], v[14:15], v[46:47], v[210:211]
	v_pk_fma_f32 v[208:209], v[16:17], v[48:49], v[208:209]
	v_pk_fma_f32 v[210:211], v[18:19], v[50:51], v[210:211]
	v_pk_fma_f32 v[208:209], v[20:21], v[52:53], v[208:209]
	v_pk_fma_f32 v[210:211], v[22:23], v[54:55], v[210:211]
	v_pk_fma_f32 v[208:209], v[24:25], v[56:57], v[208:209]
	v_pk_fma_f32 v[210:211], v[26:27], v[58:59], v[210:211]
	v_pk_fma_f32 v[208:209], v[28:29], v[60:61], v[208:209]
	v_pk_fma_f32 v[210:211], v[30:31], v[62:63], v[210:211]
	v_pk_add_f32 v[208:209], v[208:209], v[210:211]
	v_add_f32_e32 v192, v208, v209
	global_load_dwordx2 v[64:65], v224, s[32:33] offset:0
	global_load_dwordx2 v[66:67], v224, s[32:33] offset:512
	global_load_dwordx2 v[68:69], v224, s[32:33] offset:1024
	global_load_dwordx2 v[70:71], v224, s[32:33] offset:1536
	global_load_dwordx2 v[72:73], v224, s[32:33] offset:2048
	global_load_dwordx2 v[74:75], v224, s[32:33] offset:2560
	global_load_dwordx2 v[76:77], v224, s[32:33] offset:3072
	global_load_dwordx2 v[78:79], v224, s[32:33] offset:3584
	v_mad_u32_u24 v217, v80, s52, v220
	v_add_u32_e32 v218, v217, v221
	global_load_dwordx4 v[96:99], v217, s[30:31]
	global_load_dwordx2 v[100:101], v218, s[30:31]
	s_waitcnt vmcnt(38)
	v_cvt_scalef32_pk32_f32_fp6 v[0:31], v[102:107], 1.0
	v_pk_mul_f32 v[208:209], v[0:1], v[32:33]
	v_pk_mul_f32 v[210:211], v[2:3], v[34:35]
	v_pk_fma_f32 v[208:209], v[4:5], v[36:37], v[208:209]
	v_pk_fma_f32 v[210:211], v[6:7], v[38:39], v[210:211]
	v_pk_fma_f32 v[208:209], v[8:9], v[40:41], v[208:209]
	v_pk_fma_f32 v[210:211], v[10:11], v[42:43], v[210:211]
	v_pk_fma_f32 v[208:209], v[12:13], v[44:45], v[208:209]
	v_pk_fma_f32 v[210:211], v[14:15], v[46:47], v[210:211]
	v_pk_fma_f32 v[208:209], v[16:17], v[48:49], v[208:209]
	v_pk_fma_f32 v[210:211], v[18:19], v[50:51], v[210:211]
	v_pk_fma_f32 v[208:209], v[20:21], v[52:53], v[208:209]
	v_pk_fma_f32 v[210:211], v[22:23], v[54:55], v[210:211]
	v_pk_fma_f32 v[208:209], v[24:25], v[56:57], v[208:209]
	v_pk_fma_f32 v[210:211], v[26:27], v[58:59], v[210:211]
	v_pk_fma_f32 v[208:209], v[28:29], v[60:61], v[208:209]
	v_pk_fma_f32 v[210:211], v[30:31], v[62:63], v[210:211]
	v_pk_add_f32 v[208:209], v[208:209], v[210:211]
	v_add_f32_e32 v193, v208, v209
	v_mad_u32_u24 v217, v81, s52, v220
	v_add_u32_e32 v218, v217, v221
	global_load_dwordx4 v[102:105], v217, s[30:31]
	global_load_dwordx2 v[106:107], v218, s[30:31]
	s_waitcnt vmcnt(38)
	v_cvt_scalef32_pk32_f32_fp6 v[0:31], v[108:113], 1.0
	v_pk_mul_f32 v[208:209], v[0:1], v[32:33]
	v_pk_mul_f32 v[210:211], v[2:3], v[34:35]
	v_pk_fma_f32 v[208:209], v[4:5], v[36:37], v[208:209]
	v_pk_fma_f32 v[210:211], v[6:7], v[38:39], v[210:211]
	v_pk_fma_f32 v[208:209], v[8:9], v[40:41], v[208:209]
	v_pk_fma_f32 v[210:211], v[10:11], v[42:43], v[210:211]
	v_pk_fma_f32 v[208:209], v[12:13], v[44:45], v[208:209]
	v_pk_fma_f32 v[210:211], v[14:15], v[46:47], v[210:211]
	v_pk_fma_f32 v[208:209], v[16:17], v[48:49], v[208:209]
	v_pk_fma_f32 v[210:211], v[18:19], v[50:51], v[210:211]
	v_pk_fma_f32 v[208:209], v[20:21], v[52:53], v[208:209]
	v_pk_fma_f32 v[210:211], v[22:23], v[54:55], v[210:211]
	v_pk_fma_f32 v[208:209], v[24:25], v[56:57], v[208:209]
	v_pk_fma_f32 v[210:211], v[26:27], v[58:59], v[210:211]
	v_pk_fma_f32 v[208:209], v[28:29], v[60:61], v[208:209]
	v_pk_fma_f32 v[210:211], v[30:31], v[62:63], v[210:211]
	v_pk_add_f32 v[208:209], v[208:209], v[210:211]
	v_add_f32_e32 v194, v208, v209
	v_mad_u32_u24 v217, v82, s52, v220
	v_add_u32_e32 v218, v217, v221
	global_load_dwordx4 v[108:111], v217, s[30:31]
	global_load_dwordx2 v[112:113], v218, s[30:31]
	s_waitcnt vmcnt(38)
	v_cvt_scalef32_pk32_f32_fp6 v[0:31], v[114:119], 1.0
	v_pk_mul_f32 v[208:209], v[0:1], v[32:33]
	v_pk_mul_f32 v[210:211], v[2:3], v[34:35]
	v_pk_fma_f32 v[208:209], v[4:5], v[36:37], v[208:209]
	v_pk_fma_f32 v[210:211], v[6:7], v[38:39], v[210:211]
	v_pk_fma_f32 v[208:209], v[8:9], v[40:41], v[208:209]
	v_pk_fma_f32 v[210:211], v[10:11], v[42:43], v[210:211]
	v_pk_fma_f32 v[208:209], v[12:13], v[44:45], v[208:209]
	v_pk_fma_f32 v[210:211], v[14:15], v[46:47], v[210:211]
	v_pk_fma_f32 v[208:209], v[16:17], v[48:49], v[208:209]
	v_pk_fma_f32 v[210:211], v[18:19], v[50:51], v[210:211]
	v_pk_fma_f32 v[208:209], v[20:21], v[52:53], v[208:209]
	v_pk_fma_f32 v[210:211], v[22:23], v[54:55], v[210:211]
	v_pk_fma_f32 v[208:209], v[24:25], v[56:57], v[208:209]
	v_pk_fma_f32 v[210:211], v[26:27], v[58:59], v[210:211]
	v_pk_fma_f32 v[208:209], v[28:29], v[60:61], v[208:209]
	v_pk_fma_f32 v[210:211], v[30:31], v[62:63], v[210:211]
	v_pk_add_f32 v[208:209], v[208:209], v[210:211]
	v_add_f32_e32 v195, v208, v209
	v_mad_u32_u24 v217, v83, s52, v220
	v_add_u32_e32 v218, v217, v221
	global_load_dwordx4 v[114:117], v217, s[30:31]
	global_load_dwordx2 v[118:119], v218, s[30:31]
	s_waitcnt vmcnt(38)
	v_cvt_scalef32_pk32_f32_fp6 v[0:31], v[120:125], 1.0
	v_pk_mul_f32 v[208:209], v[0:1], v[32:33]
	v_pk_mul_f32 v[210:211], v[2:3], v[34:35]
	v_pk_fma_f32 v[208:209], v[4:5], v[36:37], v[208:209]
	v_pk_fma_f32 v[210:211], v[6:7], v[38:39], v[210:211]
	v_pk_fma_f32 v[208:209], v[8:9], v[40:41], v[208:209]
	v_pk_fma_f32 v[210:211], v[10:11], v[42:43], v[210:211]
	v_pk_fma_f32 v[208:209], v[12:13], v[44:45], v[208:209]
	v_pk_fma_f32 v[210:211], v[14:15], v[46:47], v[210:211]
	v_pk_fma_f32 v[208:209], v[16:17], v[48:49], v[208:209]
	v_pk_fma_f32 v[210:211], v[18:19], v[50:51], v[210:211]
	v_pk_fma_f32 v[208:209], v[20:21], v[52:53], v[208:209]
	v_pk_fma_f32 v[210:211], v[22:23], v[54:55], v[210:211]
	v_pk_fma_f32 v[208:209], v[24:25], v[56:57], v[208:209]
	v_pk_fma_f32 v[210:211], v[26:27], v[58:59], v[210:211]
	v_pk_fma_f32 v[208:209], v[28:29], v[60:61], v[208:209]
	v_pk_fma_f32 v[210:211], v[30:31], v[62:63], v[210:211]
	v_pk_add_f32 v[208:209], v[208:209], v[210:211]
	v_add_f32_e32 v196, v208, v209
	v_mad_u32_u24 v217, v84, s52, v220
	v_add_u32_e32 v218, v217, v221
	global_load_dwordx4 v[120:123], v217, s[30:31]
	global_load_dwordx2 v[124:125], v218, s[30:31]
	s_waitcnt vmcnt(38)
	v_cvt_scalef32_pk32_f32_fp6 v[0:31], v[126:131], 1.0
	v_pk_mul_f32 v[208:209], v[0:1], v[32:33]
	v_pk_mul_f32 v[210:211], v[2:3], v[34:35]
	v_pk_fma_f32 v[208:209], v[4:5], v[36:37], v[208:209]
	v_pk_fma_f32 v[210:211], v[6:7], v[38:39], v[210:211]
	v_pk_fma_f32 v[208:209], v[8:9], v[40:41], v[208:209]
	v_pk_fma_f32 v[210:211], v[10:11], v[42:43], v[210:211]
	v_pk_fma_f32 v[208:209], v[12:13], v[44:45], v[208:209]
	v_pk_fma_f32 v[210:211], v[14:15], v[46:47], v[210:211]
	v_pk_fma_f32 v[208:209], v[16:17], v[48:49], v[208:209]
	v_pk_fma_f32 v[210:211], v[18:19], v[50:51], v[210:211]
	v_pk_fma_f32 v[208:209], v[20:21], v[52:53], v[208:209]
	v_pk_fma_f32 v[210:211], v[22:23], v[54:55], v[210:211]
	v_pk_fma_f32 v[208:209], v[24:25], v[56:57], v[208:209]
	v_pk_fma_f32 v[210:211], v[26:27], v[58:59], v[210:211]
	v_pk_fma_f32 v[208:209], v[28:29], v[60:61], v[208:209]
	v_pk_fma_f32 v[210:211], v[30:31], v[62:63], v[210:211]
	v_pk_add_f32 v[208:209], v[208:209], v[210:211]
	v_add_f32_e32 v197, v208, v209
	v_mad_u32_u24 v217, v85, s52, v220
	v_add_u32_e32 v218, v217, v221
	global_load_dwordx4 v[126:129], v217, s[30:31]
	global_load_dwordx2 v[130:131], v218, s[30:31]
	s_waitcnt vmcnt(38)
	v_cvt_scalef32_pk32_f32_fp6 v[0:31], v[132:137], 1.0
	v_pk_mul_f32 v[208:209], v[0:1], v[32:33]
	v_pk_mul_f32 v[210:211], v[2:3], v[34:35]
	v_pk_fma_f32 v[208:209], v[4:5], v[36:37], v[208:209]
	v_pk_fma_f32 v[210:211], v[6:7], v[38:39], v[210:211]
	v_pk_fma_f32 v[208:209], v[8:9], v[40:41], v[208:209]
	v_pk_fma_f32 v[210:211], v[10:11], v[42:43], v[210:211]
	v_pk_fma_f32 v[208:209], v[12:13], v[44:45], v[208:209]
	v_pk_fma_f32 v[210:211], v[14:15], v[46:47], v[210:211]
	v_pk_fma_f32 v[208:209], v[16:17], v[48:49], v[208:209]
	v_pk_fma_f32 v[210:211], v[18:19], v[50:51], v[210:211]
	v_pk_fma_f32 v[208:209], v[20:21], v[52:53], v[208:209]
	v_pk_fma_f32 v[210:211], v[22:23], v[54:55], v[210:211]
	v_pk_fma_f32 v[208:209], v[24:25], v[56:57], v[208:209]
	v_pk_fma_f32 v[210:211], v[26:27], v[58:59], v[210:211]
	v_pk_fma_f32 v[208:209], v[28:29], v[60:61], v[208:209]
	v_pk_fma_f32 v[210:211], v[30:31], v[62:63], v[210:211]
	v_pk_add_f32 v[208:209], v[208:209], v[210:211]
	v_add_f32_e32 v198, v208, v209
	v_mad_u32_u24 v217, v86, s52, v220
	v_add_u32_e32 v218, v217, v221
	global_load_dwordx4 v[132:135], v217, s[30:31]
	global_load_dwordx2 v[136:137], v218, s[30:31]
	s_waitcnt vmcnt(38)
	v_cvt_scalef32_pk32_f32_fp6 v[0:31], v[138:143], 1.0
	v_pk_mul_f32 v[208:209], v[0:1], v[32:33]
	v_pk_mul_f32 v[210:211], v[2:3], v[34:35]
	v_pk_fma_f32 v[208:209], v[4:5], v[36:37], v[208:209]
	v_pk_fma_f32 v[210:211], v[6:7], v[38:39], v[210:211]
	v_pk_fma_f32 v[208:209], v[8:9], v[40:41], v[208:209]
	v_pk_fma_f32 v[210:211], v[10:11], v[42:43], v[210:211]
	v_pk_fma_f32 v[208:209], v[12:13], v[44:45], v[208:209]
	v_pk_fma_f32 v[210:211], v[14:15], v[46:47], v[210:211]
	v_pk_fma_f32 v[208:209], v[16:17], v[48:49], v[208:209]
	v_pk_fma_f32 v[210:211], v[18:19], v[50:51], v[210:211]
	v_pk_fma_f32 v[208:209], v[20:21], v[52:53], v[208:209]
	v_pk_fma_f32 v[210:211], v[22:23], v[54:55], v[210:211]
	v_pk_fma_f32 v[208:209], v[24:25], v[56:57], v[208:209]
	v_pk_fma_f32 v[210:211], v[26:27], v[58:59], v[210:211]
	v_pk_fma_f32 v[208:209], v[28:29], v[60:61], v[208:209]
	v_pk_fma_f32 v[210:211], v[30:31], v[62:63], v[210:211]
	v_pk_add_f32 v[208:209], v[208:209], v[210:211]
	v_add_f32_e32 v199, v208, v209
	v_mad_u32_u24 v217, v87, s52, v220
	v_add_u32_e32 v218, v217, v221
	global_load_dwordx4 v[138:141], v217, s[30:31]
	global_load_dwordx2 v[142:143], v218, s[30:31]
	s_waitcnt vmcnt(38)
	v_cvt_scalef32_pk32_f32_fp6 v[0:31], v[144:149], 1.0
	v_pk_mul_f32 v[208:209], v[0:1], v[32:33]
	v_pk_mul_f32 v[210:211], v[2:3], v[34:35]
	v_pk_fma_f32 v[208:209], v[4:5], v[36:37], v[208:209]
	v_pk_fma_f32 v[210:211], v[6:7], v[38:39], v[210:211]
	v_pk_fma_f32 v[208:209], v[8:9], v[40:41], v[208:209]
	v_pk_fma_f32 v[210:211], v[10:11], v[42:43], v[210:211]
	v_pk_fma_f32 v[208:209], v[12:13], v[44:45], v[208:209]
	v_pk_fma_f32 v[210:211], v[14:15], v[46:47], v[210:211]
	v_pk_fma_f32 v[208:209], v[16:17], v[48:49], v[208:209]
	v_pk_fma_f32 v[210:211], v[18:19], v[50:51], v[210:211]
	v_pk_fma_f32 v[208:209], v[20:21], v[52:53], v[208:209]
	v_pk_fma_f32 v[210:211], v[22:23], v[54:55], v[210:211]
	v_pk_fma_f32 v[208:209], v[24:25], v[56:57], v[208:209]
	v_pk_fma_f32 v[210:211], v[26:27], v[58:59], v[210:211]
	v_pk_fma_f32 v[208:209], v[28:29], v[60:61], v[208:209]
	v_pk_fma_f32 v[210:211], v[30:31], v[62:63], v[210:211]
	v_pk_add_f32 v[208:209], v[208:209], v[210:211]
	v_add_f32_e32 v200, v208, v209
	v_mad_u32_u24 v217, v88, s52, v220
	v_add_u32_e32 v218, v217, v221
	global_load_dwordx4 v[144:147], v217, s[30:31]
	global_load_dwordx2 v[148:149], v218, s[30:31]
	s_waitcnt vmcnt(38)
	v_cvt_scalef32_pk32_f32_fp6 v[0:31], v[150:155], 1.0
	v_pk_mul_f32 v[208:209], v[0:1], v[32:33]
	v_pk_mul_f32 v[210:211], v[2:3], v[34:35]
	v_pk_fma_f32 v[208:209], v[4:5], v[36:37], v[208:209]
	v_pk_fma_f32 v[210:211], v[6:7], v[38:39], v[210:211]
	v_pk_fma_f32 v[208:209], v[8:9], v[40:41], v[208:209]
	v_pk_fma_f32 v[210:211], v[10:11], v[42:43], v[210:211]
	v_pk_fma_f32 v[208:209], v[12:13], v[44:45], v[208:209]
	v_pk_fma_f32 v[210:211], v[14:15], v[46:47], v[210:211]
	v_pk_fma_f32 v[208:209], v[16:17], v[48:49], v[208:209]
	v_pk_fma_f32 v[210:211], v[18:19], v[50:51], v[210:211]
	v_pk_fma_f32 v[208:209], v[20:21], v[52:53], v[208:209]
	v_pk_fma_f32 v[210:211], v[22:23], v[54:55], v[210:211]
	v_pk_fma_f32 v[208:209], v[24:25], v[56:57], v[208:209]
	v_pk_fma_f32 v[210:211], v[26:27], v[58:59], v[210:211]
	v_pk_fma_f32 v[208:209], v[28:29], v[60:61], v[208:209]
	v_pk_fma_f32 v[210:211], v[30:31], v[62:63], v[210:211]
	v_pk_add_f32 v[208:209], v[208:209], v[210:211]
	v_add_f32_e32 v201, v208, v209
	v_mad_u32_u24 v217, v89, s52, v220
	v_add_u32_e32 v218, v217, v221
	global_load_dwordx4 v[150:153], v217, s[30:31]
	global_load_dwordx2 v[154:155], v218, s[30:31]
	s_waitcnt vmcnt(38)
	v_cvt_scalef32_pk32_f32_fp6 v[0:31], v[156:161], 1.0
	v_pk_mul_f32 v[208:209], v[0:1], v[32:33]
	v_pk_mul_f32 v[210:211], v[2:3], v[34:35]
	v_pk_fma_f32 v[208:209], v[4:5], v[36:37], v[208:209]
	v_pk_fma_f32 v[210:211], v[6:7], v[38:39], v[210:211]
	v_pk_fma_f32 v[208:209], v[8:9], v[40:41], v[208:209]
	v_pk_fma_f32 v[210:211], v[10:11], v[42:43], v[210:211]
	v_pk_fma_f32 v[208:209], v[12:13], v[44:45], v[208:209]
	v_pk_fma_f32 v[210:211], v[14:15], v[46:47], v[210:211]
	v_pk_fma_f32 v[208:209], v[16:17], v[48:49], v[208:209]
	v_pk_fma_f32 v[210:211], v[18:19], v[50:51], v[210:211]
	v_pk_fma_f32 v[208:209], v[20:21], v[52:53], v[208:209]
	v_pk_fma_f32 v[210:211], v[22:23], v[54:55], v[210:211]
	v_pk_fma_f32 v[208:209], v[24:25], v[56:57], v[208:209]
	v_pk_fma_f32 v[210:211], v[26:27], v[58:59], v[210:211]
	v_pk_fma_f32 v[208:209], v[28:29], v[60:61], v[208:209]
	v_pk_fma_f32 v[210:211], v[30:31], v[62:63], v[210:211]
	v_pk_add_f32 v[208:209], v[208:209], v[210:211]
	v_add_f32_e32 v202, v208, v209
	v_mad_u32_u24 v217, v90, s52, v220
	v_add_u32_e32 v218, v217, v221
	global_load_dwordx4 v[156:159], v217, s[30:31]
	global_load_dwordx2 v[160:161], v218, s[30:31]
	s_waitcnt vmcnt(38)
	v_cvt_scalef32_pk32_f32_fp6 v[0:31], v[162:167], 1.0
	v_pk_mul_f32 v[208:209], v[0:1], v[32:33]
	v_pk_mul_f32 v[210:211], v[2:3], v[34:35]
	v_pk_fma_f32 v[208:209], v[4:5], v[36:37], v[208:209]
	v_pk_fma_f32 v[210:211], v[6:7], v[38:39], v[210:211]
	v_pk_fma_f32 v[208:209], v[8:9], v[40:41], v[208:209]
	v_pk_fma_f32 v[210:211], v[10:11], v[42:43], v[210:211]
	v_pk_fma_f32 v[208:209], v[12:13], v[44:45], v[208:209]
	v_pk_fma_f32 v[210:211], v[14:15], v[46:47], v[210:211]
	v_pk_fma_f32 v[208:209], v[16:17], v[48:49], v[208:209]
	v_pk_fma_f32 v[210:211], v[18:19], v[50:51], v[210:211]
	v_pk_fma_f32 v[208:209], v[20:21], v[52:53], v[208:209]
	v_pk_fma_f32 v[210:211], v[22:23], v[54:55], v[210:211]
	v_pk_fma_f32 v[208:209], v[24:25], v[56:57], v[208:209]
	v_pk_fma_f32 v[210:211], v[26:27], v[58:59], v[210:211]
	v_pk_fma_f32 v[208:209], v[28:29], v[60:61], v[208:209]
	v_pk_fma_f32 v[210:211], v[30:31], v[62:63], v[210:211]
	v_pk_add_f32 v[208:209], v[208:209], v[210:211]
	v_add_f32_e32 v203, v208, v209
	v_mad_u32_u24 v217, v91, s52, v220
	v_add_u32_e32 v218, v217, v221
	global_load_dwordx4 v[162:165], v217, s[30:31]
	global_load_dwordx2 v[166:167], v218, s[30:31]
	s_waitcnt vmcnt(38)
	v_cvt_scalef32_pk32_f32_fp6 v[0:31], v[168:173], 1.0
	v_pk_mul_f32 v[208:209], v[0:1], v[32:33]
	v_pk_mul_f32 v[210:211], v[2:3], v[34:35]
	v_pk_fma_f32 v[208:209], v[4:5], v[36:37], v[208:209]
	v_pk_fma_f32 v[210:211], v[6:7], v[38:39], v[210:211]
	v_pk_fma_f32 v[208:209], v[8:9], v[40:41], v[208:209]
	v_pk_fma_f32 v[210:211], v[10:11], v[42:43], v[210:211]
	v_pk_fma_f32 v[208:209], v[12:13], v[44:45], v[208:209]
	v_pk_fma_f32 v[210:211], v[14:15], v[46:47], v[210:211]
	v_pk_fma_f32 v[208:209], v[16:17], v[48:49], v[208:209]
	v_pk_fma_f32 v[210:211], v[18:19], v[50:51], v[210:211]
	v_pk_fma_f32 v[208:209], v[20:21], v[52:53], v[208:209]
	v_pk_fma_f32 v[210:211], v[22:23], v[54:55], v[210:211]
	v_pk_fma_f32 v[208:209], v[24:25], v[56:57], v[208:209]
	v_pk_fma_f32 v[210:211], v[26:27], v[58:59], v[210:211]
	v_pk_fma_f32 v[208:209], v[28:29], v[60:61], v[208:209]
	v_pk_fma_f32 v[210:211], v[30:31], v[62:63], v[210:211]
	v_pk_add_f32 v[208:209], v[208:209], v[210:211]
	v_add_f32_e32 v204, v208, v209
	v_mad_u32_u24 v217, v92, s52, v220
	v_add_u32_e32 v218, v217, v221
	global_load_dwordx4 v[168:171], v217, s[30:31]
	global_load_dwordx2 v[172:173], v218, s[30:31]
	s_waitcnt vmcnt(38)
	v_cvt_scalef32_pk32_f32_fp6 v[0:31], v[174:179], 1.0
	v_pk_mul_f32 v[208:209], v[0:1], v[32:33]
	v_pk_mul_f32 v[210:211], v[2:3], v[34:35]
	v_pk_fma_f32 v[208:209], v[4:5], v[36:37], v[208:209]
	v_pk_fma_f32 v[210:211], v[6:7], v[38:39], v[210:211]
	v_pk_fma_f32 v[208:209], v[8:9], v[40:41], v[208:209]
	v_pk_fma_f32 v[210:211], v[10:11], v[42:43], v[210:211]
	v_pk_fma_f32 v[208:209], v[12:13], v[44:45], v[208:209]
	v_pk_fma_f32 v[210:211], v[14:15], v[46:47], v[210:211]
	v_pk_fma_f32 v[208:209], v[16:17], v[48:49], v[208:209]
	v_pk_fma_f32 v[210:211], v[18:19], v[50:51], v[210:211]
	v_pk_fma_f32 v[208:209], v[20:21], v[52:53], v[208:209]
	v_pk_fma_f32 v[210:211], v[22:23], v[54:55], v[210:211]
	v_pk_fma_f32 v[208:209], v[24:25], v[56:57], v[208:209]
	v_pk_fma_f32 v[210:211], v[26:27], v[58:59], v[210:211]
	v_pk_fma_f32 v[208:209], v[28:29], v[60:61], v[208:209]
	v_pk_fma_f32 v[210:211], v[30:31], v[62:63], v[210:211]
	v_pk_add_f32 v[208:209], v[208:209], v[210:211]
	v_add_f32_e32 v205, v208, v209
	v_mad_u32_u24 v217, v93, s52, v220
	v_add_u32_e32 v218, v217, v221
	global_load_dwordx4 v[174:177], v217, s[30:31]
	global_load_dwordx2 v[178:179], v218, s[30:31]
	s_waitcnt vmcnt(38)
	v_cvt_scalef32_pk32_f32_fp6 v[0:31], v[180:185], 1.0
	v_pk_mul_f32 v[208:209], v[0:1], v[32:33]
	v_pk_mul_f32 v[210:211], v[2:3], v[34:35]
	v_pk_fma_f32 v[208:209], v[4:5], v[36:37], v[208:209]
	v_pk_fma_f32 v[210:211], v[6:7], v[38:39], v[210:211]
	v_pk_fma_f32 v[208:209], v[8:9], v[40:41], v[208:209]
	v_pk_fma_f32 v[210:211], v[10:11], v[42:43], v[210:211]
	v_pk_fma_f32 v[208:209], v[12:13], v[44:45], v[208:209]
	v_pk_fma_f32 v[210:211], v[14:15], v[46:47], v[210:211]
	v_pk_fma_f32 v[208:209], v[16:17], v[48:49], v[208:209]
	v_pk_fma_f32 v[210:211], v[18:19], v[50:51], v[210:211]
	v_pk_fma_f32 v[208:209], v[20:21], v[52:53], v[208:209]
	v_pk_fma_f32 v[210:211], v[22:23], v[54:55], v[210:211]
	v_pk_fma_f32 v[208:209], v[24:25], v[56:57], v[208:209]
	v_pk_fma_f32 v[210:211], v[26:27], v[58:59], v[210:211]
	v_pk_fma_f32 v[208:209], v[28:29], v[60:61], v[208:209]
	v_pk_fma_f32 v[210:211], v[30:31], v[62:63], v[210:211]
	v_pk_add_f32 v[208:209], v[208:209], v[210:211]
	v_add_f32_e32 v206, v208, v209
	v_mad_u32_u24 v217, v94, s52, v220
	v_add_u32_e32 v218, v217, v221
	global_load_dwordx4 v[180:183], v217, s[30:31]
	global_load_dwordx2 v[184:185], v218, s[30:31]
	s_waitcnt vmcnt(38)
	v_cvt_scalef32_pk32_f32_fp6 v[0:31], v[186:191], 1.0
	v_pk_mul_f32 v[208:209], v[0:1], v[32:33]
	v_pk_mul_f32 v[210:211], v[2:3], v[34:35]
	v_pk_fma_f32 v[208:209], v[4:5], v[36:37], v[208:209]
	v_pk_fma_f32 v[210:211], v[6:7], v[38:39], v[210:211]
	v_pk_fma_f32 v[208:209], v[8:9], v[40:41], v[208:209]
	v_pk_fma_f32 v[210:211], v[10:11], v[42:43], v[210:211]
	v_pk_fma_f32 v[208:209], v[12:13], v[44:45], v[208:209]
	v_pk_fma_f32 v[210:211], v[14:15], v[46:47], v[210:211]
	v_pk_fma_f32 v[208:209], v[16:17], v[48:49], v[208:209]
	v_pk_fma_f32 v[210:211], v[18:19], v[50:51], v[210:211]
	v_pk_fma_f32 v[208:209], v[20:21], v[52:53], v[208:209]
	v_pk_fma_f32 v[210:211], v[22:23], v[54:55], v[210:211]
	v_pk_fma_f32 v[208:209], v[24:25], v[56:57], v[208:209]
	v_pk_fma_f32 v[210:211], v[26:27], v[58:59], v[210:211]
	v_pk_fma_f32 v[208:209], v[28:29], v[60:61], v[208:209]
	v_pk_fma_f32 v[210:211], v[30:31], v[62:63], v[210:211]
	v_pk_add_f32 v[208:209], v[208:209], v[210:211]
	v_add_f32_e32 v207, v208, v209
	v_mad_u32_u24 v217, v95, s52, v220
	v_add_u32_e32 v218, v217, v221
	global_load_dwordx4 v[186:189], v217, s[30:31]
	global_load_dwordx2 v[190:191], v218, s[30:31]
	s_mov_b32 s89, s7
	s_mov_b32 s90, s8
	s_mov_b32 s7, s53
	s_mov_b32 s8, s54
	s_add_i32 s53, s7, 1
	s_mov_b32 s54, s8
	s_cmp_eq_u32 s53, 8
	s_cselect_b32 s53, 0, s53
	s_cselect_b32 s34, 1, 0
	s_add_i32 s54, s54, s34
	s_mul_i32 s55, s53, s5
	s_add_i32 s55, s55, s6
	s_min_u32 s55, s55, 0x3fff
	s_and_b32 s34, s54, 7
	s_mul_i32 s34, s34, 0x300000
	s_cmp_lt_u32 s54, 8
	s_cselect_b32 s30, s16, s18
	s_cselect_b32 s31, s17, s19
	s_add_u32 s30, s30, s34
	s_addc_u32 s31, s31, 0
	s_and_b32 s34, s54, 7
	s_lshl_b32 s34, s34, 6
	s_lshl_b32 s35, s55, 12
	s_add_u32 s34, s34, s35
	s_add_u32 s32, s10, s34
	s_addc_u32 s33, s11, 0
	s_lshl_b32 s34, s53, 9
	v_add_u32_e32 v216, s34, v223
	ds_read_b128 v[80:83], v216 offset:0
	ds_read_b128 v[84:87], v216 offset:16
	ds_read_b128 v[88:91], v216 offset:32
	ds_read_b128 v[92:95], v216 offset:48
	v_cndmask_b32_e64 v212, v200, v192, s[44:45]
	v_cndmask_b32_e64 v213, v192, v200, s[44:45]
	v_cndmask_b32_e64 v214, v201, v193, s[44:45]
	v_cndmask_b32_e64 v215, v193, v201, s[44:45]
	v_add_f32_dpp v192, v212, v213 row_half_mirror row_mask:0xf bank_mask:0xf
	v_add_f32_dpp v193, v214, v215 row_half_mirror row_mask:0xf bank_mask:0xf
	v_cndmask_b32_e64 v212, v202, v194, s[44:45]
	v_cndmask_b32_e64 v213, v194, v202, s[44:45]
	v_cndmask_b32_e64 v214, v203, v195, s[44:45]
	v_cndmask_b32_e64 v215, v195, v203, s[44:45]
	v_add_f32_dpp v194, v212, v213 row_half_mirror row_mask:0xf bank_mask:0xf
	v_add_f32_dpp v195, v214, v215 row_half_mirror row_mask:0xf bank_mask:0xf
	v_cndmask_b32_e64 v212, v204, v196, s[44:45]
	v_cndmask_b32_e64 v213, v196, v204, s[44:45]
	v_cndmask_b32_e64 v214, v205, v197, s[44:45]
	v_cndmask_b32_e64 v215, v197, v205, s[44:45]
	v_add_f32_dpp v196, v212, v213 row_half_mirror row_mask:0xf bank_mask:0xf
	v_add_f32_dpp v197, v214, v215 row_half_mirror row_mask:0xf bank_mask:0xf
	v_cndmask_b32_e64 v212, v206, v198, s[44:45]
	v_cndmask_b32_e64 v213, v198, v206, s[44:45]
	v_cndmask_b32_e64 v214, v207, v199, s[44:45]
	v_cndmask_b32_e64 v215, v199, v207, s[44:45]
	v_add_f32_dpp v198, v212, v213 row_half_mirror row_mask:0xf bank_mask:0xf
	v_add_f32_dpp v199, v214, v215 row_half_mirror row_mask:0xf bank_mask:0xf
	v_cndmask_b32_e64 v212, v196, v192, s[42:43]
	v_cndmask_b32_e64 v213, v192, v196, s[42:43]
	v_cndmask_b32_e64 v214, v197, v193, s[42:43]
	v_cndmask_b32_e64 v215, v193, v197, s[42:43]
	v_add_f32_dpp v192, v212, v213 quad_perm:[2,3,0,1] row_mask:0xf bank_mask:0xf
	v_add_f32_dpp v193, v214, v215 quad_perm:[2,3,0,1] row_mask:0xf bank_mask:0xf
	v_cndmask_b32_e64 v212, v198, v194, s[42:43]
	v_cndmask_b32_e64 v213, v194, v198, s[42:43]
	v_cndmask_b32_e64 v214, v199, v195, s[42:43]
	v_cndmask_b32_e64 v215, v195, v199, s[42:43]
	v_add_f32_dpp v194, v212, v213 quad_perm:[2,3,0,1] row_mask:0xf bank_mask:0xf
	v_add_f32_dpp v195, v214, v215 quad_perm:[2,3,0,1] row_mask:0xf bank_mask:0xf
	v_cndmask_b32_e64 v212, v194, v192, s[40:41]
	v_cndmask_b32_e64 v213, v192, v194, s[40:41]
	v_cndmask_b32_e64 v214, v195, v193, s[40:41]
	v_cndmask_b32_e64 v215, v193, v195, s[40:41]
	v_add_f32_dpp v192, v212, v213 quad_perm:[1,0,3,2] row_mask:0xf bank_mask:0xf
	v_add_f32_dpp v193, v214, v215 quad_perm:[1,0,3,2] row_mask:0xf bank_mask:0xf
	s_lshl_b32 s34, s89, 9
	s_addk_i32 s34, 0x1000
	v_add_u32_e32 v219, s34, v222
	s_cmp_eq_u32 s90, 0
	s_cbranch_scc1 .Lex_ufirst
	ds_read_b64 v[212:213], v219
	s_waitcnt lgkmcnt(0)
	v_pk_add_f32 v[192:193], v[192:193], v[212:213]
.Lex_ufirst:
	ds_write_b64 v219, v[192:193]
	s_cmp_lt_u32 s8, 8
	s_cbranch_scc1 .Lex_uloop
	s_waitcnt vmcnt(0) lgkmcnt(0)
	ds_read_b64 v[96:97], v222 offset:4096
	ds_read_b64 v[98:99], v222 offset:0
	ds_read_b64 v[108:109], v222 offset:4608
	ds_read_b64 v[110:111], v222 offset:512
	ds_read_b64 v[120:121], v222 offset:5120
	ds_read_b64 v[122:123], v222 offset:1024
	ds_read_b64 v[132:133], v222 offset:5632
	ds_read_b64 v[134:135], v222 offset:1536
	ds_read_b64 v[144:145], v222 offset:6144
	ds_read_b64 v[146:147], v222 offset:2048
	ds_read_b64 v[156:157], v222 offset:6656
	ds_read_b64 v[158:159], v222 offset:2560
	ds_read_b64 v[168:169], v222 offset:7168
	ds_read_b64 v[170:171], v222 offset:3072
	ds_read_b64 v[180:181], v222 offset:7680
	ds_read_b64 v[182:183], v222 offset:3584
	s_waitcnt lgkmcnt(0)
	s_movk_i32 s36, 0
	s_mul_i32 s37, s36, s5
	s_add_i32 s37, s37, s6
	s_min_u32 s37, s37, 0x3fff
	s_lshl_b32 s37, s37, 9
	s_add_u32 s82, s14, s37
	s_addc_u32 s83, s15, 0
	v_lshlrev_b32_e32 v219, 3, v228
	global_load_dwordx2 v[100:101], v219, s[82:83]
	v_lshlrev_b32_e32 v217, 2, v98
	v_lshlrev_b32_e32 v218, 2, v99
	global_load_dword v102, v217, s[20:21]
	global_load_dword v103, v218, s[20:21]
	global_load_dword v104, v217, s[22:23]
	global_load_dword v105, v218, s[22:23]
	s_movk_i32 s36, 1
	s_mul_i32 s37, s36, s5
	s_add_i32 s37, s37, s6
	s_min_u32 s37, s37, 0x3fff
	s_lshl_b32 s37, s37, 9
	s_add_u32 s82, s14, s37
	s_addc_u32 s83, s15, 0
	v_lshlrev_b32_e32 v219, 3, v228
	global_load_dwordx2 v[112:113], v219, s[82:83]
	v_lshlrev_b32_e32 v217, 2, v110
	v_lshlrev_b32_e32 v218, 2, v111
	global_load_dword v114, v217, s[20:21]
	global_load_dword v115, v218, s[20:21]
	global_load_dword v116, v217, s[22:23]
	global_load_dword v117, v218, s[22:23]
	s_movk_i32 s36, 2
	s_mul_i32 s37, s36, s5
	s_add_i32 s37, s37, s6
	s_min_u32 s37, s37, 0x3fff
	s_lshl_b32 s37, s37, 9
	s_add_u32 s82, s14, s37
	s_addc_u32 s83, s15, 0
	v_lshlrev_b32_e32 v219, 3, v228
	global_load_dwordx2 v[124:125], v219, s[82:83]
	v_lshlrev_b32_e32 v217, 2, v122
	v_lshlrev_b32_e32 v218, 2, v123
	global_load_dword v126, v217, s[20:21]
	global_load_dword v127, v218, s[20:21]
	global_load_dword v128, v217, s[22:23]
	global_load_dword v129, v218, s[22:23]
	s_movk_i32 s36, 3
	s_mul_i32 s37, s36, s5
	s_add_i32 s37, s37, s6
	s_min_u32 s37, s37, 0x3fff
	s_lshl_b32 s37, s37, 9
	s_add_u32 s82, s14, s37
	s_addc_u32 s83, s15, 0
	v_lshlrev_b32_e32 v219, 3, v228
	global_load_dwordx2 v[136:137], v219, s[82:83]
	v_lshlrev_b32_e32 v217, 2, v134
	v_lshlrev_b32_e32 v218, 2, v135
	global_load_dword v138, v217, s[20:21]
	global_load_dword v139, v218, s[20:21]
	global_load_dword v140, v217, s[22:23]
	global_load_dword v141, v218, s[22:23]
	s_movk_i32 s36, 4
	s_mul_i32 s37, s36, s5
	s_add_i32 s37, s37, s6
	s_min_u32 s37, s37, 0x3fff
	s_lshl_b32 s37, s37, 9
	s_add_u32 s82, s14, s37
	s_addc_u32 s83, s15, 0
	v_lshlrev_b32_e32 v219, 3, v228
	global_load_dwordx2 v[148:149], v219, s[82:83]
	v_lshlrev_b32_e32 v217, 2, v146
	v_lshlrev_b32_e32 v218, 2, v147
	global_load_dword v150, v217, s[20:21]
	global_load_dword v151, v218, s[20:21]
	global_load_dword v152, v217, s[22:23]
	global_load_dword v153, v218, s[22:23]
	s_movk_i32 s36, 5
	s_mul_i32 s37, s36, s5
	s_add_i32 s37, s37, s6
	s_min_u32 s37, s37, 0x3fff
	s_lshl_b32 s37, s37, 9
	s_add_u32 s82, s14, s37
	s_addc_u32 s83, s15, 0
	v_lshlrev_b32_e32 v219, 3, v228
	global_load_dwordx2 v[160:161], v219, s[82:83]
	v_lshlrev_b32_e32 v217, 2, v158
	v_lshlrev_b32_e32 v218, 2, v159
	global_load_dword v162, v217, s[20:21]
	global_load_dword v163, v218, s[20:21]
	global_load_dword v164, v217, s[22:23]
	global_load_dword v165, v218, s[22:23]
	s_movk_i32 s36, 6
	s_mul_i32 s37, s36, s5
	s_add_i32 s37, s37, s6
	s_min_u32 s37, s37, 0x3fff
	s_lshl_b32 s37, s37, 9
	s_add_u32 s82, s14, s37
	s_addc_u32 s83, s15, 0
	v_lshlrev_b32_e32 v219, 3, v228
	global_load_dwordx2 v[172:173], v219, s[82:83]
	v_lshlrev_b32_e32 v217, 2, v170
	v_lshlrev_b32_e32 v218, 2, v171
	global_load_dword v174, v217, s[20:21]
	global_load_dword v175, v218, s[20:21]
	global_load_dword v176, v217, s[22:23]
	global_load_dword v177, v218, s[22:23]
	s_movk_i32 s36, 7
	s_mul_i32 s37, s36, s5
	s_add_i32 s37, s37, s6
	s_min_u32 s37, s37, 0x3fff
	s_lshl_b32 s37, s37, 9
	s_add_u32 s82, s14, s37
	s_addc_u32 s83, s15, 0
	v_lshlrev_b32_e32 v219, 3, v228
	global_load_dwordx2 v[184:185], v219, s[82:83]
	v_lshlrev_b32_e32 v217, 2, v182
	v_lshlrev_b32_e32 v218, 2, v183
	global_load_dword v186, v217, s[20:21]
	global_load_dword v187, v218, s[20:21]
	global_load_dword v188, v217, s[22:23]
	global_load_dword v189, v218, s[22:23]
	s_waitcnt vmcnt(0)
	v_mul_f32_e32 v96, v102, v96
	v_mul_f32_e32 v0, 0x3f3504f3, v96
	v_mov_b32_e32 v6, s67
	v_fma_f32 v2, |v0|, s66, v6
	v_fma_f32 v2, |v0|, v2, s68
	v_fma_f32 v2, |v0|, v2, s69
	v_fma_f32 v2, |v0|, v2, s70
	v_fma_f32 v2, |v0|, v2, s71
	v_fma_f32 v2, |v0|, v2, s72
	v_fma_f32 v2, |v0|, v2, |v0|
	v_mul_f32_e32 v4, 0xbfb8aa3b, v2
	v_fma_f32 v5, v2, s73, -v4
	v_rndne_f32_e32 v6, v4
	v_fmac_f32_e32 v5, 0xb2a5705f, v2
	v_sub_f32_e32 v4, v4, v6
	v_add_f32_e32 v4, v4, v5
	v_cvt_i32_f32_e32 v5, v6
	v_exp_f32_e32 v4, v4
	v_cmp_nlt_f32_e64 s[82:83], s74, v2
	v_ldexp_f32 v4, v4, v5
	s_nop 0
	v_cndmask_b32_e64 v4, 0, v4, s[82:83]
	v_cmp_ngt_f32_e64 s[82:83], s75, v2
	v_mov_b32_e32 v6, 0x7f800000
	s_nop 0
	v_cndmask_b32_e64 v3, v6, v4, s[82:83]
	v_sub_f32_e32 v3, 1.0, v3
	v_mul_f32_e32 v4, v0, v0
	v_mov_b32_e32 v6, s76
	v_fmamk_f32 v5, v4, 0xba1345e1, v6
	v_fmaak_f32 v5, v4, v5, 0xbcdac9b8
	v_fmaak_f32 v5, v4, v5, 0x3de703be
	v_fmaak_f32 v5, v4, v5, 0xbec09330
	v_fmaak_f32 v4, v4, v5, 0x3e0375d0
	v_fma_f32 v7, |v0|, v4, |v0|
	v_cmp_nlt_f32_e64 s[82:83], |v0|, 1.0
	s_nop 1
	v_cndmask_b32_e64 v3, v7, v3, s[82:83]
	v_bfi_b32 v3, s77, v3, v0
	v_mul_f32_e32 v96, 0.5, v96
	v_add_f32_e32 v3, 1.0, v3
	v_mul_f32_e32 v96, v96, v3
	v_mul_f32_e32 v96, v96, v100
	v_mul_f32_e32 v96, v104, v96
	v_mul_f32_e32 v97, v103, v97
	v_mul_f32_e32 v0, 0x3f3504f3, v97
	v_mov_b32_e32 v6, s67
	v_fma_f32 v2, |v0|, s66, v6
	v_fma_f32 v2, |v0|, v2, s68
	v_fma_f32 v2, |v0|, v2, s69
	v_fma_f32 v2, |v0|, v2, s70
	v_fma_f32 v2, |v0|, v2, s71
	v_fma_f32 v2, |v0|, v2, s72
	v_fma_f32 v2, |v0|, v2, |v0|
	v_mul_f32_e32 v4, 0xbfb8aa3b, v2
	v_fma_f32 v5, v2, s73, -v4
	v_rndne_f32_e32 v6, v4
	v_fmac_f32_e32 v5, 0xb2a5705f, v2
	v_sub_f32_e32 v4, v4, v6
	v_add_f32_e32 v4, v4, v5
	v_cvt_i32_f32_e32 v5, v6
	v_exp_f32_e32 v4, v4
	v_cmp_nlt_f32_e64 s[82:83], s74, v2
	v_ldexp_f32 v4, v4, v5
	s_nop 0
	v_cndmask_b32_e64 v4, 0, v4, s[82:83]
	v_cmp_ngt_f32_e64 s[82:83], s75, v2
	v_mov_b32_e32 v6, 0x7f800000
	s_nop 0
	v_cndmask_b32_e64 v3, v6, v4, s[82:83]
	v_sub_f32_e32 v3, 1.0, v3
	v_mul_f32_e32 v4, v0, v0
	v_mov_b32_e32 v6, s76
	v_fmamk_f32 v5, v4, 0xba1345e1, v6
	v_fmaak_f32 v5, v4, v5, 0xbcdac9b8
	v_fmaak_f32 v5, v4, v5, 0x3de703be
	v_fmaak_f32 v5, v4, v5, 0xbec09330
	v_fmaak_f32 v4, v4, v5, 0x3e0375d0
	v_fma_f32 v7, |v0|, v4, |v0|
	v_cmp_nlt_f32_e64 s[82:83], |v0|, 1.0
	s_nop 1
	v_cndmask_b32_e64 v3, v7, v3, s[82:83]
	v_bfi_b32 v3, s77, v3, v0
	v_mul_f32_e32 v97, 0.5, v97
	v_add_f32_e32 v3, 1.0, v3
	v_mul_f32_e32 v97, v97, v3
	v_mul_f32_e32 v97, v97, v101
	v_mul_f32_e32 v97, v105, v97
	ds_write_b64 v222, v[96:97] offset:4096
	v_mul_f32_e32 v108, v114, v108
	v_mul_f32_e32 v0, 0x3f3504f3, v108
	v_mov_b32_e32 v6, s67
	v_fma_f32 v2, |v0|, s66, v6
	v_fma_f32 v2, |v0|, v2, s68
	v_fma_f32 v2, |v0|, v2, s69
	v_fma_f32 v2, |v0|, v2, s70
	v_fma_f32 v2, |v0|, v2, s71
	v_fma_f32 v2, |v0|, v2, s72
	v_fma_f32 v2, |v0|, v2, |v0|
	v_mul_f32_e32 v4, 0xbfb8aa3b, v2
	v_fma_f32 v5, v2, s73, -v4
	v_rndne_f32_e32 v6, v4
	v_fmac_f32_e32 v5, 0xb2a5705f, v2
	v_sub_f32_e32 v4, v4, v6
	v_add_f32_e32 v4, v4, v5
	v_cvt_i32_f32_e32 v5, v6
	v_exp_f32_e32 v4, v4
	v_cmp_nlt_f32_e64 s[82:83], s74, v2
	v_ldexp_f32 v4, v4, v5
	s_nop 0
	v_cndmask_b32_e64 v4, 0, v4, s[82:83]
	v_cmp_ngt_f32_e64 s[82:83], s75, v2
	v_mov_b32_e32 v6, 0x7f800000
	s_nop 0
	v_cndmask_b32_e64 v3, v6, v4, s[82:83]
	v_sub_f32_e32 v3, 1.0, v3
	v_mul_f32_e32 v4, v0, v0
	v_mov_b32_e32 v6, s76
	v_fmamk_f32 v5, v4, 0xba1345e1, v6
	v_fmaak_f32 v5, v4, v5, 0xbcdac9b8
	v_fmaak_f32 v5, v4, v5, 0x3de703be
	v_fmaak_f32 v5, v4, v5, 0xbec09330
	v_fmaak_f32 v4, v4, v5, 0x3e0375d0
	v_fma_f32 v7, |v0|, v4, |v0|
	v_cmp_nlt_f32_e64 s[82:83], |v0|, 1.0
	s_nop 1
	v_cndmask_b32_e64 v3, v7, v3, s[82:83]
	v_bfi_b32 v3, s77, v3, v0
	v_mul_f32_e32 v108, 0.5, v108
	v_add_f32_e32 v3, 1.0, v3
	v_mul_f32_e32 v108, v108, v3
	v_mul_f32_e32 v108, v108, v112
	v_mul_f32_e32 v108, v116, v108
	v_mul_f32_e32 v109, v115, v109
	v_mul_f32_e32 v0, 0x3f3504f3, v109
	v_mov_b32_e32 v6, s67
	v_fma_f32 v2, |v0|, s66, v6
	v_fma_f32 v2, |v0|, v2, s68
	v_fma_f32 v2, |v0|, v2, s69
	v_fma_f32 v2, |v0|, v2, s70
	v_fma_f32 v2, |v0|, v2, s71
	v_fma_f32 v2, |v0|, v2, s72
	v_fma_f32 v2, |v0|, v2, |v0|
	v_mul_f32_e32 v4, 0xbfb8aa3b, v2
	v_fma_f32 v5, v2, s73, -v4
	v_rndne_f32_e32 v6, v4
	v_fmac_f32_e32 v5, 0xb2a5705f, v2
	v_sub_f32_e32 v4, v4, v6
	v_add_f32_e32 v4, v4, v5
	v_cvt_i32_f32_e32 v5, v6
	v_exp_f32_e32 v4, v4
	v_cmp_nlt_f32_e64 s[82:83], s74, v2
	v_ldexp_f32 v4, v4, v5
	s_nop 0
	v_cndmask_b32_e64 v4, 0, v4, s[82:83]
	v_cmp_ngt_f32_e64 s[82:83], s75, v2
	v_mov_b32_e32 v6, 0x7f800000
	s_nop 0
	v_cndmask_b32_e64 v3, v6, v4, s[82:83]
	v_sub_f32_e32 v3, 1.0, v3
	v_mul_f32_e32 v4, v0, v0
	v_mov_b32_e32 v6, s76
	v_fmamk_f32 v5, v4, 0xba1345e1, v6
	v_fmaak_f32 v5, v4, v5, 0xbcdac9b8
	v_fmaak_f32 v5, v4, v5, 0x3de703be
	v_fmaak_f32 v5, v4, v5, 0xbec09330
	v_fmaak_f32 v4, v4, v5, 0x3e0375d0
	v_fma_f32 v7, |v0|, v4, |v0|
	v_cmp_nlt_f32_e64 s[82:83], |v0|, 1.0
	s_nop 1
	v_cndmask_b32_e64 v3, v7, v3, s[82:83]
	v_bfi_b32 v3, s77, v3, v0
	v_mul_f32_e32 v109, 0.5, v109
	v_add_f32_e32 v3, 1.0, v3
	v_mul_f32_e32 v109, v109, v3
	v_mul_f32_e32 v109, v109, v113
	v_mul_f32_e32 v109, v117, v109
	ds_write_b64 v222, v[108:109] offset:4608
	v_mul_f32_e32 v120, v126, v120
	v_mul_f32_e32 v0, 0x3f3504f3, v120
	v_mov_b32_e32 v6, s67
	v_fma_f32 v2, |v0|, s66, v6
	v_fma_f32 v2, |v0|, v2, s68
	v_fma_f32 v2, |v0|, v2, s69
	v_fma_f32 v2, |v0|, v2, s70
	v_fma_f32 v2, |v0|, v2, s71
	v_fma_f32 v2, |v0|, v2, s72
	v_fma_f32 v2, |v0|, v2, |v0|
	v_mul_f32_e32 v4, 0xbfb8aa3b, v2
	v_fma_f32 v5, v2, s73, -v4
	v_rndne_f32_e32 v6, v4
	v_fmac_f32_e32 v5, 0xb2a5705f, v2
	v_sub_f32_e32 v4, v4, v6
	v_add_f32_e32 v4, v4, v5
	v_cvt_i32_f32_e32 v5, v6
	v_exp_f32_e32 v4, v4
	v_cmp_nlt_f32_e64 s[82:83], s74, v2
	v_ldexp_f32 v4, v4, v5
	s_nop 0
	v_cndmask_b32_e64 v4, 0, v4, s[82:83]
	v_cmp_ngt_f32_e64 s[82:83], s75, v2
	v_mov_b32_e32 v6, 0x7f800000
	s_nop 0
	v_cndmask_b32_e64 v3, v6, v4, s[82:83]
	v_sub_f32_e32 v3, 1.0, v3
	v_mul_f32_e32 v4, v0, v0
	v_mov_b32_e32 v6, s76
	v_fmamk_f32 v5, v4, 0xba1345e1, v6
	v_fmaak_f32 v5, v4, v5, 0xbcdac9b8
	v_fmaak_f32 v5, v4, v5, 0x3de703be
	v_fmaak_f32 v5, v4, v5, 0xbec09330
	v_fmaak_f32 v4, v4, v5, 0x3e0375d0
	v_fma_f32 v7, |v0|, v4, |v0|
	v_cmp_nlt_f32_e64 s[82:83], |v0|, 1.0
	s_nop 1
	v_cndmask_b32_e64 v3, v7, v3, s[82:83]
	v_bfi_b32 v3, s77, v3, v0
	v_mul_f32_e32 v120, 0.5, v120
	v_add_f32_e32 v3, 1.0, v3
	v_mul_f32_e32 v120, v120, v3
	v_mul_f32_e32 v120, v120, v124
	v_mul_f32_e32 v120, v128, v120
	v_mul_f32_e32 v121, v127, v121
	v_mul_f32_e32 v0, 0x3f3504f3, v121
	v_mov_b32_e32 v6, s67
	v_fma_f32 v2, |v0|, s66, v6
	v_fma_f32 v2, |v0|, v2, s68
	v_fma_f32 v2, |v0|, v2, s69
	v_fma_f32 v2, |v0|, v2, s70
	v_fma_f32 v2, |v0|, v2, s71
	v_fma_f32 v2, |v0|, v2, s72
	v_fma_f32 v2, |v0|, v2, |v0|
	v_mul_f32_e32 v4, 0xbfb8aa3b, v2
	v_fma_f32 v5, v2, s73, -v4
	v_rndne_f32_e32 v6, v4
	v_fmac_f32_e32 v5, 0xb2a5705f, v2
	v_sub_f32_e32 v4, v4, v6
	v_add_f32_e32 v4, v4, v5
	v_cvt_i32_f32_e32 v5, v6
	v_exp_f32_e32 v4, v4
	v_cmp_nlt_f32_e64 s[82:83], s74, v2
	v_ldexp_f32 v4, v4, v5
	s_nop 0
	v_cndmask_b32_e64 v4, 0, v4, s[82:83]
	v_cmp_ngt_f32_e64 s[82:83], s75, v2
	v_mov_b32_e32 v6, 0x7f800000
	s_nop 0
	v_cndmask_b32_e64 v3, v6, v4, s[82:83]
	v_sub_f32_e32 v3, 1.0, v3
	v_mul_f32_e32 v4, v0, v0
	v_mov_b32_e32 v6, s76
	v_fmamk_f32 v5, v4, 0xba1345e1, v6
	v_fmaak_f32 v5, v4, v5, 0xbcdac9b8
	v_fmaak_f32 v5, v4, v5, 0x3de703be
	v_fmaak_f32 v5, v4, v5, 0xbec09330
	v_fmaak_f32 v4, v4, v5, 0x3e0375d0
	v_fma_f32 v7, |v0|, v4, |v0|
	v_cmp_nlt_f32_e64 s[82:83], |v0|, 1.0
	s_nop 1
	v_cndmask_b32_e64 v3, v7, v3, s[82:83]
	v_bfi_b32 v3, s77, v3, v0
	v_mul_f32_e32 v121, 0.5, v121
	v_add_f32_e32 v3, 1.0, v3
	v_mul_f32_e32 v121, v121, v3
	v_mul_f32_e32 v121, v121, v125
	v_mul_f32_e32 v121, v129, v121
	ds_write_b64 v222, v[120:121] offset:5120
	v_mul_f32_e32 v132, v138, v132
	v_mul_f32_e32 v0, 0x3f3504f3, v132
	v_mov_b32_e32 v6, s67
	v_fma_f32 v2, |v0|, s66, v6
	v_fma_f32 v2, |v0|, v2, s68
	v_fma_f32 v2, |v0|, v2, s69
	v_fma_f32 v2, |v0|, v2, s70
	v_fma_f32 v2, |v0|, v2, s71
	v_fma_f32 v2, |v0|, v2, s72
	v_fma_f32 v2, |v0|, v2, |v0|
	v_mul_f32_e32 v4, 0xbfb8aa3b, v2
	v_fma_f32 v5, v2, s73, -v4
	v_rndne_f32_e32 v6, v4
	v_fmac_f32_e32 v5, 0xb2a5705f, v2
	v_sub_f32_e32 v4, v4, v6
	v_add_f32_e32 v4, v4, v5
	v_cvt_i32_f32_e32 v5, v6
	v_exp_f32_e32 v4, v4
	v_cmp_nlt_f32_e64 s[82:83], s74, v2
	v_ldexp_f32 v4, v4, v5
	s_nop 0
	v_cndmask_b32_e64 v4, 0, v4, s[82:83]
	v_cmp_ngt_f32_e64 s[82:83], s75, v2
	v_mov_b32_e32 v6, 0x7f800000
	s_nop 0
	v_cndmask_b32_e64 v3, v6, v4, s[82:83]
	v_sub_f32_e32 v3, 1.0, v3
	v_mul_f32_e32 v4, v0, v0
	v_mov_b32_e32 v6, s76
	v_fmamk_f32 v5, v4, 0xba1345e1, v6
	v_fmaak_f32 v5, v4, v5, 0xbcdac9b8
	v_fmaak_f32 v5, v4, v5, 0x3de703be
	v_fmaak_f32 v5, v4, v5, 0xbec09330
	v_fmaak_f32 v4, v4, v5, 0x3e0375d0
	v_fma_f32 v7, |v0|, v4, |v0|
	v_cmp_nlt_f32_e64 s[82:83], |v0|, 1.0
	s_nop 1
	v_cndmask_b32_e64 v3, v7, v3, s[82:83]
	v_bfi_b32 v3, s77, v3, v0
	v_mul_f32_e32 v132, 0.5, v132
	v_add_f32_e32 v3, 1.0, v3
	v_mul_f32_e32 v132, v132, v3
	v_mul_f32_e32 v132, v132, v136
	v_mul_f32_e32 v132, v140, v132
	v_mul_f32_e32 v133, v139, v133
	v_mul_f32_e32 v0, 0x3f3504f3, v133
	v_mov_b32_e32 v6, s67
	v_fma_f32 v2, |v0|, s66, v6
	v_fma_f32 v2, |v0|, v2, s68
	v_fma_f32 v2, |v0|, v2, s69
	v_fma_f32 v2, |v0|, v2, s70
	v_fma_f32 v2, |v0|, v2, s71
	v_fma_f32 v2, |v0|, v2, s72
	v_fma_f32 v2, |v0|, v2, |v0|
	v_mul_f32_e32 v4, 0xbfb8aa3b, v2
	v_fma_f32 v5, v2, s73, -v4
	v_rndne_f32_e32 v6, v4
	v_fmac_f32_e32 v5, 0xb2a5705f, v2
	v_sub_f32_e32 v4, v4, v6
	v_add_f32_e32 v4, v4, v5
	v_cvt_i32_f32_e32 v5, v6
	v_exp_f32_e32 v4, v4
	v_cmp_nlt_f32_e64 s[82:83], s74, v2
	v_ldexp_f32 v4, v4, v5
	s_nop 0
	v_cndmask_b32_e64 v4, 0, v4, s[82:83]
	v_cmp_ngt_f32_e64 s[82:83], s75, v2
	v_mov_b32_e32 v6, 0x7f800000
	s_nop 0
	v_cndmask_b32_e64 v3, v6, v4, s[82:83]
	v_sub_f32_e32 v3, 1.0, v3
	v_mul_f32_e32 v4, v0, v0
	v_mov_b32_e32 v6, s76
	v_fmamk_f32 v5, v4, 0xba1345e1, v6
	v_fmaak_f32 v5, v4, v5, 0xbcdac9b8
	v_fmaak_f32 v5, v4, v5, 0x3de703be
	v_fmaak_f32 v5, v4, v5, 0xbec09330
	v_fmaak_f32 v4, v4, v5, 0x3e0375d0
	v_fma_f32 v7, |v0|, v4, |v0|
	v_cmp_nlt_f32_e64 s[82:83], |v0|, 1.0
	s_nop 1
	v_cndmask_b32_e64 v3, v7, v3, s[82:83]
	v_bfi_b32 v3, s77, v3, v0
	v_mul_f32_e32 v133, 0.5, v133
	v_add_f32_e32 v3, 1.0, v3
	v_mul_f32_e32 v133, v133, v3
	v_mul_f32_e32 v133, v133, v137
	v_mul_f32_e32 v133, v141, v133
	ds_write_b64 v222, v[132:133] offset:5632
	v_mul_f32_e32 v144, v150, v144
	v_mul_f32_e32 v0, 0x3f3504f3, v144
	v_mov_b32_e32 v6, s67
	v_fma_f32 v2, |v0|, s66, v6
	v_fma_f32 v2, |v0|, v2, s68
	v_fma_f32 v2, |v0|, v2, s69
	v_fma_f32 v2, |v0|, v2, s70
	v_fma_f32 v2, |v0|, v2, s71
	v_fma_f32 v2, |v0|, v2, s72
	v_fma_f32 v2, |v0|, v2, |v0|
	v_mul_f32_e32 v4, 0xbfb8aa3b, v2
	v_fma_f32 v5, v2, s73, -v4
	v_rndne_f32_e32 v6, v4
	v_fmac_f32_e32 v5, 0xb2a5705f, v2
	v_sub_f32_e32 v4, v4, v6
	v_add_f32_e32 v4, v4, v5
	v_cvt_i32_f32_e32 v5, v6
	v_exp_f32_e32 v4, v4
	v_cmp_nlt_f32_e64 s[82:83], s74, v2
	v_ldexp_f32 v4, v4, v5
	s_nop 0
	v_cndmask_b32_e64 v4, 0, v4, s[82:83]
	v_cmp_ngt_f32_e64 s[82:83], s75, v2
	v_mov_b32_e32 v6, 0x7f800000
	s_nop 0
	v_cndmask_b32_e64 v3, v6, v4, s[82:83]
	v_sub_f32_e32 v3, 1.0, v3
	v_mul_f32_e32 v4, v0, v0
	v_mov_b32_e32 v6, s76
	v_fmamk_f32 v5, v4, 0xba1345e1, v6
	v_fmaak_f32 v5, v4, v5, 0xbcdac9b8
	v_fmaak_f32 v5, v4, v5, 0x3de703be
	v_fmaak_f32 v5, v4, v5, 0xbec09330
	v_fmaak_f32 v4, v4, v5, 0x3e0375d0
	v_fma_f32 v7, |v0|, v4, |v0|
	v_cmp_nlt_f32_e64 s[82:83], |v0|, 1.0
	s_nop 1
	v_cndmask_b32_e64 v3, v7, v3, s[82:83]
	v_bfi_b32 v3, s77, v3, v0
	v_mul_f32_e32 v144, 0.5, v144
	v_add_f32_e32 v3, 1.0, v3
	v_mul_f32_e32 v144, v144, v3
	v_mul_f32_e32 v144, v144, v148
	v_mul_f32_e32 v144, v152, v144
	v_mul_f32_e32 v145, v151, v145
	v_mul_f32_e32 v0, 0x3f3504f3, v145
	v_mov_b32_e32 v6, s67
	v_fma_f32 v2, |v0|, s66, v6
	v_fma_f32 v2, |v0|, v2, s68
	v_fma_f32 v2, |v0|, v2, s69
	v_fma_f32 v2, |v0|, v2, s70
	v_fma_f32 v2, |v0|, v2, s71
	v_fma_f32 v2, |v0|, v2, s72
	v_fma_f32 v2, |v0|, v2, |v0|
	v_mul_f32_e32 v4, 0xbfb8aa3b, v2
	v_fma_f32 v5, v2, s73, -v4
	v_rndne_f32_e32 v6, v4
	v_fmac_f32_e32 v5, 0xb2a5705f, v2
	v_sub_f32_e32 v4, v4, v6
	v_add_f32_e32 v4, v4, v5
	v_cvt_i32_f32_e32 v5, v6
	v_exp_f32_e32 v4, v4
	v_cmp_nlt_f32_e64 s[82:83], s74, v2
	v_ldexp_f32 v4, v4, v5
	s_nop 0
	v_cndmask_b32_e64 v4, 0, v4, s[82:83]
	v_cmp_ngt_f32_e64 s[82:83], s75, v2
	v_mov_b32_e32 v6, 0x7f800000
	s_nop 0
	v_cndmask_b32_e64 v3, v6, v4, s[82:83]
	v_sub_f32_e32 v3, 1.0, v3
	v_mul_f32_e32 v4, v0, v0
	v_mov_b32_e32 v6, s76
	v_fmamk_f32 v5, v4, 0xba1345e1, v6
	v_fmaak_f32 v5, v4, v5, 0xbcdac9b8
	v_fmaak_f32 v5, v4, v5, 0x3de703be
	v_fmaak_f32 v5, v4, v5, 0xbec09330
	v_fmaak_f32 v4, v4, v5, 0x3e0375d0
	v_fma_f32 v7, |v0|, v4, |v0|
	v_cmp_nlt_f32_e64 s[82:83], |v0|, 1.0
	s_nop 1
	v_cndmask_b32_e64 v3, v7, v3, s[82:83]
	v_bfi_b32 v3, s77, v3, v0
	v_mul_f32_e32 v145, 0.5, v145
	v_add_f32_e32 v3, 1.0, v3
	v_mul_f32_e32 v145, v145, v3
	v_mul_f32_e32 v145, v145, v149
	v_mul_f32_e32 v145, v153, v145
	ds_write_b64 v222, v[144:145] offset:6144
	v_mul_f32_e32 v156, v162, v156
	v_mul_f32_e32 v0, 0x3f3504f3, v156
	v_mov_b32_e32 v6, s67
	v_fma_f32 v2, |v0|, s66, v6
	v_fma_f32 v2, |v0|, v2, s68
	v_fma_f32 v2, |v0|, v2, s69
	v_fma_f32 v2, |v0|, v2, s70
	v_fma_f32 v2, |v0|, v2, s71
	v_fma_f32 v2, |v0|, v2, s72
	v_fma_f32 v2, |v0|, v2, |v0|
	v_mul_f32_e32 v4, 0xbfb8aa3b, v2
	v_fma_f32 v5, v2, s73, -v4
	v_rndne_f32_e32 v6, v4
	v_fmac_f32_e32 v5, 0xb2a5705f, v2
	v_sub_f32_e32 v4, v4, v6
	v_add_f32_e32 v4, v4, v5
	v_cvt_i32_f32_e32 v5, v6
	v_exp_f32_e32 v4, v4
	v_cmp_nlt_f32_e64 s[82:83], s74, v2
	v_ldexp_f32 v4, v4, v5
	s_nop 0
	v_cndmask_b32_e64 v4, 0, v4, s[82:83]
	v_cmp_ngt_f32_e64 s[82:83], s75, v2
	v_mov_b32_e32 v6, 0x7f800000
	s_nop 0
	v_cndmask_b32_e64 v3, v6, v4, s[82:83]
	v_sub_f32_e32 v3, 1.0, v3
	v_mul_f32_e32 v4, v0, v0
	v_mov_b32_e32 v6, s76
	v_fmamk_f32 v5, v4, 0xba1345e1, v6
	v_fmaak_f32 v5, v4, v5, 0xbcdac9b8
	v_fmaak_f32 v5, v4, v5, 0x3de703be
	v_fmaak_f32 v5, v4, v5, 0xbec09330
	v_fmaak_f32 v4, v4, v5, 0x3e0375d0
	v_fma_f32 v7, |v0|, v4, |v0|
	v_cmp_nlt_f32_e64 s[82:83], |v0|, 1.0
	s_nop 1
	v_cndmask_b32_e64 v3, v7, v3, s[82:83]
	v_bfi_b32 v3, s77, v3, v0
	v_mul_f32_e32 v156, 0.5, v156
	v_add_f32_e32 v3, 1.0, v3
	v_mul_f32_e32 v156, v156, v3
	v_mul_f32_e32 v156, v156, v160
	v_mul_f32_e32 v156, v164, v156
	v_mul_f32_e32 v157, v163, v157
	v_mul_f32_e32 v0, 0x3f3504f3, v157
	v_mov_b32_e32 v6, s67
	v_fma_f32 v2, |v0|, s66, v6
	v_fma_f32 v2, |v0|, v2, s68
	v_fma_f32 v2, |v0|, v2, s69
	v_fma_f32 v2, |v0|, v2, s70
	v_fma_f32 v2, |v0|, v2, s71
	v_fma_f32 v2, |v0|, v2, s72
	v_fma_f32 v2, |v0|, v2, |v0|
	v_mul_f32_e32 v4, 0xbfb8aa3b, v2
	v_fma_f32 v5, v2, s73, -v4
	v_rndne_f32_e32 v6, v4
	v_fmac_f32_e32 v5, 0xb2a5705f, v2
	v_sub_f32_e32 v4, v4, v6
	v_add_f32_e32 v4, v4, v5
	v_cvt_i32_f32_e32 v5, v6
	v_exp_f32_e32 v4, v4
	v_cmp_nlt_f32_e64 s[82:83], s74, v2
	v_ldexp_f32 v4, v4, v5
	s_nop 0
	v_cndmask_b32_e64 v4, 0, v4, s[82:83]
	v_cmp_ngt_f32_e64 s[82:83], s75, v2
	v_mov_b32_e32 v6, 0x7f800000
	s_nop 0
	v_cndmask_b32_e64 v3, v6, v4, s[82:83]
	v_sub_f32_e32 v3, 1.0, v3
	v_mul_f32_e32 v4, v0, v0
	v_mov_b32_e32 v6, s76
	v_fmamk_f32 v5, v4, 0xba1345e1, v6
	v_fmaak_f32 v5, v4, v5, 0xbcdac9b8
	v_fmaak_f32 v5, v4, v5, 0x3de703be
	v_fmaak_f32 v5, v4, v5, 0xbec09330
	v_fmaak_f32 v4, v4, v5, 0x3e0375d0
	v_fma_f32 v7, |v0|, v4, |v0|
	v_cmp_nlt_f32_e64 s[82:83], |v0|, 1.0
	s_nop 1
	v_cndmask_b32_e64 v3, v7, v3, s[82:83]
	v_bfi_b32 v3, s77, v3, v0
	v_mul_f32_e32 v157, 0.5, v157
	v_add_f32_e32 v3, 1.0, v3
	v_mul_f32_e32 v157, v157, v3
	v_mul_f32_e32 v157, v157, v161
	v_mul_f32_e32 v157, v165, v157
	ds_write_b64 v222, v[156:157] offset:6656
	v_mul_f32_e32 v168, v174, v168
	v_mul_f32_e32 v0, 0x3f3504f3, v168
	v_mov_b32_e32 v6, s67
	v_fma_f32 v2, |v0|, s66, v6
	v_fma_f32 v2, |v0|, v2, s68
	v_fma_f32 v2, |v0|, v2, s69
	v_fma_f32 v2, |v0|, v2, s70
	v_fma_f32 v2, |v0|, v2, s71
	v_fma_f32 v2, |v0|, v2, s72
	v_fma_f32 v2, |v0|, v2, |v0|
	v_mul_f32_e32 v4, 0xbfb8aa3b, v2
	v_fma_f32 v5, v2, s73, -v4
	v_rndne_f32_e32 v6, v4
	v_fmac_f32_e32 v5, 0xb2a5705f, v2
	v_sub_f32_e32 v4, v4, v6
	v_add_f32_e32 v4, v4, v5
	v_cvt_i32_f32_e32 v5, v6
	v_exp_f32_e32 v4, v4
	v_cmp_nlt_f32_e64 s[82:83], s74, v2
	v_ldexp_f32 v4, v4, v5
	s_nop 0
	v_cndmask_b32_e64 v4, 0, v4, s[82:83]
	v_cmp_ngt_f32_e64 s[82:83], s75, v2
	v_mov_b32_e32 v6, 0x7f800000
	s_nop 0
	v_cndmask_b32_e64 v3, v6, v4, s[82:83]
	v_sub_f32_e32 v3, 1.0, v3
	v_mul_f32_e32 v4, v0, v0
	v_mov_b32_e32 v6, s76
	v_fmamk_f32 v5, v4, 0xba1345e1, v6
	v_fmaak_f32 v5, v4, v5, 0xbcdac9b8
	v_fmaak_f32 v5, v4, v5, 0x3de703be
	v_fmaak_f32 v5, v4, v5, 0xbec09330
	v_fmaak_f32 v4, v4, v5, 0x3e0375d0
	v_fma_f32 v7, |v0|, v4, |v0|
	v_cmp_nlt_f32_e64 s[82:83], |v0|, 1.0
	s_nop 1
	v_cndmask_b32_e64 v3, v7, v3, s[82:83]
	v_bfi_b32 v3, s77, v3, v0
	v_mul_f32_e32 v168, 0.5, v168
	v_add_f32_e32 v3, 1.0, v3
	v_mul_f32_e32 v168, v168, v3
	v_mul_f32_e32 v168, v168, v172
	v_mul_f32_e32 v168, v176, v168
	v_mul_f32_e32 v169, v175, v169
	v_mul_f32_e32 v0, 0x3f3504f3, v169
	v_mov_b32_e32 v6, s67
	v_fma_f32 v2, |v0|, s66, v6
	v_fma_f32 v2, |v0|, v2, s68
	v_fma_f32 v2, |v0|, v2, s69
	v_fma_f32 v2, |v0|, v2, s70
	v_fma_f32 v2, |v0|, v2, s71
	v_fma_f32 v2, |v0|, v2, s72
	v_fma_f32 v2, |v0|, v2, |v0|
	v_mul_f32_e32 v4, 0xbfb8aa3b, v2
	v_fma_f32 v5, v2, s73, -v4
	v_rndne_f32_e32 v6, v4
	v_fmac_f32_e32 v5, 0xb2a5705f, v2
	v_sub_f32_e32 v4, v4, v6
	v_add_f32_e32 v4, v4, v5
	v_cvt_i32_f32_e32 v5, v6
	v_exp_f32_e32 v4, v4
	v_cmp_nlt_f32_e64 s[82:83], s74, v2
	v_ldexp_f32 v4, v4, v5
	s_nop 0
	v_cndmask_b32_e64 v4, 0, v4, s[82:83]
	v_cmp_ngt_f32_e64 s[82:83], s75, v2
	v_mov_b32_e32 v6, 0x7f800000
	s_nop 0
	v_cndmask_b32_e64 v3, v6, v4, s[82:83]
	v_sub_f32_e32 v3, 1.0, v3
	v_mul_f32_e32 v4, v0, v0
	v_mov_b32_e32 v6, s76
	v_fmamk_f32 v5, v4, 0xba1345e1, v6
	v_fmaak_f32 v5, v4, v5, 0xbcdac9b8
	v_fmaak_f32 v5, v4, v5, 0x3de703be
	v_fmaak_f32 v5, v4, v5, 0xbec09330
	v_fmaak_f32 v4, v4, v5, 0x3e0375d0
	v_fma_f32 v7, |v0|, v4, |v0|
	v_cmp_nlt_f32_e64 s[82:83], |v0|, 1.0
	s_nop 1
	v_cndmask_b32_e64 v3, v7, v3, s[82:83]
	v_bfi_b32 v3, s77, v3, v0
	v_mul_f32_e32 v169, 0.5, v169
	v_add_f32_e32 v3, 1.0, v3
	v_mul_f32_e32 v169, v169, v3
	v_mul_f32_e32 v169, v169, v173
	v_mul_f32_e32 v169, v177, v169
	ds_write_b64 v222, v[168:169] offset:7168
	v_mul_f32_e32 v180, v186, v180
	v_mul_f32_e32 v0, 0x3f3504f3, v180
	v_mov_b32_e32 v6, s67
	v_fma_f32 v2, |v0|, s66, v6
	v_fma_f32 v2, |v0|, v2, s68
	v_fma_f32 v2, |v0|, v2, s69
	v_fma_f32 v2, |v0|, v2, s70
	v_fma_f32 v2, |v0|, v2, s71
	v_fma_f32 v2, |v0|, v2, s72
	v_fma_f32 v2, |v0|, v2, |v0|
	v_mul_f32_e32 v4, 0xbfb8aa3b, v2
	v_fma_f32 v5, v2, s73, -v4
	v_rndne_f32_e32 v6, v4
	v_fmac_f32_e32 v5, 0xb2a5705f, v2
	v_sub_f32_e32 v4, v4, v6
	v_add_f32_e32 v4, v4, v5
	v_cvt_i32_f32_e32 v5, v6
	v_exp_f32_e32 v4, v4
	v_cmp_nlt_f32_e64 s[82:83], s74, v2
	v_ldexp_f32 v4, v4, v5
	s_nop 0
	v_cndmask_b32_e64 v4, 0, v4, s[82:83]
	v_cmp_ngt_f32_e64 s[82:83], s75, v2
	v_mov_b32_e32 v6, 0x7f800000
	s_nop 0
	v_cndmask_b32_e64 v3, v6, v4, s[82:83]
	v_sub_f32_e32 v3, 1.0, v3
	v_mul_f32_e32 v4, v0, v0
	v_mov_b32_e32 v6, s76
	v_fmamk_f32 v5, v4, 0xba1345e1, v6
	v_fmaak_f32 v5, v4, v5, 0xbcdac9b8
	v_fmaak_f32 v5, v4, v5, 0x3de703be
	v_fmaak_f32 v5, v4, v5, 0xbec09330
	v_fmaak_f32 v4, v4, v5, 0x3e0375d0
	v_fma_f32 v7, |v0|, v4, |v0|
	v_cmp_nlt_f32_e64 s[82:83], |v0|, 1.0
	s_nop 1
	v_cndmask_b32_e64 v3, v7, v3, s[82:83]
	v_bfi_b32 v3, s77, v3, v0
	v_mul_f32_e32 v180, 0.5, v180
	v_add_f32_e32 v3, 1.0, v3
	v_mul_f32_e32 v180, v180, v3
	v_mul_f32_e32 v180, v180, v184
	v_mul_f32_e32 v180, v188, v180
	v_mul_f32_e32 v181, v187, v181
	v_mul_f32_e32 v0, 0x3f3504f3, v181
	v_mov_b32_e32 v6, s67
	v_fma_f32 v2, |v0|, s66, v6
	v_fma_f32 v2, |v0|, v2, s68
	v_fma_f32 v2, |v0|, v2, s69
	v_fma_f32 v2, |v0|, v2, s70
	v_fma_f32 v2, |v0|, v2, s71
	v_fma_f32 v2, |v0|, v2, s72
	v_fma_f32 v2, |v0|, v2, |v0|
	v_mul_f32_e32 v4, 0xbfb8aa3b, v2
	v_fma_f32 v5, v2, s73, -v4
	v_rndne_f32_e32 v6, v4
	v_fmac_f32_e32 v5, 0xb2a5705f, v2
	v_sub_f32_e32 v4, v4, v6
	v_add_f32_e32 v4, v4, v5
	v_cvt_i32_f32_e32 v5, v6
	v_exp_f32_e32 v4, v4
	v_cmp_nlt_f32_e64 s[82:83], s74, v2
	v_ldexp_f32 v4, v4, v5
	s_nop 0
	v_cndmask_b32_e64 v4, 0, v4, s[82:83]
	v_cmp_ngt_f32_e64 s[82:83], s75, v2
	v_mov_b32_e32 v6, 0x7f800000
	s_nop 0
	v_cndmask_b32_e64 v3, v6, v4, s[82:83]
	v_sub_f32_e32 v3, 1.0, v3
	v_mul_f32_e32 v4, v0, v0
	v_mov_b32_e32 v6, s76
	v_fmamk_f32 v5, v4, 0xba1345e1, v6
	v_fmaak_f32 v5, v4, v5, 0xbcdac9b8
	v_fmaak_f32 v5, v4, v5, 0x3de703be
	v_fmaak_f32 v5, v4, v5, 0xbec09330
	v_fmaak_f32 v4, v4, v5, 0x3e0375d0
	v_fma_f32 v7, |v0|, v4, |v0|
	v_cmp_nlt_f32_e64 s[82:83], |v0|, 1.0
	s_nop 1
	v_cndmask_b32_e64 v3, v7, v3, s[82:83]
	v_bfi_b32 v3, s77, v3, v0
	v_mul_f32_e32 v181, 0.5, v181
	v_add_f32_e32 v3, 1.0, v3
	v_mul_f32_e32 v181, v181, v3
	v_mul_f32_e32 v181, v181, v185
	v_mul_f32_e32 v181, v189, v181
	ds_write_b64 v222, v[180:181] offset:7680
	s_waitcnt lgkmcnt(0)
	s_mov_b32 s8, 8
	s_mov_b32 s7, 0
	s_mov_b32 s54, 8
	s_mov_b32 s53, 0
	s_mul_i32 s55, s53, s5
	s_add_i32 s55, s55, s6
	s_min_u32 s55, s55, 0x3fff
	s_and_b32 s34, s54, 7
	s_mul_i32 s34, s34, 0x300000
	s_cmp_lt_u32 s54, 8
	s_cselect_b32 s30, s16, s18
	s_cselect_b32 s31, s17, s19
	s_add_u32 s30, s30, s34
	s_addc_u32 s31, s31, 0
	s_and_b32 s34, s54, 7
	s_lshl_b32 s34, s34, 6
	s_lshl_b32 s35, s55, 12
	s_add_u32 s34, s34, s35
	s_add_u32 s32, s24, s34
	s_addc_u32 s33, s25, 0
	s_and_b32 s34, s54, 7
	s_lshl_b32 s34, s34, 7
	s_lshr_b32 s35, s55, 13
	s_mul_i32 s35, s35, 0xc000
	s_add_u32 s35, s35, s34
	s_add_u32 s35, s35, 0xa000
	s_add_u32 s58, s26, s35
	s_addc_u32 s59, s27, 0
	s_lshl_b32 s35, s55, 13
	s_add_u32 s35, s35, s34
	s_add_u32 s60, s28, s35
	s_addc_u32 s61, s29, 0
	s_mul_i32 s34, s53, s5
	s_add_i32 s34, s34, s6
	s_cmp_lt_u32 s34, 0x4000
	s_cselect_b32 s57, 1, 0
	s_mov_b32 s78, s60
	s_mov_b32 s79, s61
	s_mov_b32 s80, s57
	s_lshl_b32 s34, s53, 9
	v_add_u32_e32 v216, s34, v223
	ds_read_b128 v[80:83], v216 offset:0
	ds_read_b128 v[84:87], v216 offset:16
	ds_read_b128 v[88:91], v216 offset:32
	ds_read_b128 v[92:95], v216 offset:48
	s_waitcnt lgkmcnt(0)
	global_load_dwordx2 v[64:65], v225, s[32:33]
	global_load_dwordx4 v[66:69], v226, s[58:59]
	v_mad_u32_u24 v217, v80, s52, v220
	v_add_u32_e32 v218, v217, v221
	global_load_dwordx4 v[96:99], v217, s[30:31]
	global_load_dwordx2 v[100:101], v218, s[30:31]
	v_mad_u32_u24 v217, v81, s52, v220
	v_add_u32_e32 v218, v217, v221
	global_load_dwordx4 v[102:105], v217, s[30:31]
	global_load_dwordx2 v[106:107], v218, s[30:31]
	v_mad_u32_u24 v217, v82, s52, v220
	v_add_u32_e32 v218, v217, v221
	global_load_dwordx4 v[108:111], v217, s[30:31]
	global_load_dwordx2 v[112:113], v218, s[30:31]
	v_mad_u32_u24 v217, v83, s52, v220
	v_add_u32_e32 v218, v217, v221
	global_load_dwordx4 v[114:117], v217, s[30:31]
	global_load_dwordx2 v[118:119], v218, s[30:31]
	v_mad_u32_u24 v217, v84, s52, v220
	v_add_u32_e32 v218, v217, v221
	global_load_dwordx4 v[120:123], v217, s[30:31]
	global_load_dwordx2 v[124:125], v218, s[30:31]
	v_mad_u32_u24 v217, v85, s52, v220
	v_add_u32_e32 v218, v217, v221
	global_load_dwordx4 v[126:129], v217, s[30:31]
	global_load_dwordx2 v[130:131], v218, s[30:31]
	v_mad_u32_u24 v217, v86, s52, v220
	v_add_u32_e32 v218, v217, v221
	global_load_dwordx4 v[132:135], v217, s[30:31]
	global_load_dwordx2 v[136:137], v218, s[30:31]
	v_mad_u32_u24 v217, v87, s52, v220
	v_add_u32_e32 v218, v217, v221
	global_load_dwordx4 v[138:141], v217, s[30:31]
	global_load_dwordx2 v[142:143], v218, s[30:31]
	v_mad_u32_u24 v217, v88, s52, v220
	v_add_u32_e32 v218, v217, v221
	global_load_dwordx4 v[144:147], v217, s[30:31]
	global_load_dwordx2 v[148:149], v218, s[30:31]
	v_mad_u32_u24 v217, v89, s52, v220
	v_add_u32_e32 v218, v217, v221
	global_load_dwordx4 v[150:153], v217, s[30:31]
	global_load_dwordx2 v[154:155], v218, s[30:31]
	v_mad_u32_u24 v217, v90, s52, v220
	v_add_u32_e32 v218, v217, v221
	global_load_dwordx4 v[156:159], v217, s[30:31]
	global_load_dwordx2 v[160:161], v218, s[30:31]
	v_mad_u32_u24 v217, v91, s52, v220
	v_add_u32_e32 v218, v217, v221
	global_load_dwordx4 v[162:165], v217, s[30:31]
	global_load_dwordx2 v[166:167], v218, s[30:31]
	v_mad_u32_u24 v217, v92, s52, v220
	v_add_u32_e32 v218, v217, v221
	global_load_dwordx4 v[168:171], v217, s[30:31]
	global_load_dwordx2 v[172:173], v218, s[30:31]
	v_mad_u32_u24 v217, v93, s52, v220
	v_add_u32_e32 v218, v217, v221
	global_load_dwordx4 v[174:177], v217, s[30:31]
	global_load_dwordx2 v[178:179], v218, s[30:31]
	v_mad_u32_u24 v217, v94, s52, v220
	v_add_u32_e32 v218, v217, v221
	global_load_dwordx4 v[180:183], v217, s[30:31]
	global_load_dwordx2 v[184:185], v218, s[30:31]
	v_mad_u32_u24 v217, v95, s52, v220
	v_add_u32_e32 v218, v217, v221
	global_load_dwordx4 v[186:189], v217, s[30:31]
	global_load_dwordx2 v[190:191], v218, s[30:31]
	global_load_dword v219, v231, s[28:29]
	s_add_i32 s53, s7, 1
	s_mov_b32 s54, s8
	s_cmp_eq_u32 s53, 8
	s_cselect_b32 s53, 0, s53
	s_cselect_b32 s34, 1, 0
	s_add_i32 s54, s54, s34
	s_mul_i32 s55, s53, s5
	s_add_i32 s55, s55, s6
	s_min_u32 s55, s55, 0x3fff
	s_and_b32 s34, s54, 7
	s_mul_i32 s34, s34, 0x300000
	s_cmp_lt_u32 s54, 8
	s_cselect_b32 s30, s16, s18
	s_cselect_b32 s31, s17, s19
	s_add_u32 s30, s30, s34
	s_addc_u32 s31, s31, 0
	s_and_b32 s34, s54, 7
	s_lshl_b32 s34, s34, 6
	s_lshl_b32 s35, s55, 12
	s_add_u32 s34, s34, s35
	s_add_u32 s32, s24, s34
	s_addc_u32 s33, s25, 0
	s_and_b32 s34, s54, 7
	s_lshl_b32 s34, s34, 7
	s_lshr_b32 s35, s55, 13
	s_mul_i32 s35, s35, 0xc000
	s_add_u32 s35, s35, s34
	s_add_u32 s35, s35, 0xa000
	s_add_u32 s58, s26, s35
	s_addc_u32 s59, s27, 0
	s_lshl_b32 s35, s55, 13
	s_add_u32 s35, s35, s34
	s_add_u32 s60, s28, s35
	s_addc_u32 s61, s29, 0
	s_mul_i32 s34, s53, s5
	s_add_i32 s34, s34, s6
	s_cmp_lt_u32 s34, 0x4000
	s_cselect_b32 s57, 1, 0
	s_lshl_b32 s34, s53, 9
	v_add_u32_e32 v216, s34, v223
	ds_read_b128 v[80:83], v216 offset:0
	ds_read_b128 v[84:87], v216 offset:16
	ds_read_b128 v[88:91], v216 offset:32
	ds_read_b128 v[92:95], v216 offset:48
.Lex_vloop:
	s_lshl_b32 s34, s7, 9
	v_add_u32_e32 v219, s34, v229
	ds_read_b128 v[192:195], v219 offset:0
	ds_read_b128 v[196:199], v219 offset:16
	ds_read_b128 v[200:203], v219 offset:32
	ds_read_b128 v[204:207], v219 offset:48
	s_waitcnt vmcnt(33)
	v_mov_b32_e32 v72, v64
	v_mov_b32_e32 v73, v65
	v_mov_b32_e32 v74, v66
	v_mov_b32_e32 v75, v67
	v_mov_b32_e32 v76, v68
	v_mov_b32_e32 v77, v69
	s_waitcnt lgkmcnt(0)
	s_waitcnt vmcnt(31)
	v_cvt_scalef32_pk32_f32_fp6 v[0:31], v[96:101], 1.0
	v_pk_mul_f32 v[32:33], v[192:193], v[0:1] op_sel_hi:[0,1]
	v_pk_mul_f32 v[34:35], v[192:193], v[2:3] op_sel_hi:[0,1]
	v_pk_mul_f32 v[36:37], v[192:193], v[4:5] op_sel_hi:[0,1]
	v_pk_mul_f32 v[38:39], v[192:193], v[6:7] op_sel_hi:[0,1]
	v_pk_mul_f32 v[40:41], v[192:193], v[8:9] op_sel_hi:[0,1]
	v_pk_mul_f32 v[42:43], v[192:193], v[10:11] op_sel_hi:[0,1]
	v_pk_mul_f32 v[44:45], v[192:193], v[12:13] op_sel_hi:[0,1]
	v_pk_mul_f32 v[46:47], v[192:193], v[14:15] op_sel_hi:[0,1]
	v_pk_mul_f32 v[48:49], v[192:193], v[16:17] op_sel_hi:[0,1]
	v_pk_mul_f32 v[50:51], v[192:193], v[18:19] op_sel_hi:[0,1]
	v_pk_mul_f32 v[52:53], v[192:193], v[20:21] op_sel_hi:[0,1]
	v_pk_mul_f32 v[54:55], v[192:193], v[22:23] op_sel_hi:[0,1]
	v_pk_mul_f32 v[56:57], v[192:193], v[24:25] op_sel_hi:[0,1]
	v_pk_mul_f32 v[58:59], v[192:193], v[26:27] op_sel_hi:[0,1]
	v_pk_mul_f32 v[60:61], v[192:193], v[28:29] op_sel_hi:[0,1]
	v_pk_mul_f32 v[62:63], v[192:193], v[30:31] op_sel_hi:[0,1]
	global_load_dwordx2 v[64:65], v225, s[32:33]
	global_load_dwordx4 v[66:69], v226, s[58:59]
	v_mad_u32_u24 v217, v80, s52, v220
	v_add_u32_e32 v218, v217, v221
	global_load_dwordx4 v[96:99], v217, s[30:31]
	global_load_dwordx2 v[100:101], v218, s[30:31]
	s_waitcnt vmcnt(33)
	v_cvt_scalef32_pk32_f32_fp6 v[0:31], v[102:107], 1.0
	v_pk_fma_f32 v[32:33], v[192:193], v[0:1], v[32:33] op_sel:[1,0,0] op_sel_hi:[1,1,1]
	v_pk_fma_f32 v[34:35], v[192:193], v[2:3], v[34:35] op_sel:[1,0,0] op_sel_hi:[1,1,1]
	v_pk_fma_f32 v[36:37], v[192:193], v[4:5], v[36:37] op_sel:[1,0,0] op_sel_hi:[1,1,1]
	v_pk_fma_f32 v[38:39], v[192:193], v[6:7], v[38:39] op_sel:[1,0,0] op_sel_hi:[1,1,1]
	v_pk_fma_f32 v[40:41], v[192:193], v[8:9], v[40:41] op_sel:[1,0,0] op_sel_hi:[1,1,1]
	v_pk_fma_f32 v[42:43], v[192:193], v[10:11], v[42:43] op_sel:[1,0,0] op_sel_hi:[1,1,1]
	v_pk_fma_f32 v[44:45], v[192:193], v[12:13], v[44:45] op_sel:[1,0,0] op_sel_hi:[1,1,1]
	v_pk_fma_f32 v[46:47], v[192:193], v[14:15], v[46:47] op_sel:[1,0,0] op_sel_hi:[1,1,1]
	v_pk_fma_f32 v[48:49], v[192:193], v[16:17], v[48:49] op_sel:[1,0,0] op_sel_hi:[1,1,1]
	v_pk_fma_f32 v[50:51], v[192:193], v[18:19], v[50:51] op_sel:[1,0,0] op_sel_hi:[1,1,1]
	v_pk_fma_f32 v[52:53], v[192:193], v[20:21], v[52:53] op_sel:[1,0,0] op_sel_hi:[1,1,1]
	v_pk_fma_f32 v[54:55], v[192:193], v[22:23], v[54:55] op_sel:[1,0,0] op_sel_hi:[1,1,1]
	v_pk_fma_f32 v[56:57], v[192:193], v[24:25], v[56:57] op_sel:[1,0,0] op_sel_hi:[1,1,1]
	v_pk_fma_f32 v[58:59], v[192:193], v[26:27], v[58:59] op_sel:[1,0,0] op_sel_hi:[1,1,1]
	v_pk_fma_f32 v[60:61], v[192:193], v[28:29], v[60:61] op_sel:[1,0,0] op_sel_hi:[1,1,1]
	v_pk_fma_f32 v[62:63], v[192:193], v[30:31], v[62:63] op_sel:[1,0,0] op_sel_hi:[1,1,1]
	v_mad_u32_u24 v217, v81, s52, v220
	v_add_u32_e32 v218, v217, v221
	global_load_dwordx4 v[102:105], v217, s[30:31]
	global_load_dwordx2 v[106:107], v218, s[30:31]
	s_waitcnt vmcnt(33)
	v_cvt_scalef32_pk32_f32_fp6 v[0:31], v[108:113], 1.0
	v_pk_fma_f32 v[32:33], v[194:195], v[0:1], v[32:33] op_sel_hi:[0,1,1]
	v_pk_fma_f32 v[34:35], v[194:195], v[2:3], v[34:35] op_sel_hi:[0,1,1]
	v_pk_fma_f32 v[36:37], v[194:195], v[4:5], v[36:37] op_sel_hi:[0,1,1]
	v_pk_fma_f32 v[38:39], v[194:195], v[6:7], v[38:39] op_sel_hi:[0,1,1]
	v_pk_fma_f32 v[40:41], v[194:195], v[8:9], v[40:41] op_sel_hi:[0,1,1]
	v_pk_fma_f32 v[42:43], v[194:195], v[10:11], v[42:43] op_sel_hi:[0,1,1]
	v_pk_fma_f32 v[44:45], v[194:195], v[12:13], v[44:45] op_sel_hi:[0,1,1]
	v_pk_fma_f32 v[46:47], v[194:195], v[14:15], v[46:47] op_sel_hi:[0,1,1]
	v_pk_fma_f32 v[48:49], v[194:195], v[16:17], v[48:49] op_sel_hi:[0,1,1]
	v_pk_fma_f32 v[50:51], v[194:195], v[18:19], v[50:51] op_sel_hi:[0,1,1]
	v_pk_fma_f32 v[52:53], v[194:195], v[20:21], v[52:53] op_sel_hi:[0,1,1]
	v_pk_fma_f32 v[54:55], v[194:195], v[22:23], v[54:55] op_sel_hi:[0,1,1]
	v_pk_fma_f32 v[56:57], v[194:195], v[24:25], v[56:57] op_sel_hi:[0,1,1]
	v_pk_fma_f32 v[58:59], v[194:195], v[26:27], v[58:59] op_sel_hi:[0,1,1]
	v_pk_fma_f32 v[60:61], v[194:195], v[28:29], v[60:61] op_sel_hi:[0,1,1]
	v_pk_fma_f32 v[62:63], v[194:195], v[30:31], v[62:63] op_sel_hi:[0,1,1]
	v_mad_u32_u24 v217, v82, s52, v220
	v_add_u32_e32 v218, v217, v221
	global_load_dwordx4 v[108:111], v217, s[30:31]
	global_load_dwordx2 v[112:113], v218, s[30:31]
	s_waitcnt vmcnt(33)
	v_cvt_scalef32_pk32_f32_fp6 v[0:31], v[114:119], 1.0
	v_pk_fma_f32 v[32:33], v[194:195], v[0:1], v[32:33] op_sel:[1,0,0] op_sel_hi:[1,1,1]
	v_pk_fma_f32 v[34:35], v[194:195], v[2:3], v[34:35] op_sel:[1,0,0] op_sel_hi:[1,1,1]
	v_pk_fma_f32 v[36:37], v[194:195], v[4:5], v[36:37] op_sel:[1,0,0] op_sel_hi:[1,1,1]
	v_pk_fma_f32 v[38:39], v[194:195], v[6:7], v[38:39] op_sel:[1,0,0] op_sel_hi:[1,1,1]
	v_pk_fma_f32 v[40:41], v[194:195], v[8:9], v[40:41] op_sel:[1,0,0] op_sel_hi:[1,1,1]
	v_pk_fma_f32 v[42:43], v[194:195], v[10:11], v[42:43] op_sel:[1,0,0] op_sel_hi:[1,1,1]
	v_pk_fma_f32 v[44:45], v[194:195], v[12:13], v[44:45] op_sel:[1,0,0] op_sel_hi:[1,1,1]
	v_pk_fma_f32 v[46:47], v[194:195], v[14:15], v[46:47] op_sel:[1,0,0] op_sel_hi:[1,1,1]
	v_pk_fma_f32 v[48:49], v[194:195], v[16:17], v[48:49] op_sel:[1,0,0] op_sel_hi:[1,1,1]
	v_pk_fma_f32 v[50:51], v[194:195], v[18:19], v[50:51] op_sel:[1,0,0] op_sel_hi:[1,1,1]
	v_pk_fma_f32 v[52:53], v[194:195], v[20:21], v[52:53] op_sel:[1,0,0] op_sel_hi:[1,1,1]
	v_pk_fma_f32 v[54:55], v[194:195], v[22:23], v[54:55] op_sel:[1,0,0] op_sel_hi:[1,1,1]
	v_pk_fma_f32 v[56:57], v[194:195], v[24:25], v[56:57] op_sel:[1,0,0] op_sel_hi:[1,1,1]
	v_pk_fma_f32 v[58:59], v[194:195], v[26:27], v[58:59] op_sel:[1,0,0] op_sel_hi:[1,1,1]
	v_pk_fma_f32 v[60:61], v[194:195], v[28:29], v[60:61] op_sel:[1,0,0] op_sel_hi:[1,1,1]
	v_pk_fma_f32 v[62:63], v[194:195], v[30:31], v[62:63] op_sel:[1,0,0] op_sel_hi:[1,1,1]
	v_mad_u32_u24 v217, v83, s52, v220
	v_add_u32_e32 v218, v217, v221
	global_load_dwordx4 v[114:117], v217, s[30:31]
	global_load_dwordx2 v[118:119], v218, s[30:31]
	s_waitcnt vmcnt(33)
	v_cvt_scalef32_pk32_f32_fp6 v[0:31], v[120:125], 1.0
	v_pk_fma_f32 v[32:33], v[196:197], v[0:1], v[32:33] op_sel_hi:[0,1,1]
	v_pk_fma_f32 v[34:35], v[196:197], v[2:3], v[34:35] op_sel_hi:[0,1,1]
	v_pk_fma_f32 v[36:37], v[196:197], v[4:5], v[36:37] op_sel_hi:[0,1,1]
	v_pk_fma_f32 v[38:39], v[196:197], v[6:7], v[38:39] op_sel_hi:[0,1,1]
	v_pk_fma_f32 v[40:41], v[196:197], v[8:9], v[40:41] op_sel_hi:[0,1,1]
	v_pk_fma_f32 v[42:43], v[196:197], v[10:11], v[42:43] op_sel_hi:[0,1,1]
	v_pk_fma_f32 v[44:45], v[196:197], v[12:13], v[44:45] op_sel_hi:[0,1,1]
	v_pk_fma_f32 v[46:47], v[196:197], v[14:15], v[46:47] op_sel_hi:[0,1,1]
	v_pk_fma_f32 v[48:49], v[196:197], v[16:17], v[48:49] op_sel_hi:[0,1,1]
	v_pk_fma_f32 v[50:51], v[196:197], v[18:19], v[50:51] op_sel_hi:[0,1,1]
	v_pk_fma_f32 v[52:53], v[196:197], v[20:21], v[52:53] op_sel_hi:[0,1,1]
	v_pk_fma_f32 v[54:55], v[196:197], v[22:23], v[54:55] op_sel_hi:[0,1,1]
	v_pk_fma_f32 v[56:57], v[196:197], v[24:25], v[56:57] op_sel_hi:[0,1,1]
	v_pk_fma_f32 v[58:59], v[196:197], v[26:27], v[58:59] op_sel_hi:[0,1,1]
	v_pk_fma_f32 v[60:61], v[196:197], v[28:29], v[60:61] op_sel_hi:[0,1,1]
	v_pk_fma_f32 v[62:63], v[196:197], v[30:31], v[62:63] op_sel_hi:[0,1,1]
	v_mad_u32_u24 v217, v84, s52, v220
	v_add_u32_e32 v218, v217, v221
	global_load_dwordx4 v[120:123], v217, s[30:31]
	global_load_dwordx2 v[124:125], v218, s[30:31]
	s_waitcnt vmcnt(33)
	v_cvt_scalef32_pk32_f32_fp6 v[0:31], v[126:131], 1.0
	v_pk_fma_f32 v[32:33], v[196:197], v[0:1], v[32:33] op_sel:[1,0,0] op_sel_hi:[1,1,1]
	v_pk_fma_f32 v[34:35], v[196:197], v[2:3], v[34:35] op_sel:[1,0,0] op_sel_hi:[1,1,1]
	v_pk_fma_f32 v[36:37], v[196:197], v[4:5], v[36:37] op_sel:[1,0,0] op_sel_hi:[1,1,1]
	v_pk_fma_f32 v[38:39], v[196:197], v[6:7], v[38:39] op_sel:[1,0,0] op_sel_hi:[1,1,1]
	v_pk_fma_f32 v[40:41], v[196:197], v[8:9], v[40:41] op_sel:[1,0,0] op_sel_hi:[1,1,1]
	v_pk_fma_f32 v[42:43], v[196:197], v[10:11], v[42:43] op_sel:[1,0,0] op_sel_hi:[1,1,1]
	v_pk_fma_f32 v[44:45], v[196:197], v[12:13], v[44:45] op_sel:[1,0,0] op_sel_hi:[1,1,1]
	v_pk_fma_f32 v[46:47], v[196:197], v[14:15], v[46:47] op_sel:[1,0,0] op_sel_hi:[1,1,1]
	v_pk_fma_f32 v[48:49], v[196:197], v[16:17], v[48:49] op_sel:[1,0,0] op_sel_hi:[1,1,1]
	v_pk_fma_f32 v[50:51], v[196:197], v[18:19], v[50:51] op_sel:[1,0,0] op_sel_hi:[1,1,1]
	v_pk_fma_f32 v[52:53], v[196:197], v[20:21], v[52:53] op_sel:[1,0,0] op_sel_hi:[1,1,1]
	v_pk_fma_f32 v[54:55], v[196:197], v[22:23], v[54:55] op_sel:[1,0,0] op_sel_hi:[1,1,1]
	v_pk_fma_f32 v[56:57], v[196:197], v[24:25], v[56:57] op_sel:[1,0,0] op_sel_hi:[1,1,1]
	v_pk_fma_f32 v[58:59], v[196:197], v[26:27], v[58:59] op_sel:[1,0,0] op_sel_hi:[1,1,1]
	v_pk_fma_f32 v[60:61], v[196:197], v[28:29], v[60:61] op_sel:[1,0,0] op_sel_hi:[1,1,1]
	v_pk_fma_f32 v[62:63], v[196:197], v[30:31], v[62:63] op_sel:[1,0,0] op_sel_hi:[1,1,1]
	v_mad_u32_u24 v217, v85, s52, v220
	v_add_u32_e32 v218, v217, v221
	global_load_dwordx4 v[126:129], v217, s[30:31]
	global_load_dwordx2 v[130:131], v218, s[30:31]
	s_waitcnt vmcnt(33)
	v_cvt_scalef32_pk32_f32_fp6 v[0:31], v[132:137], 1.0
	v_pk_fma_f32 v[32:33], v[198:199], v[0:1], v[32:33] op_sel_hi:[0,1,1]
	v_pk_fma_f32 v[34:35], v[198:199], v[2:3], v[34:35] op_sel_hi:[0,1,1]
	v_pk_fma_f32 v[36:37], v[198:199], v[4:5], v[36:37] op_sel_hi:[0,1,1]
	v_pk_fma_f32 v[38:39], v[198:199], v[6:7], v[38:39] op_sel_hi:[0,1,1]
	v_pk_fma_f32 v[40:41], v[198:199], v[8:9], v[40:41] op_sel_hi:[0,1,1]
	v_pk_fma_f32 v[42:43], v[198:199], v[10:11], v[42:43] op_sel_hi:[0,1,1]
	v_pk_fma_f32 v[44:45], v[198:199], v[12:13], v[44:45] op_sel_hi:[0,1,1]
	v_pk_fma_f32 v[46:47], v[198:199], v[14:15], v[46:47] op_sel_hi:[0,1,1]
	v_pk_fma_f32 v[48:49], v[198:199], v[16:17], v[48:49] op_sel_hi:[0,1,1]
	v_pk_fma_f32 v[50:51], v[198:199], v[18:19], v[50:51] op_sel_hi:[0,1,1]
	v_pk_fma_f32 v[52:53], v[198:199], v[20:21], v[52:53] op_sel_hi:[0,1,1]
	v_pk_fma_f32 v[54:55], v[198:199], v[22:23], v[54:55] op_sel_hi:[0,1,1]
	v_pk_fma_f32 v[56:57], v[198:199], v[24:25], v[56:57] op_sel_hi:[0,1,1]
	v_pk_fma_f32 v[58:59], v[198:199], v[26:27], v[58:59] op_sel_hi:[0,1,1]
	v_pk_fma_f32 v[60:61], v[198:199], v[28:29], v[60:61] op_sel_hi:[0,1,1]
	v_pk_fma_f32 v[62:63], v[198:199], v[30:31], v[62:63] op_sel_hi:[0,1,1]
	v_mad_u32_u24 v217, v86, s52, v220
	v_add_u32_e32 v218, v217, v221
	global_load_dwordx4 v[132:135], v217, s[30:31]
	global_load_dwordx2 v[136:137], v218, s[30:31]
	s_waitcnt vmcnt(33)
	v_cvt_scalef32_pk32_f32_fp6 v[0:31], v[138:143], 1.0
	v_pk_fma_f32 v[32:33], v[198:199], v[0:1], v[32:33] op_sel:[1,0,0] op_sel_hi:[1,1,1]
	v_pk_fma_f32 v[34:35], v[198:199], v[2:3], v[34:35] op_sel:[1,0,0] op_sel_hi:[1,1,1]
	v_pk_fma_f32 v[36:37], v[198:199], v[4:5], v[36:37] op_sel:[1,0,0] op_sel_hi:[1,1,1]
	v_pk_fma_f32 v[38:39], v[198:199], v[6:7], v[38:39] op_sel:[1,0,0] op_sel_hi:[1,1,1]
	v_pk_fma_f32 v[40:41], v[198:199], v[8:9], v[40:41] op_sel:[1,0,0] op_sel_hi:[1,1,1]
	v_pk_fma_f32 v[42:43], v[198:199], v[10:11], v[42:43] op_sel:[1,0,0] op_sel_hi:[1,1,1]
	v_pk_fma_f32 v[44:45], v[198:199], v[12:13], v[44:45] op_sel:[1,0,0] op_sel_hi:[1,1,1]
	v_pk_fma_f32 v[46:47], v[198:199], v[14:15], v[46:47] op_sel:[1,0,0] op_sel_hi:[1,1,1]
	v_pk_fma_f32 v[48:49], v[198:199], v[16:17], v[48:49] op_sel:[1,0,0] op_sel_hi:[1,1,1]
	v_pk_fma_f32 v[50:51], v[198:199], v[18:19], v[50:51] op_sel:[1,0,0] op_sel_hi:[1,1,1]
	v_pk_fma_f32 v[52:53], v[198:199], v[20:21], v[52:53] op_sel:[1,0,0] op_sel_hi:[1,1,1]
	v_pk_fma_f32 v[54:55], v[198:199], v[22:23], v[54:55] op_sel:[1,0,0] op_sel_hi:[1,1,1]
	v_pk_fma_f32 v[56:57], v[198:199], v[24:25], v[56:57] op_sel:[1,0,0] op_sel_hi:[1,1,1]
	v_pk_fma_f32 v[58:59], v[198:199], v[26:27], v[58:59] op_sel:[1,0,0] op_sel_hi:[1,1,1]
	v_pk_fma_f32 v[60:61], v[198:199], v[28:29], v[60:61] op_sel:[1,0,0] op_sel_hi:[1,1,1]
	v_pk_fma_f32 v[62:63], v[198:199], v[30:31], v[62:63] op_sel:[1,0,0] op_sel_hi:[1,1,1]
	v_mad_u32_u24 v217, v87, s52, v220
	v_add_u32_e32 v218, v217, v221
	global_load_dwordx4 v[138:141], v217, s[30:31]
	global_load_dwordx2 v[142:143], v218, s[30:31]
	s_waitcnt vmcnt(33)
	v_cvt_scalef32_pk32_f32_fp6 v[0:31], v[144:149], 1.0
	v_pk_fma_f32 v[32:33], v[200:201], v[0:1], v[32:33] op_sel_hi:[0,1,1]
	v_pk_fma_f32 v[34:35], v[200:201], v[2:3], v[34:35] op_sel_hi:[0,1,1]
	v_pk_fma_f32 v[36:37], v[200:201], v[4:5], v[36:37] op_sel_hi:[0,1,1]
	v_pk_fma_f32 v[38:39], v[200:201], v[6:7], v[38:39] op_sel_hi:[0,1,1]
	v_pk_fma_f32 v[40:41], v[200:201], v[8:9], v[40:41] op_sel_hi:[0,1,1]
	v_pk_fma_f32 v[42:43], v[200:201], v[10:11], v[42:43] op_sel_hi:[0,1,1]
	v_pk_fma_f32 v[44:45], v[200:201], v[12:13], v[44:45] op_sel_hi:[0,1,1]
	v_pk_fma_f32 v[46:47], v[200:201], v[14:15], v[46:47] op_sel_hi:[0,1,1]
	v_pk_fma_f32 v[48:49], v[200:201], v[16:17], v[48:49] op_sel_hi:[0,1,1]
	v_pk_fma_f32 v[50:51], v[200:201], v[18:19], v[50:51] op_sel_hi:[0,1,1]
	v_pk_fma_f32 v[52:53], v[200:201], v[20:21], v[52:53] op_sel_hi:[0,1,1]
	v_pk_fma_f32 v[54:55], v[200:201], v[22:23], v[54:55] op_sel_hi:[0,1,1]
	v_pk_fma_f32 v[56:57], v[200:201], v[24:25], v[56:57] op_sel_hi:[0,1,1]
	v_pk_fma_f32 v[58:59], v[200:201], v[26:27], v[58:59] op_sel_hi:[0,1,1]
	v_pk_fma_f32 v[60:61], v[200:201], v[28:29], v[60:61] op_sel_hi:[0,1,1]
	v_pk_fma_f32 v[62:63], v[200:201], v[30:31], v[62:63] op_sel_hi:[0,1,1]
	v_mad_u32_u24 v217, v88, s52, v220
	v_add_u32_e32 v218, v217, v221
	global_load_dwordx4 v[144:147], v217, s[30:31]
	global_load_dwordx2 v[148:149], v218, s[30:31]
	s_waitcnt vmcnt(33)
	v_cvt_scalef32_pk32_f32_fp6 v[0:31], v[150:155], 1.0
	v_pk_fma_f32 v[32:33], v[200:201], v[0:1], v[32:33] op_sel:[1,0,0] op_sel_hi:[1,1,1]
	v_pk_fma_f32 v[34:35], v[200:201], v[2:3], v[34:35] op_sel:[1,0,0] op_sel_hi:[1,1,1]
	v_pk_fma_f32 v[36:37], v[200:201], v[4:5], v[36:37] op_sel:[1,0,0] op_sel_hi:[1,1,1]
	v_pk_fma_f32 v[38:39], v[200:201], v[6:7], v[38:39] op_sel:[1,0,0] op_sel_hi:[1,1,1]
	v_pk_fma_f32 v[40:41], v[200:201], v[8:9], v[40:41] op_sel:[1,0,0] op_sel_hi:[1,1,1]
	v_pk_fma_f32 v[42:43], v[200:201], v[10:11], v[42:43] op_sel:[1,0,0] op_sel_hi:[1,1,1]
	v_pk_fma_f32 v[44:45], v[200:201], v[12:13], v[44:45] op_sel:[1,0,0] op_sel_hi:[1,1,1]
	v_pk_fma_f32 v[46:47], v[200:201], v[14:15], v[46:47] op_sel:[1,0,0] op_sel_hi:[1,1,1]
	v_pk_fma_f32 v[48:49], v[200:201], v[16:17], v[48:49] op_sel:[1,0,0] op_sel_hi:[1,1,1]
	v_pk_fma_f32 v[50:51], v[200:201], v[18:19], v[50:51] op_sel:[1,0,0] op_sel_hi:[1,1,1]
	v_pk_fma_f32 v[52:53], v[200:201], v[20:21], v[52:53] op_sel:[1,0,0] op_sel_hi:[1,1,1]
	v_pk_fma_f32 v[54:55], v[200:201], v[22:23], v[54:55] op_sel:[1,0,0] op_sel_hi:[1,1,1]
	v_pk_fma_f32 v[56:57], v[200:201], v[24:25], v[56:57] op_sel:[1,0,0] op_sel_hi:[1,1,1]
	v_pk_fma_f32 v[58:59], v[200:201], v[26:27], v[58:59] op_sel:[1,0,0] op_sel_hi:[1,1,1]
	v_pk_fma_f32 v[60:61], v[200:201], v[28:29], v[60:61] op_sel:[1,0,0] op_sel_hi:[1,1,1]
	v_pk_fma_f32 v[62:63], v[200:201], v[30:31], v[62:63] op_sel:[1,0,0] op_sel_hi:[1,1,1]
	v_mad_u32_u24 v217, v89, s52, v220
	v_add_u32_e32 v218, v217, v221
	global_load_dwordx4 v[150:153], v217, s[30:31]
	global_load_dwordx2 v[154:155], v218, s[30:31]
	s_waitcnt vmcnt(33)
	v_cvt_scalef32_pk32_f32_fp6 v[0:31], v[156:161], 1.0
	v_pk_fma_f32 v[32:33], v[202:203], v[0:1], v[32:33] op_sel_hi:[0,1,1]
	v_pk_fma_f32 v[34:35], v[202:203], v[2:3], v[34:35] op_sel_hi:[0,1,1]
	v_pk_fma_f32 v[36:37], v[202:203], v[4:5], v[36:37] op_sel_hi:[0,1,1]
	v_pk_fma_f32 v[38:39], v[202:203], v[6:7], v[38:39] op_sel_hi:[0,1,1]
	v_pk_fma_f32 v[40:41], v[202:203], v[8:9], v[40:41] op_sel_hi:[0,1,1]
	v_pk_fma_f32 v[42:43], v[202:203], v[10:11], v[42:43] op_sel_hi:[0,1,1]
	v_pk_fma_f32 v[44:45], v[202:203], v[12:13], v[44:45] op_sel_hi:[0,1,1]
	v_pk_fma_f32 v[46:47], v[202:203], v[14:15], v[46:47] op_sel_hi:[0,1,1]
	v_pk_fma_f32 v[48:49], v[202:203], v[16:17], v[48:49] op_sel_hi:[0,1,1]
	v_pk_fma_f32 v[50:51], v[202:203], v[18:19], v[50:51] op_sel_hi:[0,1,1]
	v_pk_fma_f32 v[52:53], v[202:203], v[20:21], v[52:53] op_sel_hi:[0,1,1]
	v_pk_fma_f32 v[54:55], v[202:203], v[22:23], v[54:55] op_sel_hi:[0,1,1]
	v_pk_fma_f32 v[56:57], v[202:203], v[24:25], v[56:57] op_sel_hi:[0,1,1]
	v_pk_fma_f32 v[58:59], v[202:203], v[26:27], v[58:59] op_sel_hi:[0,1,1]
	v_pk_fma_f32 v[60:61], v[202:203], v[28:29], v[60:61] op_sel_hi:[0,1,1]
	v_pk_fma_f32 v[62:63], v[202:203], v[30:31], v[62:63] op_sel_hi:[0,1,1]
	v_mad_u32_u24 v217, v90, s52, v220
	v_add_u32_e32 v218, v217, v221
	global_load_dwordx4 v[156:159], v217, s[30:31]
	global_load_dwordx2 v[160:161], v218, s[30:31]
	s_waitcnt vmcnt(33)
	v_cvt_scalef32_pk32_f32_fp6 v[0:31], v[162:167], 1.0
	v_pk_fma_f32 v[32:33], v[202:203], v[0:1], v[32:33] op_sel:[1,0,0] op_sel_hi:[1,1,1]
	v_pk_fma_f32 v[34:35], v[202:203], v[2:3], v[34:35] op_sel:[1,0,0] op_sel_hi:[1,1,1]
	v_pk_fma_f32 v[36:37], v[202:203], v[4:5], v[36:37] op_sel:[1,0,0] op_sel_hi:[1,1,1]
	v_pk_fma_f32 v[38:39], v[202:203], v[6:7], v[38:39] op_sel:[1,0,0] op_sel_hi:[1,1,1]
	v_pk_fma_f32 v[40:41], v[202:203], v[8:9], v[40:41] op_sel:[1,0,0] op_sel_hi:[1,1,1]
	v_pk_fma_f32 v[42:43], v[202:203], v[10:11], v[42:43] op_sel:[1,0,0] op_sel_hi:[1,1,1]
	v_pk_fma_f32 v[44:45], v[202:203], v[12:13], v[44:45] op_sel:[1,0,0] op_sel_hi:[1,1,1]
	v_pk_fma_f32 v[46:47], v[202:203], v[14:15], v[46:47] op_sel:[1,0,0] op_sel_hi:[1,1,1]
	v_pk_fma_f32 v[48:49], v[202:203], v[16:17], v[48:49] op_sel:[1,0,0] op_sel_hi:[1,1,1]
	v_pk_fma_f32 v[50:51], v[202:203], v[18:19], v[50:51] op_sel:[1,0,0] op_sel_hi:[1,1,1]
	v_pk_fma_f32 v[52:53], v[202:203], v[20:21], v[52:53] op_sel:[1,0,0] op_sel_hi:[1,1,1]
	v_pk_fma_f32 v[54:55], v[202:203], v[22:23], v[54:55] op_sel:[1,0,0] op_sel_hi:[1,1,1]
	v_pk_fma_f32 v[56:57], v[202:203], v[24:25], v[56:57] op_sel:[1,0,0] op_sel_hi:[1,1,1]
	v_pk_fma_f32 v[58:59], v[202:203], v[26:27], v[58:59] op_sel:[1,0,0] op_sel_hi:[1,1,1]
	v_pk_fma_f32 v[60:61], v[202:203], v[28:29], v[60:61] op_sel:[1,0,0] op_sel_hi:[1,1,1]
	v_pk_fma_f32 v[62:63], v[202:203], v[30:31], v[62:63] op_sel:[1,0,0] op_sel_hi:[1,1,1]
	v_mad_u32_u24 v217, v91, s52, v220
	v_add_u32_e32 v218, v217, v221
	global_load_dwordx4 v[162:165], v217, s[30:31]
	global_load_dwordx2 v[166:167], v218, s[30:31]
	s_waitcnt vmcnt(33)
	v_cvt_scalef32_pk32_f32_fp6 v[0:31], v[168:173], 1.0
	v_pk_fma_f32 v[32:33], v[204:205], v[0:1], v[32:33] op_sel_hi:[0,1,1]
	v_pk_fma_f32 v[34:35], v[204:205], v[2:3], v[34:35] op_sel_hi:[0,1,1]
	v_pk_fma_f32 v[36:37], v[204:205], v[4:5], v[36:37] op_sel_hi:[0,1,1]
	v_pk_fma_f32 v[38:39], v[204:205], v[6:7], v[38:39] op_sel_hi:[0,1,1]
	v_pk_fma_f32 v[40:41], v[204:205], v[8:9], v[40:41] op_sel_hi:[0,1,1]
	v_pk_fma_f32 v[42:43], v[204:205], v[10:11], v[42:43] op_sel_hi:[0,1,1]
	v_pk_fma_f32 v[44:45], v[204:205], v[12:13], v[44:45] op_sel_hi:[0,1,1]
	v_pk_fma_f32 v[46:47], v[204:205], v[14:15], v[46:47] op_sel_hi:[0,1,1]
	v_pk_fma_f32 v[48:49], v[204:205], v[16:17], v[48:49] op_sel_hi:[0,1,1]
	v_pk_fma_f32 v[50:51], v[204:205], v[18:19], v[50:51] op_sel_hi:[0,1,1]
	v_pk_fma_f32 v[52:53], v[204:205], v[20:21], v[52:53] op_sel_hi:[0,1,1]
	v_pk_fma_f32 v[54:55], v[204:205], v[22:23], v[54:55] op_sel_hi:[0,1,1]
	v_pk_fma_f32 v[56:57], v[204:205], v[24:25], v[56:57] op_sel_hi:[0,1,1]
	v_pk_fma_f32 v[58:59], v[204:205], v[26:27], v[58:59] op_sel_hi:[0,1,1]
	v_pk_fma_f32 v[60:61], v[204:205], v[28:29], v[60:61] op_sel_hi:[0,1,1]
	v_pk_fma_f32 v[62:63], v[204:205], v[30:31], v[62:63] op_sel_hi:[0,1,1]
	v_mad_u32_u24 v217, v92, s52, v220
	v_add_u32_e32 v218, v217, v221
	global_load_dwordx4 v[168:171], v217, s[30:31]
	global_load_dwordx2 v[172:173], v218, s[30:31]
	s_waitcnt vmcnt(33)
	v_cvt_scalef32_pk32_f32_fp6 v[0:31], v[174:179], 1.0
	v_pk_fma_f32 v[32:33], v[204:205], v[0:1], v[32:33] op_sel:[1,0,0] op_sel_hi:[1,1,1]
	v_pk_fma_f32 v[34:35], v[204:205], v[2:3], v[34:35] op_sel:[1,0,0] op_sel_hi:[1,1,1]
	v_pk_fma_f32 v[36:37], v[204:205], v[4:5], v[36:37] op_sel:[1,0,0] op_sel_hi:[1,1,1]
	v_pk_fma_f32 v[38:39], v[204:205], v[6:7], v[38:39] op_sel:[1,0,0] op_sel_hi:[1,1,1]
	v_pk_fma_f32 v[40:41], v[204:205], v[8:9], v[40:41] op_sel:[1,0,0] op_sel_hi:[1,1,1]
	v_pk_fma_f32 v[42:43], v[204:205], v[10:11], v[42:43] op_sel:[1,0,0] op_sel_hi:[1,1,1]
	v_pk_fma_f32 v[44:45], v[204:205], v[12:13], v[44:45] op_sel:[1,0,0] op_sel_hi:[1,1,1]
	v_pk_fma_f32 v[46:47], v[204:205], v[14:15], v[46:47] op_sel:[1,0,0] op_sel_hi:[1,1,1]
	v_pk_fma_f32 v[48:49], v[204:205], v[16:17], v[48:49] op_sel:[1,0,0] op_sel_hi:[1,1,1]
	v_pk_fma_f32 v[50:51], v[204:205], v[18:19], v[50:51] op_sel:[1,0,0] op_sel_hi:[1,1,1]
	v_pk_fma_f32 v[52:53], v[204:205], v[20:21], v[52:53] op_sel:[1,0,0] op_sel_hi:[1,1,1]
	v_pk_fma_f32 v[54:55], v[204:205], v[22:23], v[54:55] op_sel:[1,0,0] op_sel_hi:[1,1,1]
	v_pk_fma_f32 v[56:57], v[204:205], v[24:25], v[56:57] op_sel:[1,0,0] op_sel_hi:[1,1,1]
	v_pk_fma_f32 v[58:59], v[204:205], v[26:27], v[58:59] op_sel:[1,0,0] op_sel_hi:[1,1,1]
	v_pk_fma_f32 v[60:61], v[204:205], v[28:29], v[60:61] op_sel:[1,0,0] op_sel_hi:[1,1,1]
	v_pk_fma_f32 v[62:63], v[204:205], v[30:31], v[62:63] op_sel:[1,0,0] op_sel_hi:[1,1,1]
	v_mad_u32_u24 v217, v93, s52, v220
	v_add_u32_e32 v218, v217, v221
	global_load_dwordx4 v[174:177], v217, s[30:31]
	global_load_dwordx2 v[178:179], v218, s[30:31]
	s_waitcnt vmcnt(33)
	v_cvt_scalef32_pk32_f32_fp6 v[0:31], v[180:185], 1.0
	v_pk_fma_f32 v[32:33], v[206:207], v[0:1], v[32:33] op_sel_hi:[0,1,1]
	v_pk_fma_f32 v[34:35], v[206:207], v[2:3], v[34:35] op_sel_hi:[0,1,1]
	v_pk_fma_f32 v[36:37], v[206:207], v[4:5], v[36:37] op_sel_hi:[0,1,1]
	v_pk_fma_f32 v[38:39], v[206:207], v[6:7], v[38:39] op_sel_hi:[0,1,1]
	v_pk_fma_f32 v[40:41], v[206:207], v[8:9], v[40:41] op_sel_hi:[0,1,1]
	v_pk_fma_f32 v[42:43], v[206:207], v[10:11], v[42:43] op_sel_hi:[0,1,1]
	v_pk_fma_f32 v[44:45], v[206:207], v[12:13], v[44:45] op_sel_hi:[0,1,1]
	v_pk_fma_f32 v[46:47], v[206:207], v[14:15], v[46:47] op_sel_hi:[0,1,1]
	v_pk_fma_f32 v[48:49], v[206:207], v[16:17], v[48:49] op_sel_hi:[0,1,1]
	v_pk_fma_f32 v[50:51], v[206:207], v[18:19], v[50:51] op_sel_hi:[0,1,1]
	v_pk_fma_f32 v[52:53], v[206:207], v[20:21], v[52:53] op_sel_hi:[0,1,1]
	v_pk_fma_f32 v[54:55], v[206:207], v[22:23], v[54:55] op_sel_hi:[0,1,1]
	v_pk_fma_f32 v[56:57], v[206:207], v[24:25], v[56:57] op_sel_hi:[0,1,1]
	v_pk_fma_f32 v[58:59], v[206:207], v[26:27], v[58:59] op_sel_hi:[0,1,1]
	v_pk_fma_f32 v[60:61], v[206:207], v[28:29], v[60:61] op_sel_hi:[0,1,1]
	v_pk_fma_f32 v[62:63], v[206:207], v[30:31], v[62:63] op_sel_hi:[0,1,1]
	v_mad_u32_u24 v217, v94, s52, v220
	v_add_u32_e32 v218, v217, v221
	global_load_dwordx4 v[180:183], v217, s[30:31]
	global_load_dwordx2 v[184:185], v218, s[30:31]
	s_waitcnt vmcnt(33)
	v_cvt_scalef32_pk32_f32_fp6 v[0:31], v[186:191], 1.0
	v_pk_fma_f32 v[32:33], v[206:207], v[0:1], v[32:33] op_sel:[1,0,0] op_sel_hi:[1,1,1]
	v_pk_fma_f32 v[34:35], v[206:207], v[2:3], v[34:35] op_sel:[1,0,0] op_sel_hi:[1,1,1]
	v_pk_fma_f32 v[36:37], v[206:207], v[4:5], v[36:37] op_sel:[1,0,0] op_sel_hi:[1,1,1]
	v_pk_fma_f32 v[38:39], v[206:207], v[6:7], v[38:39] op_sel:[1,0,0] op_sel_hi:[1,1,1]
	v_pk_fma_f32 v[40:41], v[206:207], v[8:9], v[40:41] op_sel:[1,0,0] op_sel_hi:[1,1,1]
	v_pk_fma_f32 v[42:43], v[206:207], v[10:11], v[42:43] op_sel:[1,0,0] op_sel_hi:[1,1,1]
	v_pk_fma_f32 v[44:45], v[206:207], v[12:13], v[44:45] op_sel:[1,0,0] op_sel_hi:[1,1,1]
	v_pk_fma_f32 v[46:47], v[206:207], v[14:15], v[46:47] op_sel:[1,0,0] op_sel_hi:[1,1,1]
	v_pk_fma_f32 v[48:49], v[206:207], v[16:17], v[48:49] op_sel:[1,0,0] op_sel_hi:[1,1,1]
	v_pk_fma_f32 v[50:51], v[206:207], v[18:19], v[50:51] op_sel:[1,0,0] op_sel_hi:[1,1,1]
	v_pk_fma_f32 v[52:53], v[206:207], v[20:21], v[52:53] op_sel:[1,0,0] op_sel_hi:[1,1,1]
	v_pk_fma_f32 v[54:55], v[206:207], v[22:23], v[54:55] op_sel:[1,0,0] op_sel_hi:[1,1,1]
	v_pk_fma_f32 v[56:57], v[206:207], v[24:25], v[56:57] op_sel:[1,0,0] op_sel_hi:[1,1,1]
	v_pk_fma_f32 v[58:59], v[206:207], v[26:27], v[58:59] op_sel:[1,0,0] op_sel_hi:[1,1,1]
	v_pk_fma_f32 v[60:61], v[206:207], v[28:29], v[60:61] op_sel:[1,0,0] op_sel_hi:[1,1,1]
	v_pk_fma_f32 v[62:63], v[206:207], v[30:31], v[62:63] op_sel:[1,0,0] op_sel_hi:[1,1,1]
	v_mad_u32_u24 v217, v95, s52, v220
	v_add_u32_e32 v218, v217, v221
	global_load_dwordx4 v[186:189], v217, s[30:31]
	global_load_dwordx2 v[190:191], v218, s[30:31]
	s_mov_b32 s86, s78
	s_mov_b32 s87, s79
	s_mov_b32 s88, s80
	s_mov_b32 s78, s60
	s_mov_b32 s79, s61
	s_mov_b32 s80, s57
	s_mov_b32 s7, s53
	s_mov_b32 s8, s54
	s_add_i32 s53, s7, 1
	s_mov_b32 s54, s8
	s_cmp_eq_u32 s53, 8
	s_cselect_b32 s53, 0, s53
	s_cselect_b32 s34, 1, 0
	s_add_i32 s54, s54, s34
	s_mul_i32 s55, s53, s5
	s_add_i32 s55, s55, s6
	s_min_u32 s55, s55, 0x3fff
	s_and_b32 s34, s54, 7
	s_mul_i32 s34, s34, 0x300000
	s_cmp_lt_u32 s54, 8
	s_cselect_b32 s30, s16, s18
	s_cselect_b32 s31, s17, s19
	s_add_u32 s30, s30, s34
	s_addc_u32 s31, s31, 0
	s_and_b32 s34, s54, 7
	s_lshl_b32 s34, s34, 6
	s_lshl_b32 s35, s55, 12
	s_add_u32 s34, s34, s35
	s_add_u32 s32, s24, s34
	s_addc_u32 s33, s25, 0
	s_and_b32 s34, s54, 7
	s_lshl_b32 s34, s34, 7
	s_lshr_b32 s35, s55, 13
	s_mul_i32 s35, s35, 0xc000
	s_add_u32 s35, s35, s34
	s_add_u32 s35, s35, 0xa000
	s_add_u32 s58, s26, s35
	s_addc_u32 s59, s27, 0
	s_lshl_b32 s35, s55, 13
	s_add_u32 s35, s35, s34
	s_add_u32 s60, s28, s35
	s_addc_u32 s61, s29, 0
	s_mul_i32 s34, s53, s5
	s_add_i32 s34, s34, s6
	s_cmp_lt_u32 s34, 0x4000
	s_cselect_b32 s57, 1, 0
	s_lshl_b32 s34, s53, 9
	v_add_u32_e32 v216, s34, v223
	ds_read_b128 v[80:83], v216 offset:0
	ds_read_b128 v[84:87], v216 offset:16
	ds_read_b128 v[88:91], v216 offset:32
	ds_read_b128 v[92:95], v216 offset:48
	v_cndmask_b32_e64 v212, v48, v32, s[46:47]
	v_cndmask_b32_e64 v213, v32, v48, s[46:47]
	v_cndmask_b32_e64 v214, v49, v33, s[46:47]
	v_cndmask_b32_e64 v215, v33, v49, s[46:47]
	v_add_f32_dpp v32, v212, v213 row_ror:8 row_mask:0xf bank_mask:0xf
	v_add_f32_dpp v33, v214, v215 row_ror:8 row_mask:0xf bank_mask:0xf
	v_cndmask_b32_e64 v212, v50, v34, s[46:47]
	v_cndmask_b32_e64 v213, v34, v50, s[46:47]
	v_cndmask_b32_e64 v214, v51, v35, s[46:47]
	v_cndmask_b32_e64 v215, v35, v51, s[46:47]
	v_add_f32_dpp v34, v212, v213 row_ror:8 row_mask:0xf bank_mask:0xf
	v_add_f32_dpp v35, v214, v215 row_ror:8 row_mask:0xf bank_mask:0xf
	v_cndmask_b32_e64 v212, v52, v36, s[46:47]
	v_cndmask_b32_e64 v213, v36, v52, s[46:47]
	v_cndmask_b32_e64 v214, v53, v37, s[46:47]
	v_cndmask_b32_e64 v215, v37, v53, s[46:47]
	v_add_f32_dpp v36, v212, v213 row_ror:8 row_mask:0xf bank_mask:0xf
	v_add_f32_dpp v37, v214, v215 row_ror:8 row_mask:0xf bank_mask:0xf
	v_cndmask_b32_e64 v212, v54, v38, s[46:47]
	v_cndmask_b32_e64 v213, v38, v54, s[46:47]
	v_cndmask_b32_e64 v214, v55, v39, s[46:47]
	v_cndmask_b32_e64 v215, v39, v55, s[46:47]
	v_add_f32_dpp v38, v212, v213 row_ror:8 row_mask:0xf bank_mask:0xf
	v_add_f32_dpp v39, v214, v215 row_ror:8 row_mask:0xf bank_mask:0xf
	v_cndmask_b32_e64 v212, v56, v40, s[46:47]
	v_cndmask_b32_e64 v213, v40, v56, s[46:47]
	v_cndmask_b32_e64 v214, v57, v41, s[46:47]
	v_cndmask_b32_e64 v215, v41, v57, s[46:47]
	v_add_f32_dpp v40, v212, v213 row_ror:8 row_mask:0xf bank_mask:0xf
	v_add_f32_dpp v41, v214, v215 row_ror:8 row_mask:0xf bank_mask:0xf
	v_cndmask_b32_e64 v212, v58, v42, s[46:47]
	v_cndmask_b32_e64 v213, v42, v58, s[46:47]
	v_cndmask_b32_e64 v214, v59, v43, s[46:47]
	v_cndmask_b32_e64 v215, v43, v59, s[46:47]
	v_add_f32_dpp v42, v212, v213 row_ror:8 row_mask:0xf bank_mask:0xf
	v_add_f32_dpp v43, v214, v215 row_ror:8 row_mask:0xf bank_mask:0xf
	v_cndmask_b32_e64 v212, v60, v44, s[46:47]
	v_cndmask_b32_e64 v213, v44, v60, s[46:47]
	v_cndmask_b32_e64 v214, v61, v45, s[46:47]
	v_cndmask_b32_e64 v215, v45, v61, s[46:47]
	v_add_f32_dpp v44, v212, v213 row_ror:8 row_mask:0xf bank_mask:0xf
	v_add_f32_dpp v45, v214, v215 row_ror:8 row_mask:0xf bank_mask:0xf
	v_cndmask_b32_e64 v212, v62, v46, s[46:47]
	v_cndmask_b32_e64 v213, v46, v62, s[46:47]
	v_cndmask_b32_e64 v214, v63, v47, s[46:47]
	v_cndmask_b32_e64 v215, v47, v63, s[46:47]
	v_add_f32_dpp v46, v212, v213 row_ror:8 row_mask:0xf bank_mask:0xf
	v_add_f32_dpp v47, v214, v215 row_ror:8 row_mask:0xf bank_mask:0xf
	v_cndmask_b32_e64 v0, v40, v32, s[48:49]
	v_cndmask_b32_e64 v32, v32, v40, s[48:49]
	v_cndmask_b32_e64 v1, v41, v33, s[48:49]
	v_cndmask_b32_e64 v33, v33, v41, s[48:49]
	v_cndmask_b32_e64 v2, v42, v34, s[48:49]
	v_cndmask_b32_e64 v34, v34, v42, s[48:49]
	v_cndmask_b32_e64 v3, v43, v35, s[48:49]
	v_cndmask_b32_e64 v35, v35, v43, s[48:49]
	v_cndmask_b32_e64 v4, v44, v36, s[48:49]
	v_cndmask_b32_e64 v36, v36, v44, s[48:49]
	v_cndmask_b32_e64 v5, v45, v37, s[48:49]
	v_cndmask_b32_e64 v37, v37, v45, s[48:49]
	v_cndmask_b32_e64 v6, v46, v38, s[48:49]
	v_cndmask_b32_e64 v38, v38, v46, s[48:49]
	v_cndmask_b32_e64 v7, v47, v39, s[48:49]
	v_cndmask_b32_e64 v39, v39, v47, s[48:49]
	ds_swizzle_b32 v0, v0 offset:0x401f
	ds_swizzle_b32 v1, v1 offset:0x401f
	ds_swizzle_b32 v2, v2 offset:0x401f
	ds_swizzle_b32 v3, v3 offset:0x401f
	ds_swizzle_b32 v4, v4 offset:0x401f
	ds_swizzle_b32 v5, v5 offset:0x401f
	ds_swizzle_b32 v6, v6 offset:0x401f
	ds_swizzle_b32 v7, v7 offset:0x401f
	s_waitcnt lgkmcnt(0)
	v_add_f32_e32 v32, v32, v0
	v_add_f32_e32 v33, v33, v1
	v_add_f32_e32 v34, v34, v2
	v_add_f32_e32 v35, v35, v3
	v_add_f32_e32 v36, v36, v4
	v_add_f32_e32 v37, v37, v5
	v_add_f32_e32 v38, v38, v6
	v_add_f32_e32 v39, v39, v7
	v_cndmask_b32_e64 v0, v36, v32, s[50:51]
	v_cndmask_b32_e64 v32, v32, v36, s[50:51]
	v_cndmask_b32_e64 v1, v37, v33, s[50:51]
	v_cndmask_b32_e64 v33, v33, v37, s[50:51]
	v_cndmask_b32_e64 v2, v38, v34, s[50:51]
	v_cndmask_b32_e64 v34, v34, v38, s[50:51]
	v_cndmask_b32_e64 v3, v39, v35, s[50:51]
	v_cndmask_b32_e64 v35, v35, v39, s[50:51]
	ds_bpermute_b32 v0, v227, v0
	ds_bpermute_b32 v1, v227, v1
	ds_bpermute_b32 v2, v227, v2
	ds_bpermute_b32 v3, v227, v3
	s_waitcnt lgkmcnt(0)
	v_add_f32_e32 v32, v32, v0
	v_add_f32_e32 v33, v33, v1
	v_add_f32_e32 v34, v34, v2
	v_add_f32_e32 v35, v35, v3
	v_lshlrev_b32_e32 v8, 16, v72
	v_and_b32_e32 v9, 0xffff0000, v72
	v_lshlrev_b32_e32 v10, 16, v73
	v_and_b32_e32 v11, 0xffff0000, v73
	v_pk_fma_f32 v[8:9], v[74:75], v[32:33], v[8:9]
	v_pk_fma_f32 v[10:11], v[76:77], v[34:35], v[10:11]
	s_cmp_eq_u32 s88, 0
	s_cbranch_scc1 .Lex_vskip
	global_store_dwordx4 v226, v[8:11], s[86:87]
	s_branch .Lex_vdone

.Lex_vdone:
	s_cmp_lt_u32 s8, 16
	s_cbranch_scc1 .Lex_vloop
	s_waitcnt vmcnt(0) lgkmcnt(0)
	s_lshl_b32 s34, s5, 3
	s_add_i32 s6, s6, s34
	s_cmp_lt_u32 s6, 0x4000
	s_cbranch_scc1 .Lex_chunk

	.amdhsa_kernel _Z14fwd_megakernel6Params
		.amdhsa_group_segment_fixed_size 16384
		.amdhsa_private_segment_fixed_size 0
		.amdhsa_kernarg_size 608
		.amdhsa_user_sgpr_count 2
		.amdhsa_user_sgpr_dispatch_ptr 0
		.amdhsa_user_sgpr_queue_ptr 0
		.amdhsa_user_sgpr_kernarg_segment_ptr 1
		.amdhsa_user_sgpr_dispatch_id 0
		.amdhsa_user_sgpr_kernarg_preload_length 0
		.amdhsa_user_sgpr_kernarg_preload_offset 0
		.amdhsa_user_sgpr_private_segment_size 0
		.amdhsa_uses_dynamic_stack 0
		.amdhsa_enable_private_segment 0
		.amdhsa_system_sgpr_workgroup_id_x 1
		.amdhsa_system_sgpr_workgroup_id_y 0
		.amdhsa_system_sgpr_workgroup_id_z 0
		.amdhsa_system_sgpr_workgroup_info 0
		.amdhsa_system_vgpr_workitem_id 2
		.amdhsa_next_free_vgpr 256
		.amdhsa_next_free_sgpr 100
		.amdhsa_accum_offset 256
		.amdhsa_reserve_vcc 1
		.amdhsa_float_round_mode_32 0
		.amdhsa_float_round_mode_16_64 0
		.amdhsa_float_denorm_mode_32 3
		.amdhsa_float_denorm_mode_16_64 3
		.amdhsa_dx10_clamp 1
		.amdhsa_ieee_mode 1
		.amdhsa_fp16_overflow 0
		.amdhsa_tg_split 0
		.amdhsa_exception_fp_ieee_invalid_op 0
		.amdhsa_exception_fp_denorm_src 0
		.amdhsa_exception_fp_ieee_div_zero 0
		.amdhsa_exception_fp_ieee_overflow 0
		.amdhsa_exception_fp_ieee_underflow 0
		.amdhsa_exception_fp_ieee_inexact 0
		.amdhsa_exception_int_div_zero 0
	.end_amdhsa_kernel

amdhsa.kernels:
  - .agpr_count:     0
    .args:
      - .offset:         0
        .size:           352
        .value_kind:     by_value
      - .offset:         352
        .size:           4
        .value_kind:     hidden_block_count_x
      - .offset:         356
        .size:           4
        .value_kind:     hidden_block_count_y
      - .offset:         360
        .size:           4
        .value_kind:     hidden_block_count_z
      - .offset:         364
        .size:           2
        .value_kind:     hidden_group_size_x
      - .offset:         366
        .size:           2
        .value_kind:     hidden_group_size_y
      - .offset:         368
        .size:           2
        .value_kind:     hidden_group_size_z
      - .offset:         370
        .size:           2
        .value_kind:     hidden_remainder_x
      - .offset:         372
        .size:           2
        .value_kind:     hidden_remainder_y
      - .offset:         374
        .size:           2
        .value_kind:     hidden_remainder_z
      - .offset:         392
        .size:           8
        .value_kind:     hidden_global_offset_x
      - .offset:         400
        .size:           8
        .value_kind:     hidden_global_offset_y
      - .offset:         408
        .size:           8
        .value_kind:     hidden_global_offset_z
      - .offset:         416
        .size:           2
        .value_kind:     hidden_grid_dims
      - .offset:         440
        .size:           8
        .value_kind:     hidden_multigrid_sync_arg
      - .offset:         472
        .size:           4
        .value_kind:     hidden_dynamic_lds_size
    .group_segment_fixed_size: 16384
    .kernarg_segment_align: 8
    .kernarg_segment_size: 608
    .language:       OpenCL C
    .language_version:
      - 2
      - 0
    .max_flat_workgroup_size: 512
    .name:           _Z14fwd_megakernel6Params
    .private_segment_fixed_size: 0
    .sgpr_count:     106
    .sgpr_spill_count: 1
    .symbol:         _Z14fwd_megakernel6Params.kd
    .uniform_work_group_size: 1
    .uses_dynamic_stack: false
    .vgpr_count:     256
    .vgpr_spill_count: 0
    .wavefront_size: 64
